# all s_setprio removed from the GEMM K-loops (MFMA and loader waves at equal priority)
# baseline (speedup 1.0000x reference)
.LBB0_197:
	ds_read_b128 v[146:149], v161
	ds_read_b128 v[150:153], v161 offset:1024
	ds_read_b128 v[154:157], v161 offset:2048
	ds_read_b128 v[166:169], v161 offset:3072
	ds_read_b128 v[170:173], v162
	ds_read_b128 v[174:177], v162 offset:1024
	ds_read_b128 v[178:181], v162 offset:2048
	ds_read_b128 v[182:185], v162 offset:3072
	s_add_u32 s38, s36, 0xfffc0080
	s_addc_u32 s39, s37, -1
	s_cmp_eq_u32 s62, 12
	s_cselect_b32 s41, s17, s39
	s_cselect_b32 s40, s23, s38
	s_cselect_b32 s39, s15, s61
	s_cselect_b32 s38, s59, s60
	v_lshl_add_u64 v[218:219], s[36:37], 0, v[138:139]
	s_add_i32 m0, s45, 0xc000
	ds_read_b128 v[186:189], v163
	ds_read_b128 v[190:193], v163 offset:1024
	ds_read_b128 v[194:197], v163 offset:2048
	ds_read_b128 v[198:201], v163 offset:3072
	ds_read_b128 v[202:205], v163 offset:4096
	ds_read_b128 v[206:209], v163 offset:5120
	ds_read_b128 v[210:213], v163 offset:6144
	ds_read_b128 v[214:217], v163 offset:7168
	global_load_lds_dwordx4 v[218:219], off
	v_lshl_add_u64 v[218:219], s[36:37], 0, v[140:141]
	s_add_i32 m0, s45, 0xe000
	s_nop 0
	global_load_lds_dwordx4 v[218:219], off
	s_waitcnt vmcnt(8)
	s_waitcnt lgkmcnt(0)
	s_barrier
	v_mfma_f32_16x16x32_bf16 v[124:127], v[146:149], v[186:189], v[124:127]
	v_mfma_f32_16x16x32_bf16 v[120:123], v[154:157], v[186:189], v[120:123]
	v_mfma_f32_16x16x32_bf16 v[116:119], v[146:149], v[194:197], v[116:119]
	v_mfma_f32_16x16x32_bf16 v[112:115], v[154:157], v[194:197], v[112:115]
	v_mfma_f32_16x16x32_bf16 v[92:95], v[146:149], v[202:205], v[92:95]
	v_mfma_f32_16x16x32_bf16 v[88:91], v[154:157], v[202:205], v[88:91]
	v_mfma_f32_16x16x32_bf16 v[76:79], v[146:149], v[210:213], v[76:79]
	v_mfma_f32_16x16x32_bf16 v[72:75], v[154:157], v[210:213], v[72:75]
	v_mfma_f32_16x16x32_bf16 v[124:127], v[150:153], v[190:193], v[124:127]
	v_mfma_f32_16x16x32_bf16 v[120:123], v[166:169], v[190:193], v[120:123]
	v_mfma_f32_16x16x32_bf16 v[116:119], v[150:153], v[198:201], v[116:119]
	v_mfma_f32_16x16x32_bf16 v[112:115], v[166:169], v[198:201], v[112:115]
	v_mfma_f32_16x16x32_bf16 v[92:95], v[150:153], v[206:209], v[92:95]
	v_mfma_f32_16x16x32_bf16 v[88:91], v[166:169], v[206:209], v[88:91]
	v_mfma_f32_16x16x32_bf16 v[76:79], v[150:153], v[214:217], v[76:79]
	v_mfma_f32_16x16x32_bf16 v[72:75], v[166:169], v[214:217], v[72:75]
	v_mfma_f32_16x16x32_bf16 v[108:111], v[170:173], v[186:189], v[108:111]
	v_mfma_f32_16x16x32_bf16 v[104:107], v[178:181], v[186:189], v[104:107]
	v_mfma_f32_16x16x32_bf16 v[100:103], v[170:173], v[194:197], v[100:103]
	v_mfma_f32_16x16x32_bf16 v[96:99], v[178:181], v[194:197], v[96:99]
	v_mfma_f32_16x16x32_bf16 v[84:87], v[170:173], v[202:205], v[84:87]
	v_mfma_f32_16x16x32_bf16 v[80:83], v[178:181], v[202:205], v[80:83]
	v_mfma_f32_16x16x32_bf16 v[68:71], v[170:173], v[210:213], v[68:71]
	v_mfma_f32_16x16x32_bf16 v[64:67], v[178:181], v[210:213], v[64:67]
	v_mfma_f32_16x16x32_bf16 v[108:111], v[174:177], v[190:193], v[108:111]
	v_mfma_f32_16x16x32_bf16 v[104:107], v[182:185], v[190:193], v[104:107]
	v_mfma_f32_16x16x32_bf16 v[100:103], v[174:177], v[198:201], v[100:103]
	v_mfma_f32_16x16x32_bf16 v[96:99], v[182:185], v[198:201], v[96:99]
	v_mfma_f32_16x16x32_bf16 v[84:87], v[174:177], v[206:209], v[84:87]
	v_mfma_f32_16x16x32_bf16 v[80:83], v[182:185], v[206:209], v[80:83]
	v_mfma_f32_16x16x32_bf16 v[68:71], v[174:177], v[214:217], v[68:71]
	v_mfma_f32_16x16x32_bf16 v[64:67], v[182:185], v[214:217], v[64:67]
	s_barrier
	s_add_i32 s63, s56, s44
	v_lshl_add_u64 v[218:219], s[38:39], 0, v[130:131]
	s_mov_b32 m0, s63
	ds_read_b128 v[186:189], v163 offset:16384
	ds_read_b128 v[190:193], v163 offset:17408
	ds_read_b128 v[194:197], v163 offset:18432
	ds_read_b128 v[198:201], v163 offset:19456
	ds_read_b128 v[202:205], v163 offset:20480
	ds_read_b128 v[206:209], v163 offset:21504
	ds_read_b128 v[210:213], v163 offset:22528
	ds_read_b128 v[214:217], v163 offset:23552
	global_load_lds_dwordx4 v[218:219], off
	s_add_i32 m0, s63, 0x2000
	s_add_u32 s64, s38, 0x40000
	v_lshl_add_u64 v[220:221], s[38:39], 0, v[134:135]
	s_addc_u32 s65, s39, 0
	s_add_i32 s63, s57, s44
	global_load_lds_dwordx4 v[220:221], off
	v_lshl_add_u64 v[222:223], s[64:65], 0, v[130:131]
	s_mov_b32 m0, s63
	v_lshl_add_u64 v[224:225], s[40:41], 0, v[132:133]
	global_load_lds_dwordx4 v[222:223], off
	v_lshl_add_u64 v[222:223], s[64:65], 0, v[134:135]
	s_add_i32 m0, s63, 0x2000
	s_nop 0
	global_load_lds_dwordx4 v[222:223], off
	v_lshl_add_u64 v[222:223], s[40:41], 0, v[128:129]
	s_mov_b32 m0, s45
	s_nop 0
	global_load_lds_dwordx4 v[222:223], off
	s_mov_b32 m0, s46
	s_nop 0
	global_load_lds_dwordx4 v[224:225], off
	s_waitcnt vmcnt(8)
	s_waitcnt lgkmcnt(0)
	s_barrier
	v_mfma_f32_16x16x32_bf16 v[60:63], v[146:149], v[186:189], v[60:63]
	v_mfma_f32_16x16x32_bf16 v[56:59], v[154:157], v[186:189], v[56:59]
	v_mfma_f32_16x16x32_bf16 v[44:47], v[146:149], v[194:197], v[44:47]
	v_mfma_f32_16x16x32_bf16 v[40:43], v[154:157], v[194:197], v[40:43]
	v_mfma_f32_16x16x32_bf16 v[28:31], v[146:149], v[202:205], v[28:31]
	v_mfma_f32_16x16x32_bf16 v[24:27], v[154:157], v[202:205], v[24:27]
	v_mfma_f32_16x16x32_bf16 v[12:15], v[146:149], v[210:213], v[12:15]
	v_mfma_f32_16x16x32_bf16 v[8:11], v[154:157], v[210:213], v[8:11]
	v_mfma_f32_16x16x32_bf16 v[60:63], v[150:153], v[190:193], v[60:63]
	v_mfma_f32_16x16x32_bf16 v[56:59], v[166:169], v[190:193], v[56:59]
	v_mfma_f32_16x16x32_bf16 v[44:47], v[150:153], v[198:201], v[44:47]
	v_mfma_f32_16x16x32_bf16 v[40:43], v[166:169], v[198:201], v[40:43]
	v_mfma_f32_16x16x32_bf16 v[28:31], v[150:153], v[206:209], v[28:31]
	v_mfma_f32_16x16x32_bf16 v[24:27], v[166:169], v[206:209], v[24:27]
	v_mfma_f32_16x16x32_bf16 v[12:15], v[150:153], v[214:217], v[12:15]
	v_mfma_f32_16x16x32_bf16 v[8:11], v[166:169], v[214:217], v[8:11]
	v_mfma_f32_16x16x32_bf16 v[52:55], v[170:173], v[186:189], v[52:55]
	v_mfma_f32_16x16x32_bf16 v[48:51], v[178:181], v[186:189], v[48:51]
	v_mfma_f32_16x16x32_bf16 v[36:39], v[170:173], v[194:197], v[36:39]
	v_mfma_f32_16x16x32_bf16 v[32:35], v[178:181], v[194:197], v[32:35]
	v_mfma_f32_16x16x32_bf16 v[20:23], v[170:173], v[202:205], v[20:23]
	v_mfma_f32_16x16x32_bf16 v[16:19], v[178:181], v[202:205], v[16:19]
	v_mfma_f32_16x16x32_bf16 v[4:7], v[170:173], v[210:213], v[4:7]
	v_mfma_f32_16x16x32_bf16 v[0:3], v[178:181], v[210:213], v[0:3]
	v_mfma_f32_16x16x32_bf16 v[52:55], v[174:177], v[190:193], v[52:55]
	v_mfma_f32_16x16x32_bf16 v[48:51], v[182:185], v[190:193], v[48:51]
	v_mfma_f32_16x16x32_bf16 v[36:39], v[174:177], v[198:201], v[36:39]
	v_mfma_f32_16x16x32_bf16 v[32:35], v[182:185], v[198:201], v[32:35]
	v_mfma_f32_16x16x32_bf16 v[20:23], v[174:177], v[206:209], v[20:23]
	v_mfma_f32_16x16x32_bf16 v[16:19], v[182:185], v[206:209], v[16:19]
	v_mfma_f32_16x16x32_bf16 v[4:7], v[174:177], v[214:217], v[4:7]
	v_mfma_f32_16x16x32_bf16 v[0:3], v[182:185], v[214:217], v[0:3]
	s_barrier
	s_add_i32 s63, 0, 0x18000
	v_add_u32_e32 v136, s63, v160
	s_add_i32 s64, 0, 0x1c000
	ds_read_b128 v[146:149], v136
	ds_read_b128 v[150:153], v136 offset:1024
	ds_read_b128 v[154:157], v136 offset:2048
	ds_read_b128 v[166:169], v136 offset:3072
	v_add_u32_e32 v136, s64, v160
	ds_read_b128 v[170:173], v136
	ds_read_b128 v[174:177], v136 offset:1024
	ds_read_b128 v[178:181], v136 offset:2048
	ds_read_b128 v[182:185], v136 offset:3072
	s_add_u32 s40, s40, 0x40000
	s_addc_u32 s41, s41, 0
	s_mov_b32 m0, s47
	v_lshl_add_u64 v[226:227], s[40:41], 0, v[128:129]
	ds_read_b128 v[186:189], v163 offset:32768
	ds_read_b128 v[190:193], v163 offset:33792
	ds_read_b128 v[194:197], v163 offset:34816
	ds_read_b128 v[198:201], v163 offset:35840
	ds_read_b128 v[202:205], v163 offset:36864
	ds_read_b128 v[206:209], v163 offset:37888
	ds_read_b128 v[210:213], v163 offset:38912
	ds_read_b128 v[214:217], v163 offset:39936
	global_load_lds_dwordx4 v[226:227], off
	v_lshl_add_u64 v[226:227], s[40:41], 0, v[132:133]
	s_mov_b32 m0, s48
	s_nop 0
	global_load_lds_dwordx4 v[226:227], off
	s_waitcnt vmcnt(8)
	s_waitcnt lgkmcnt(0)
	s_barrier
	v_mfma_f32_16x16x32_bf16 v[124:127], v[146:149], v[186:189], v[124:127]
	v_mfma_f32_16x16x32_bf16 v[120:123], v[154:157], v[186:189], v[120:123]
	v_mfma_f32_16x16x32_bf16 v[116:119], v[146:149], v[194:197], v[116:119]
	v_mfma_f32_16x16x32_bf16 v[112:115], v[154:157], v[194:197], v[112:115]
	v_mfma_f32_16x16x32_bf16 v[92:95], v[146:149], v[202:205], v[92:95]
	v_mfma_f32_16x16x32_bf16 v[88:91], v[154:157], v[202:205], v[88:91]
	v_mfma_f32_16x16x32_bf16 v[76:79], v[146:149], v[210:213], v[76:79]
	v_mfma_f32_16x16x32_bf16 v[72:75], v[154:157], v[210:213], v[72:75]
	v_mfma_f32_16x16x32_bf16 v[124:127], v[150:153], v[190:193], v[124:127]
	v_mfma_f32_16x16x32_bf16 v[120:123], v[166:169], v[190:193], v[120:123]
	v_mfma_f32_16x16x32_bf16 v[116:119], v[150:153], v[198:201], v[116:119]
	v_mfma_f32_16x16x32_bf16 v[112:115], v[166:169], v[198:201], v[112:115]
	v_mfma_f32_16x16x32_bf16 v[92:95], v[150:153], v[206:209], v[92:95]
	v_mfma_f32_16x16x32_bf16 v[88:91], v[166:169], v[206:209], v[88:91]
	v_mfma_f32_16x16x32_bf16 v[76:79], v[150:153], v[214:217], v[76:79]
	v_mfma_f32_16x16x32_bf16 v[72:75], v[166:169], v[214:217], v[72:75]
	v_mfma_f32_16x16x32_bf16 v[108:111], v[170:173], v[186:189], v[108:111]
	v_mfma_f32_16x16x32_bf16 v[104:107], v[178:181], v[186:189], v[104:107]
	v_mfma_f32_16x16x32_bf16 v[100:103], v[170:173], v[194:197], v[100:103]
	v_mfma_f32_16x16x32_bf16 v[96:99], v[178:181], v[194:197], v[96:99]
	v_mfma_f32_16x16x32_bf16 v[84:87], v[170:173], v[202:205], v[84:87]
	v_mfma_f32_16x16x32_bf16 v[80:83], v[178:181], v[202:205], v[80:83]
	v_mfma_f32_16x16x32_bf16 v[68:71], v[170:173], v[210:213], v[68:71]
	v_mfma_f32_16x16x32_bf16 v[64:67], v[178:181], v[210:213], v[64:67]
	v_mfma_f32_16x16x32_bf16 v[108:111], v[174:177], v[190:193], v[108:111]
	v_mfma_f32_16x16x32_bf16 v[104:107], v[182:185], v[190:193], v[104:107]
	v_mfma_f32_16x16x32_bf16 v[100:103], v[174:177], v[198:201], v[100:103]
	v_mfma_f32_16x16x32_bf16 v[96:99], v[182:185], v[198:201], v[96:99]
	v_mfma_f32_16x16x32_bf16 v[84:87], v[174:177], v[206:209], v[84:87]
	v_mfma_f32_16x16x32_bf16 v[80:83], v[182:185], v[206:209], v[80:83]
	v_mfma_f32_16x16x32_bf16 v[68:71], v[174:177], v[214:217], v[68:71]
	v_mfma_f32_16x16x32_bf16 v[64:67], v[182:185], v[214:217], v[64:67]
	s_barrier
	s_add_i32 s40, s63, s44
	v_lshl_add_u64 v[218:219], v[218:219], 0, s[8:9]
	s_mov_b32 m0, s40
	ds_read_b128 v[186:189], v163 offset:49152
	ds_read_b128 v[190:193], v163 offset:50176
	ds_read_b128 v[194:197], v163 offset:51200
	ds_read_b128 v[198:201], v163 offset:52224
	ds_read_b128 v[202:205], v163 offset:53248
	ds_read_b128 v[206:209], v163 offset:54272
	ds_read_b128 v[210:213], v163 offset:55296
	ds_read_b128 v[214:217], v163 offset:56320
	global_load_lds_dwordx4 v[218:219], off
	s_add_i32 m0, s40, 0x2000
	s_add_u32 s38, s38, 0x40080
	v_lshl_add_u64 v[218:219], v[220:221], 0, s[8:9]
	s_addc_u32 s39, s39, 0
	s_add_i32 s40, s64, s44
	global_load_lds_dwordx4 v[218:219], off
	v_lshl_add_u64 v[218:219], s[38:39], 0, v[130:131]
	s_mov_b32 m0, s40
	s_nop 0
	global_load_lds_dwordx4 v[218:219], off
	v_lshl_add_u64 v[218:219], s[38:39], 0, v[134:135]
	s_add_i32 m0, s40, 0x2000
	s_nop 0
	global_load_lds_dwordx4 v[218:219], off
	v_lshl_add_u64 v[218:219], v[222:223], 0, s[8:9]
	s_mov_b32 m0, s54
	s_nop 0
	global_load_lds_dwordx4 v[218:219], off
	v_lshl_add_u64 v[218:219], v[224:225], 0, s[8:9]
	s_mov_b32 m0, s55
	s_nop 0
	global_load_lds_dwordx4 v[218:219], off
	s_waitcnt vmcnt(8)
	s_waitcnt lgkmcnt(0)
	s_barrier
	v_mfma_f32_16x16x32_bf16 v[60:63], v[146:149], v[186:189], v[60:63]
	v_mfma_f32_16x16x32_bf16 v[56:59], v[154:157], v[186:189], v[56:59]
	v_mfma_f32_16x16x32_bf16 v[44:47], v[146:149], v[194:197], v[44:47]
	v_mfma_f32_16x16x32_bf16 v[40:43], v[154:157], v[194:197], v[40:43]
	v_mfma_f32_16x16x32_bf16 v[28:31], v[146:149], v[202:205], v[28:31]
	v_mfma_f32_16x16x32_bf16 v[24:27], v[154:157], v[202:205], v[24:27]
	v_mfma_f32_16x16x32_bf16 v[12:15], v[146:149], v[210:213], v[12:15]
	v_mfma_f32_16x16x32_bf16 v[8:11], v[154:157], v[210:213], v[8:11]
	v_mfma_f32_16x16x32_bf16 v[60:63], v[150:153], v[190:193], v[60:63]
	v_mfma_f32_16x16x32_bf16 v[56:59], v[166:169], v[190:193], v[56:59]
	v_mfma_f32_16x16x32_bf16 v[44:47], v[150:153], v[198:201], v[44:47]
	v_mfma_f32_16x16x32_bf16 v[40:43], v[166:169], v[198:201], v[40:43]
	v_mfma_f32_16x16x32_bf16 v[28:31], v[150:153], v[206:209], v[28:31]
	v_mfma_f32_16x16x32_bf16 v[24:27], v[166:169], v[206:209], v[24:27]
	v_mfma_f32_16x16x32_bf16 v[12:15], v[150:153], v[214:217], v[12:15]
	v_mfma_f32_16x16x32_bf16 v[8:11], v[166:169], v[214:217], v[8:11]
	v_mfma_f32_16x16x32_bf16 v[52:55], v[170:173], v[186:189], v[52:55]
	v_mfma_f32_16x16x32_bf16 v[48:51], v[178:181], v[186:189], v[48:51]
	v_mfma_f32_16x16x32_bf16 v[36:39], v[170:173], v[194:197], v[36:39]
	v_mfma_f32_16x16x32_bf16 v[32:35], v[178:181], v[194:197], v[32:35]
	v_mfma_f32_16x16x32_bf16 v[20:23], v[170:173], v[202:205], v[20:23]
	v_mfma_f32_16x16x32_bf16 v[16:19], v[178:181], v[202:205], v[16:19]
	v_mfma_f32_16x16x32_bf16 v[4:7], v[170:173], v[210:213], v[4:7]
	v_mfma_f32_16x16x32_bf16 v[0:3], v[178:181], v[210:213], v[0:3]
	v_mfma_f32_16x16x32_bf16 v[52:55], v[174:177], v[190:193], v[52:55]
	v_mfma_f32_16x16x32_bf16 v[48:51], v[182:185], v[190:193], v[48:51]
	v_mfma_f32_16x16x32_bf16 v[36:39], v[174:177], v[198:201], v[36:39]
	v_mfma_f32_16x16x32_bf16 v[32:35], v[182:185], v[198:201], v[32:35]
	v_mfma_f32_16x16x32_bf16 v[20:23], v[174:177], v[206:209], v[20:23]
	v_mfma_f32_16x16x32_bf16 v[16:19], v[182:185], v[206:209], v[16:19]
	v_mfma_f32_16x16x32_bf16 v[4:7], v[174:177], v[214:217], v[4:7]
	v_mfma_f32_16x16x32_bf16 v[0:3], v[182:185], v[214:217], v[0:3]
	s_barrier
	s_add_i32 s62, s62, 2
	s_add_u32 s36, s36, 0x100
	s_addc_u32 s37, s37, 0
	s_add_u32 s60, s60, 0x100
	s_addc_u32 s61, s61, 0
	s_cmp_gt_u32 s62, 13
	s_cbranch_scc0 .LBB0_197
	s_and_b64 vcc, exec, s[12:13]
	s_cbranch_vccz .LBB0_200
	s_barrier

.Lrb0_skip:
	s_add_u32 s48, s46, 0xfffc0080
	s_addc_u32 s49, s47, -1
	s_add_i32 s63, 0, 0x10000
	s_cmp_eq_u32 s62, 12
	s_cselect_b32 s51, s39, s49
	s_cselect_b32 s50, s58, s48
	v_add_u32_e32 v0, s63, v144
	s_cselect_b32 s49, s23, s61
	s_cselect_b32 s48, s59, s60
	s_add_i32 s66, 0, 0x14000
	ds_read_b128 v[146:149], v0
	ds_read_b128 v[150:153], v0 offset:1024
	ds_read_b128 v[154:157], v0 offset:2048
	ds_read_b128 v[158:161], v0 offset:3072
	v_add_u32_e32 v0, s66, v144
	ds_read_b128 v[162:165], v0
	ds_read_b128 v[166:169], v0 offset:1024
	ds_read_b128 v[170:173], v0 offset:2048
	ds_read_b128 v[174:177], v0 offset:3072
	s_add_i32 m0, s5, 0xc000
	ds_read_b128 v[178:181], v145
	ds_read_b128 v[182:185], v145 offset:1024
	ds_read_b128 v[204:207], v145 offset:2048
	ds_read_b128 v[208:211], v145 offset:3072
	ds_read_b128 v[212:215], v145 offset:4096
	ds_read_b128 v[216:219], v145 offset:5120
	ds_read_b128 v[220:223], v145 offset:6144
	ds_read_b128 v[224:227], v145 offset:7168
	global_load_lds_dwordx4 v138, s[46:47]
	s_add_i32 m0, s5, 0xe000
	s_nop 0
	global_load_lds_dwordx4 v140, s[46:47]
	s_waitcnt vmcnt(8)
	s_waitcnt lgkmcnt(0)
	s_barrier
	v_mfma_f32_16x16x32_bf16 v[118:121], v[146:149], v[178:181], 0
	v_mfma_f32_16x16x32_bf16 v[114:117], v[154:157], v[178:181], 0
	v_mfma_f32_16x16x32_bf16 v[110:113], v[146:149], v[204:207], 0
	v_mfma_f32_16x16x32_bf16 v[102:105], v[154:157], v[204:207], 0
	v_mfma_f32_16x16x32_bf16 v[94:97], v[146:149], v[212:215], 0
	v_mfma_f32_16x16x32_bf16 v[86:89], v[154:157], v[212:215], 0
	v_mfma_f32_16x16x32_bf16 v[78:81], v[146:149], v[220:223], 0
	v_mfma_f32_16x16x32_bf16 v[70:73], v[154:157], v[220:223], 0
	v_mfma_f32_16x16x32_bf16 v[118:121], v[150:153], v[182:185], v[118:121]
	v_mfma_f32_16x16x32_bf16 v[114:117], v[158:161], v[182:185], v[114:117]
	v_mfma_f32_16x16x32_bf16 v[110:113], v[150:153], v[208:211], v[110:113]
	v_mfma_f32_16x16x32_bf16 v[102:105], v[158:161], v[208:211], v[102:105]
	v_mfma_f32_16x16x32_bf16 v[94:97], v[150:153], v[216:219], v[94:97]
	v_mfma_f32_16x16x32_bf16 v[86:89], v[158:161], v[216:219], v[86:89]
	v_mfma_f32_16x16x32_bf16 v[78:81], v[150:153], v[224:227], v[78:81]
	v_mfma_f32_16x16x32_bf16 v[70:73], v[158:161], v[224:227], v[70:73]
	v_mfma_f32_16x16x32_bf16 v[126:129], v[162:165], v[178:181], 0
	v_mfma_f32_16x16x32_bf16 v[122:125], v[170:173], v[178:181], 0
	v_mfma_f32_16x16x32_bf16 v[106:109], v[162:165], v[204:207], 0
	v_mfma_f32_16x16x32_bf16 v[98:101], v[170:173], v[204:207], 0
	v_mfma_f32_16x16x32_bf16 v[90:93], v[162:165], v[212:215], 0
	v_mfma_f32_16x16x32_bf16 v[82:85], v[170:173], v[212:215], 0
	v_mfma_f32_16x16x32_bf16 v[74:77], v[162:165], v[220:223], 0
	v_mfma_f32_16x16x32_bf16 v[66:69], v[170:173], v[220:223], 0
	v_mfma_f32_16x16x32_bf16 v[126:129], v[166:169], v[182:185], v[126:129]
	v_mfma_f32_16x16x32_bf16 v[122:125], v[174:177], v[182:185], v[122:125]
	v_mfma_f32_16x16x32_bf16 v[106:109], v[166:169], v[208:211], v[106:109]
	v_mfma_f32_16x16x32_bf16 v[98:101], v[174:177], v[208:211], v[98:101]
	v_mfma_f32_16x16x32_bf16 v[90:93], v[166:169], v[216:219], v[90:93]
	v_mfma_f32_16x16x32_bf16 v[82:85], v[174:177], v[216:219], v[82:85]
	v_mfma_f32_16x16x32_bf16 v[74:77], v[166:169], v[224:227], v[74:77]
	v_mfma_f32_16x16x32_bf16 v[66:69], v[174:177], v[224:227], v[66:69]
	s_barrier
	s_add_i32 s63, s63, s4
	s_mov_b32 m0, s63
	ds_read_b128 v[178:181], v145 offset:16384
	ds_read_b128 v[182:185], v145 offset:17408
	ds_read_b128 v[204:207], v145 offset:18432
	ds_read_b128 v[208:211], v145 offset:19456
	ds_read_b128 v[212:215], v145 offset:20480
	ds_read_b128 v[216:219], v145 offset:21504
	ds_read_b128 v[220:223], v145 offset:22528
	ds_read_b128 v[224:227], v145 offset:23552
	global_load_lds_dwordx4 v134, s[48:49]
	s_add_i32 m0, s63, 0x2000
	s_add_u32 s64, s48, 0x40000
	s_addc_u32 s65, s49, 0
	s_add_i32 s63, s66, s4
	global_load_lds_dwordx4 v130, s[48:49]
	s_mov_b32 m0, s63
	s_nop 0
	global_load_lds_dwordx4 v134, s[64:65]
	s_add_i32 m0, s63, 0x2000
	s_nop 0
	global_load_lds_dwordx4 v130, s[64:65]
	s_mov_b32 m0, s5
	s_nop 0
	global_load_lds_dwordx4 v136, s[50:51]
	s_mov_b32 m0, s6
	s_nop 0
	global_load_lds_dwordx4 v132, s[50:51]
	s_waitcnt vmcnt(8)
	s_waitcnt lgkmcnt(0)
	s_barrier
	v_mfma_f32_16x16x32_bf16 v[62:65], v[146:149], v[178:181], 0
	v_mfma_f32_16x16x32_bf16 v[54:57], v[154:157], v[178:181], 0
	v_mfma_f32_16x16x32_bf16 v[46:49], v[146:149], v[204:207], 0
	v_mfma_f32_16x16x32_bf16 v[38:41], v[154:157], v[204:207], 0
	v_mfma_f32_16x16x32_bf16 v[30:33], v[146:149], v[212:215], 0
	v_mfma_f32_16x16x32_bf16 v[22:25], v[154:157], v[212:215], 0
	v_mfma_f32_16x16x32_bf16 v[14:17], v[146:149], v[220:223], 0
	v_mfma_f32_16x16x32_bf16 v[6:9], v[154:157], v[220:223], 0
	v_mfma_f32_16x16x32_bf16 v[62:65], v[150:153], v[182:185], v[62:65]
	v_mfma_f32_16x16x32_bf16 v[54:57], v[158:161], v[182:185], v[54:57]
	v_mfma_f32_16x16x32_bf16 v[46:49], v[150:153], v[208:211], v[46:49]
	v_mfma_f32_16x16x32_bf16 v[38:41], v[158:161], v[208:211], v[38:41]
	v_mfma_f32_16x16x32_bf16 v[30:33], v[150:153], v[216:219], v[30:33]
	v_mfma_f32_16x16x32_bf16 v[22:25], v[158:161], v[216:219], v[22:25]
	v_mfma_f32_16x16x32_bf16 v[14:17], v[150:153], v[224:227], v[14:17]
	v_mfma_f32_16x16x32_bf16 v[6:9], v[158:161], v[224:227], v[6:9]
	v_mfma_f32_16x16x32_bf16 v[58:61], v[162:165], v[178:181], 0
	v_mfma_f32_16x16x32_bf16 v[50:53], v[170:173], v[178:181], 0
	v_mfma_f32_16x16x32_bf16 v[42:45], v[162:165], v[204:207], 0
	v_mfma_f32_16x16x32_bf16 v[34:37], v[170:173], v[204:207], 0
	v_mfma_f32_16x16x32_bf16 v[26:29], v[162:165], v[212:215], 0
	v_mfma_f32_16x16x32_bf16 v[18:21], v[170:173], v[212:215], 0
	v_mfma_f32_16x16x32_bf16 v[10:13], v[162:165], v[220:223], 0
	v_mfma_f32_16x16x32_bf16 v[2:5], v[170:173], v[220:223], 0
	v_mfma_f32_16x16x32_bf16 v[58:61], v[166:169], v[182:185], v[58:61]
	v_mfma_f32_16x16x32_bf16 v[50:53], v[174:177], v[182:185], v[50:53]
	v_mfma_f32_16x16x32_bf16 v[42:45], v[166:169], v[208:211], v[42:45]
	v_mfma_f32_16x16x32_bf16 v[34:37], v[174:177], v[208:211], v[34:37]
	v_mfma_f32_16x16x32_bf16 v[26:29], v[166:169], v[216:219], v[26:29]
	v_mfma_f32_16x16x32_bf16 v[18:21], v[174:177], v[216:219], v[18:21]
	v_mfma_f32_16x16x32_bf16 v[10:13], v[166:169], v[224:227], v[10:13]
	v_mfma_f32_16x16x32_bf16 v[2:5], v[174:177], v[224:227], v[2:5]
	s_barrier
	s_add_i32 s63, 0, 0x18000
	v_add_u32_e32 v0, s63, v144
	s_add_i32 s64, 0, 0x1c000
	ds_read_b128 v[146:149], v0
	ds_read_b128 v[150:153], v0 offset:1024
	ds_read_b128 v[154:157], v0 offset:2048
	ds_read_b128 v[158:161], v0 offset:3072
	v_add_u32_e32 v0, s64, v144
	ds_read_b128 v[162:165], v0
	ds_read_b128 v[166:169], v0 offset:1024
	ds_read_b128 v[170:173], v0 offset:2048
	ds_read_b128 v[174:177], v0 offset:3072
	s_add_u32 s50, s50, 0x40000
	s_addc_u32 s51, s51, 0
	s_mov_b32 m0, s7
	ds_read_b128 v[178:181], v145 offset:32768
	ds_read_b128 v[182:185], v145 offset:33792
	ds_read_b128 v[204:207], v145 offset:34816
	ds_read_b128 v[208:211], v145 offset:35840
	ds_read_b128 v[212:215], v145 offset:36864
	ds_read_b128 v[216:219], v145 offset:37888
	ds_read_b128 v[220:223], v145 offset:38912
	ds_read_b128 v[224:227], v145 offset:39936
	global_load_lds_dwordx4 v136, s[50:51]
	s_mov_b32 m0, s52
	s_nop 0
	global_load_lds_dwordx4 v132, s[50:51]
	s_waitcnt vmcnt(8)
	s_waitcnt lgkmcnt(0)
	s_barrier
	v_mfma_f32_16x16x32_bf16 v[118:121], v[146:149], v[178:181], v[118:121]
	v_mfma_f32_16x16x32_bf16 v[114:117], v[154:157], v[178:181], v[114:117]
	v_mfma_f32_16x16x32_bf16 v[110:113], v[146:149], v[204:207], v[110:113]
	v_mfma_f32_16x16x32_bf16 v[102:105], v[154:157], v[204:207], v[102:105]
	v_mfma_f32_16x16x32_bf16 v[94:97], v[146:149], v[212:215], v[94:97]
	v_mfma_f32_16x16x32_bf16 v[86:89], v[154:157], v[212:215], v[86:89]
	v_mfma_f32_16x16x32_bf16 v[78:81], v[146:149], v[220:223], v[78:81]
	v_mfma_f32_16x16x32_bf16 v[70:73], v[154:157], v[220:223], v[70:73]
	v_mfma_f32_16x16x32_bf16 v[118:121], v[150:153], v[182:185], v[118:121]
	v_mfma_f32_16x16x32_bf16 v[114:117], v[158:161], v[182:185], v[114:117]
	v_mfma_f32_16x16x32_bf16 v[110:113], v[150:153], v[208:211], v[110:113]
	v_mfma_f32_16x16x32_bf16 v[102:105], v[158:161], v[208:211], v[102:105]
	v_mfma_f32_16x16x32_bf16 v[94:97], v[150:153], v[216:219], v[94:97]
	v_mfma_f32_16x16x32_bf16 v[86:89], v[158:161], v[216:219], v[86:89]
	v_mfma_f32_16x16x32_bf16 v[78:81], v[150:153], v[224:227], v[78:81]
	v_mfma_f32_16x16x32_bf16 v[70:73], v[158:161], v[224:227], v[70:73]
	v_mfma_f32_16x16x32_bf16 v[126:129], v[162:165], v[178:181], v[126:129]
	v_mfma_f32_16x16x32_bf16 v[122:125], v[170:173], v[178:181], v[122:125]
	v_mfma_f32_16x16x32_bf16 v[106:109], v[162:165], v[204:207], v[106:109]
	v_mfma_f32_16x16x32_bf16 v[98:101], v[170:173], v[204:207], v[98:101]
	v_mfma_f32_16x16x32_bf16 v[90:93], v[162:165], v[212:215], v[90:93]
	v_mfma_f32_16x16x32_bf16 v[82:85], v[170:173], v[212:215], v[82:85]
	v_mfma_f32_16x16x32_bf16 v[74:77], v[162:165], v[220:223], v[74:77]
	v_mfma_f32_16x16x32_bf16 v[66:69], v[170:173], v[220:223], v[66:69]
	v_mfma_f32_16x16x32_bf16 v[126:129], v[166:169], v[182:185], v[126:129]
	v_mfma_f32_16x16x32_bf16 v[122:125], v[174:177], v[182:185], v[122:125]
	v_mfma_f32_16x16x32_bf16 v[106:109], v[166:169], v[208:211], v[106:109]
	v_mfma_f32_16x16x32_bf16 v[98:101], v[174:177], v[208:211], v[98:101]
	v_mfma_f32_16x16x32_bf16 v[90:93], v[166:169], v[216:219], v[90:93]
	v_mfma_f32_16x16x32_bf16 v[82:85], v[174:177], v[216:219], v[82:85]
	v_mfma_f32_16x16x32_bf16 v[74:77], v[166:169], v[224:227], v[74:77]
	v_mfma_f32_16x16x32_bf16 v[66:69], v[174:177], v[224:227], v[66:69]
	s_barrier
	s_add_i32 s65, s63, s4
	s_add_u32 s48, s48, 0x80
	s_addc_u32 s49, s49, 0
	s_mov_b32 m0, s65
	ds_read_b128 v[178:181], v145 offset:49152
	ds_read_b128 v[182:185], v145 offset:50176
	ds_read_b128 v[204:207], v145 offset:51200
	ds_read_b128 v[208:211], v145 offset:52224
	ds_read_b128 v[212:215], v145 offset:53248
	ds_read_b128 v[216:219], v145 offset:54272
	ds_read_b128 v[220:223], v145 offset:55296
	ds_read_b128 v[224:227], v145 offset:56320
	global_load_lds_dwordx4 v134, s[48:49]
	s_add_i32 m0, s65, 0x2000
	s_add_i32 s65, s64, s4
	global_load_lds_dwordx4 v130, s[48:49]
	s_add_u32 s48, s48, 0x40000
	s_addc_u32 s49, s49, 0
	s_mov_b32 m0, s65
	s_sub_u32 s50, s50, 0x3ff80
	global_load_lds_dwordx4 v134, s[48:49]
	s_subb_u32 s51, s51, 0
	s_add_i32 m0, s65, 0x2000
	s_nop 0
	global_load_lds_dwordx4 v130, s[48:49]
	s_mov_b32 m0, s55
	s_nop 0
	global_load_lds_dwordx4 v136, s[50:51]
	s_mov_b32 m0, s56
	s_nop 0
	global_load_lds_dwordx4 v132, s[50:51]
	s_waitcnt vmcnt(8)
	s_waitcnt lgkmcnt(0)
	s_barrier
	v_mfma_f32_16x16x32_bf16 v[62:65], v[146:149], v[178:181], v[62:65]
	v_mfma_f32_16x16x32_bf16 v[54:57], v[154:157], v[178:181], v[54:57]
	v_mfma_f32_16x16x32_bf16 v[46:49], v[146:149], v[204:207], v[46:49]
	v_mfma_f32_16x16x32_bf16 v[38:41], v[154:157], v[204:207], v[38:41]
	v_mfma_f32_16x16x32_bf16 v[30:33], v[146:149], v[212:215], v[30:33]
	v_mfma_f32_16x16x32_bf16 v[22:25], v[154:157], v[212:215], v[22:25]
	v_mfma_f32_16x16x32_bf16 v[14:17], v[146:149], v[220:223], v[14:17]
	v_mfma_f32_16x16x32_bf16 v[6:9], v[154:157], v[220:223], v[6:9]
	v_mfma_f32_16x16x32_bf16 v[62:65], v[150:153], v[182:185], v[62:65]
	v_mfma_f32_16x16x32_bf16 v[54:57], v[158:161], v[182:185], v[54:57]
	v_mfma_f32_16x16x32_bf16 v[46:49], v[150:153], v[208:211], v[46:49]
	v_mfma_f32_16x16x32_bf16 v[38:41], v[158:161], v[208:211], v[38:41]
	v_mfma_f32_16x16x32_bf16 v[30:33], v[150:153], v[216:219], v[30:33]
	v_mfma_f32_16x16x32_bf16 v[22:25], v[158:161], v[216:219], v[22:25]
	v_mfma_f32_16x16x32_bf16 v[14:17], v[150:153], v[224:227], v[14:17]
	v_mfma_f32_16x16x32_bf16 v[6:9], v[158:161], v[224:227], v[6:9]
	v_mfma_f32_16x16x32_bf16 v[58:61], v[162:165], v[178:181], v[58:61]
	v_mfma_f32_16x16x32_bf16 v[50:53], v[170:173], v[178:181], v[50:53]
	v_mfma_f32_16x16x32_bf16 v[42:45], v[162:165], v[204:207], v[42:45]
	v_mfma_f32_16x16x32_bf16 v[34:37], v[170:173], v[204:207], v[34:37]
	v_mfma_f32_16x16x32_bf16 v[26:29], v[162:165], v[212:215], v[26:29]
	v_mfma_f32_16x16x32_bf16 v[18:21], v[170:173], v[212:215], v[18:21]
	v_mfma_f32_16x16x32_bf16 v[10:13], v[162:165], v[220:223], v[10:13]
	v_mfma_f32_16x16x32_bf16 v[2:5], v[170:173], v[220:223], v[2:5]
	v_mfma_f32_16x16x32_bf16 v[58:61], v[166:169], v[182:185], v[58:61]
	v_mfma_f32_16x16x32_bf16 v[50:53], v[174:177], v[182:185], v[50:53]
	v_mfma_f32_16x16x32_bf16 v[42:45], v[166:169], v[208:211], v[42:45]
	v_mfma_f32_16x16x32_bf16 v[34:37], v[174:177], v[208:211], v[34:37]
	v_mfma_f32_16x16x32_bf16 v[26:29], v[166:169], v[216:219], v[26:29]
	v_mfma_f32_16x16x32_bf16 v[18:21], v[174:177], v[216:219], v[18:21]
	v_mfma_f32_16x16x32_bf16 v[10:13], v[166:169], v[224:227], v[10:13]
	v_mfma_f32_16x16x32_bf16 v[2:5], v[174:177], v[224:227], v[2:5]
	s_barrier
	s_add_i32 s62, s62, 2
	s_add_u32 s46, s46, 0x100
	s_addc_u32 s47, s47, 0
	s_add_u32 s60, s60, 0x100
	s_addc_u32 s61, s61, 0
	s_cmp_gt_u32 s62, 13
.LBB0_229:
	s_add_u32 s48, s46, 0xfffc0080
	s_addc_u32 s49, s47, -1
	s_add_i32 s63, 0, 0x10000
	s_cmp_eq_u32 s62, 12
	s_cselect_b32 s51, s39, s49
	s_cselect_b32 s50, s58, s48
	v_add_u32_e32 v0, s63, v144
	s_cselect_b32 s49, s23, s61
	s_cselect_b32 s48, s59, s60
	s_add_i32 s66, 0, 0x14000
	ds_read_b128 v[146:149], v0
	ds_read_b128 v[150:153], v0 offset:1024
	ds_read_b128 v[154:157], v0 offset:2048
	ds_read_b128 v[158:161], v0 offset:3072
	v_add_u32_e32 v0, s66, v144
	ds_read_b128 v[162:165], v0
	ds_read_b128 v[166:169], v0 offset:1024
	ds_read_b128 v[170:173], v0 offset:2048
	ds_read_b128 v[174:177], v0 offset:3072
	s_add_i32 m0, s5, 0xc000
	ds_read_b128 v[178:181], v145
	ds_read_b128 v[182:185], v145 offset:1024
	ds_read_b128 v[204:207], v145 offset:2048
	ds_read_b128 v[208:211], v145 offset:3072
	ds_read_b128 v[212:215], v145 offset:4096
	ds_read_b128 v[216:219], v145 offset:5120
	ds_read_b128 v[220:223], v145 offset:6144
	ds_read_b128 v[224:227], v145 offset:7168
	global_load_lds_dwordx4 v138, s[46:47]
	s_add_i32 m0, s5, 0xe000
	s_nop 0
	global_load_lds_dwordx4 v140, s[46:47]
	s_waitcnt vmcnt(8)
	s_waitcnt lgkmcnt(0)
	s_barrier
	v_mfma_f32_16x16x32_bf16 v[118:121], v[146:149], v[178:181], v[118:121]
	v_mfma_f32_16x16x32_bf16 v[114:117], v[154:157], v[178:181], v[114:117]
	v_mfma_f32_16x16x32_bf16 v[110:113], v[146:149], v[204:207], v[110:113]
	v_mfma_f32_16x16x32_bf16 v[102:105], v[154:157], v[204:207], v[102:105]
	v_mfma_f32_16x16x32_bf16 v[94:97], v[146:149], v[212:215], v[94:97]
	v_mfma_f32_16x16x32_bf16 v[86:89], v[154:157], v[212:215], v[86:89]
	v_mfma_f32_16x16x32_bf16 v[78:81], v[146:149], v[220:223], v[78:81]
	v_mfma_f32_16x16x32_bf16 v[70:73], v[154:157], v[220:223], v[70:73]
	v_mfma_f32_16x16x32_bf16 v[118:121], v[150:153], v[182:185], v[118:121]
	v_mfma_f32_16x16x32_bf16 v[114:117], v[158:161], v[182:185], v[114:117]
	v_mfma_f32_16x16x32_bf16 v[110:113], v[150:153], v[208:211], v[110:113]
	v_mfma_f32_16x16x32_bf16 v[102:105], v[158:161], v[208:211], v[102:105]
	v_mfma_f32_16x16x32_bf16 v[94:97], v[150:153], v[216:219], v[94:97]
	v_mfma_f32_16x16x32_bf16 v[86:89], v[158:161], v[216:219], v[86:89]
	v_mfma_f32_16x16x32_bf16 v[78:81], v[150:153], v[224:227], v[78:81]
	v_mfma_f32_16x16x32_bf16 v[70:73], v[158:161], v[224:227], v[70:73]
	v_mfma_f32_16x16x32_bf16 v[126:129], v[162:165], v[178:181], v[126:129]
	v_mfma_f32_16x16x32_bf16 v[122:125], v[170:173], v[178:181], v[122:125]
	v_mfma_f32_16x16x32_bf16 v[106:109], v[162:165], v[204:207], v[106:109]
	v_mfma_f32_16x16x32_bf16 v[98:101], v[170:173], v[204:207], v[98:101]
	v_mfma_f32_16x16x32_bf16 v[90:93], v[162:165], v[212:215], v[90:93]
	v_mfma_f32_16x16x32_bf16 v[82:85], v[170:173], v[212:215], v[82:85]
	v_mfma_f32_16x16x32_bf16 v[74:77], v[162:165], v[220:223], v[74:77]
	v_mfma_f32_16x16x32_bf16 v[66:69], v[170:173], v[220:223], v[66:69]
	v_mfma_f32_16x16x32_bf16 v[126:129], v[166:169], v[182:185], v[126:129]
	v_mfma_f32_16x16x32_bf16 v[122:125], v[174:177], v[182:185], v[122:125]
	v_mfma_f32_16x16x32_bf16 v[106:109], v[166:169], v[208:211], v[106:109]
	v_mfma_f32_16x16x32_bf16 v[98:101], v[174:177], v[208:211], v[98:101]
	v_mfma_f32_16x16x32_bf16 v[90:93], v[166:169], v[216:219], v[90:93]
	v_mfma_f32_16x16x32_bf16 v[82:85], v[174:177], v[216:219], v[82:85]
	v_mfma_f32_16x16x32_bf16 v[74:77], v[166:169], v[224:227], v[74:77]
	v_mfma_f32_16x16x32_bf16 v[66:69], v[174:177], v[224:227], v[66:69]
	s_barrier
	s_add_i32 s63, s63, s4
	s_mov_b32 m0, s63
	ds_read_b128 v[178:181], v145 offset:16384
	ds_read_b128 v[182:185], v145 offset:17408
	ds_read_b128 v[204:207], v145 offset:18432
	ds_read_b128 v[208:211], v145 offset:19456
	ds_read_b128 v[212:215], v145 offset:20480
	ds_read_b128 v[216:219], v145 offset:21504
	ds_read_b128 v[220:223], v145 offset:22528
	ds_read_b128 v[224:227], v145 offset:23552
	global_load_lds_dwordx4 v134, s[48:49]
	s_add_i32 m0, s63, 0x2000
	s_add_u32 s64, s48, 0x40000
	s_addc_u32 s65, s49, 0
	s_add_i32 s63, s66, s4
	global_load_lds_dwordx4 v130, s[48:49]
	s_mov_b32 m0, s63
	s_nop 0
	global_load_lds_dwordx4 v134, s[64:65]
	s_add_i32 m0, s63, 0x2000
	s_nop 0
	global_load_lds_dwordx4 v130, s[64:65]
	s_mov_b32 m0, s5
	s_nop 0
	global_load_lds_dwordx4 v136, s[50:51]
	s_mov_b32 m0, s6
	s_nop 0
	global_load_lds_dwordx4 v132, s[50:51]
	s_waitcnt vmcnt(8)
	s_waitcnt lgkmcnt(0)
	s_barrier
	v_mfma_f32_16x16x32_bf16 v[62:65], v[146:149], v[178:181], v[62:65]
	v_mfma_f32_16x16x32_bf16 v[54:57], v[154:157], v[178:181], v[54:57]
	v_mfma_f32_16x16x32_bf16 v[46:49], v[146:149], v[204:207], v[46:49]
	v_mfma_f32_16x16x32_bf16 v[38:41], v[154:157], v[204:207], v[38:41]
	v_mfma_f32_16x16x32_bf16 v[30:33], v[146:149], v[212:215], v[30:33]
	v_mfma_f32_16x16x32_bf16 v[22:25], v[154:157], v[212:215], v[22:25]
	v_mfma_f32_16x16x32_bf16 v[14:17], v[146:149], v[220:223], v[14:17]
	v_mfma_f32_16x16x32_bf16 v[6:9], v[154:157], v[220:223], v[6:9]
	v_mfma_f32_16x16x32_bf16 v[62:65], v[150:153], v[182:185], v[62:65]
	v_mfma_f32_16x16x32_bf16 v[54:57], v[158:161], v[182:185], v[54:57]
	v_mfma_f32_16x16x32_bf16 v[46:49], v[150:153], v[208:211], v[46:49]
	v_mfma_f32_16x16x32_bf16 v[38:41], v[158:161], v[208:211], v[38:41]
	v_mfma_f32_16x16x32_bf16 v[30:33], v[150:153], v[216:219], v[30:33]
	v_mfma_f32_16x16x32_bf16 v[22:25], v[158:161], v[216:219], v[22:25]
	v_mfma_f32_16x16x32_bf16 v[14:17], v[150:153], v[224:227], v[14:17]
	v_mfma_f32_16x16x32_bf16 v[6:9], v[158:161], v[224:227], v[6:9]
	v_mfma_f32_16x16x32_bf16 v[58:61], v[162:165], v[178:181], v[58:61]
	v_mfma_f32_16x16x32_bf16 v[50:53], v[170:173], v[178:181], v[50:53]
	v_mfma_f32_16x16x32_bf16 v[42:45], v[162:165], v[204:207], v[42:45]
	v_mfma_f32_16x16x32_bf16 v[34:37], v[170:173], v[204:207], v[34:37]
	v_mfma_f32_16x16x32_bf16 v[26:29], v[162:165], v[212:215], v[26:29]
	v_mfma_f32_16x16x32_bf16 v[18:21], v[170:173], v[212:215], v[18:21]
	v_mfma_f32_16x16x32_bf16 v[10:13], v[162:165], v[220:223], v[10:13]
	v_mfma_f32_16x16x32_bf16 v[2:5], v[170:173], v[220:223], v[2:5]
	v_mfma_f32_16x16x32_bf16 v[58:61], v[166:169], v[182:185], v[58:61]
	v_mfma_f32_16x16x32_bf16 v[50:53], v[174:177], v[182:185], v[50:53]
	v_mfma_f32_16x16x32_bf16 v[42:45], v[166:169], v[208:211], v[42:45]
	v_mfma_f32_16x16x32_bf16 v[34:37], v[174:177], v[208:211], v[34:37]
	v_mfma_f32_16x16x32_bf16 v[26:29], v[166:169], v[216:219], v[26:29]
	v_mfma_f32_16x16x32_bf16 v[18:21], v[174:177], v[216:219], v[18:21]
	v_mfma_f32_16x16x32_bf16 v[10:13], v[166:169], v[224:227], v[10:13]
	v_mfma_f32_16x16x32_bf16 v[2:5], v[174:177], v[224:227], v[2:5]
	s_barrier
	s_add_i32 s63, 0, 0x18000
	v_add_u32_e32 v0, s63, v144
	s_add_i32 s64, 0, 0x1c000
	ds_read_b128 v[146:149], v0
	ds_read_b128 v[150:153], v0 offset:1024
	ds_read_b128 v[154:157], v0 offset:2048
	ds_read_b128 v[158:161], v0 offset:3072
	v_add_u32_e32 v0, s64, v144
	ds_read_b128 v[162:165], v0
	ds_read_b128 v[166:169], v0 offset:1024
	ds_read_b128 v[170:173], v0 offset:2048
	ds_read_b128 v[174:177], v0 offset:3072
	s_add_u32 s50, s50, 0x40000
	s_addc_u32 s51, s51, 0
	s_mov_b32 m0, s7
	ds_read_b128 v[178:181], v145 offset:32768
	ds_read_b128 v[182:185], v145 offset:33792
	ds_read_b128 v[204:207], v145 offset:34816
	ds_read_b128 v[208:211], v145 offset:35840
	ds_read_b128 v[212:215], v145 offset:36864
	ds_read_b128 v[216:219], v145 offset:37888
	ds_read_b128 v[220:223], v145 offset:38912
	ds_read_b128 v[224:227], v145 offset:39936
	global_load_lds_dwordx4 v136, s[50:51]
	s_mov_b32 m0, s52
	s_nop 0
	global_load_lds_dwordx4 v132, s[50:51]
	s_waitcnt vmcnt(8)
	s_waitcnt lgkmcnt(0)
	s_barrier
	v_mfma_f32_16x16x32_bf16 v[118:121], v[146:149], v[178:181], v[118:121]
	v_mfma_f32_16x16x32_bf16 v[114:117], v[154:157], v[178:181], v[114:117]
	v_mfma_f32_16x16x32_bf16 v[110:113], v[146:149], v[204:207], v[110:113]
	v_mfma_f32_16x16x32_bf16 v[102:105], v[154:157], v[204:207], v[102:105]
	v_mfma_f32_16x16x32_bf16 v[94:97], v[146:149], v[212:215], v[94:97]
	v_mfma_f32_16x16x32_bf16 v[86:89], v[154:157], v[212:215], v[86:89]
	v_mfma_f32_16x16x32_bf16 v[78:81], v[146:149], v[220:223], v[78:81]
	v_mfma_f32_16x16x32_bf16 v[70:73], v[154:157], v[220:223], v[70:73]
	v_mfma_f32_16x16x32_bf16 v[118:121], v[150:153], v[182:185], v[118:121]
	v_mfma_f32_16x16x32_bf16 v[114:117], v[158:161], v[182:185], v[114:117]
	v_mfma_f32_16x16x32_bf16 v[110:113], v[150:153], v[208:211], v[110:113]
	v_mfma_f32_16x16x32_bf16 v[102:105], v[158:161], v[208:211], v[102:105]
	v_mfma_f32_16x16x32_bf16 v[94:97], v[150:153], v[216:219], v[94:97]
	v_mfma_f32_16x16x32_bf16 v[86:89], v[158:161], v[216:219], v[86:89]
	v_mfma_f32_16x16x32_bf16 v[78:81], v[150:153], v[224:227], v[78:81]
	v_mfma_f32_16x16x32_bf16 v[70:73], v[158:161], v[224:227], v[70:73]
	v_mfma_f32_16x16x32_bf16 v[126:129], v[162:165], v[178:181], v[126:129]
	v_mfma_f32_16x16x32_bf16 v[122:125], v[170:173], v[178:181], v[122:125]
	v_mfma_f32_16x16x32_bf16 v[106:109], v[162:165], v[204:207], v[106:109]
	v_mfma_f32_16x16x32_bf16 v[98:101], v[170:173], v[204:207], v[98:101]
	v_mfma_f32_16x16x32_bf16 v[90:93], v[162:165], v[212:215], v[90:93]
	v_mfma_f32_16x16x32_bf16 v[82:85], v[170:173], v[212:215], v[82:85]
	v_mfma_f32_16x16x32_bf16 v[74:77], v[162:165], v[220:223], v[74:77]
	v_mfma_f32_16x16x32_bf16 v[66:69], v[170:173], v[220:223], v[66:69]
	v_mfma_f32_16x16x32_bf16 v[126:129], v[166:169], v[182:185], v[126:129]
	v_mfma_f32_16x16x32_bf16 v[122:125], v[174:177], v[182:185], v[122:125]
	v_mfma_f32_16x16x32_bf16 v[106:109], v[166:169], v[208:211], v[106:109]
	v_mfma_f32_16x16x32_bf16 v[98:101], v[174:177], v[208:211], v[98:101]
	v_mfma_f32_16x16x32_bf16 v[90:93], v[166:169], v[216:219], v[90:93]
	v_mfma_f32_16x16x32_bf16 v[82:85], v[174:177], v[216:219], v[82:85]
	v_mfma_f32_16x16x32_bf16 v[74:77], v[166:169], v[224:227], v[74:77]
	v_mfma_f32_16x16x32_bf16 v[66:69], v[174:177], v[224:227], v[66:69]
	s_barrier
	s_add_i32 s65, s63, s4
	s_add_u32 s48, s48, 0x80
	s_addc_u32 s49, s49, 0
	s_mov_b32 m0, s65
	ds_read_b128 v[178:181], v145 offset:49152
	ds_read_b128 v[182:185], v145 offset:50176
	ds_read_b128 v[204:207], v145 offset:51200
	ds_read_b128 v[208:211], v145 offset:52224
	ds_read_b128 v[212:215], v145 offset:53248
	ds_read_b128 v[216:219], v145 offset:54272
	ds_read_b128 v[220:223], v145 offset:55296
	ds_read_b128 v[224:227], v145 offset:56320
	global_load_lds_dwordx4 v134, s[48:49]
	s_add_i32 m0, s65, 0x2000
	s_add_i32 s65, s64, s4
	global_load_lds_dwordx4 v130, s[48:49]
	s_add_u32 s48, s48, 0x40000
	s_addc_u32 s49, s49, 0
	s_mov_b32 m0, s65
	s_sub_u32 s50, s50, 0x3ff80
	global_load_lds_dwordx4 v134, s[48:49]
	s_subb_u32 s51, s51, 0
	s_add_i32 m0, s65, 0x2000
	s_nop 0
	global_load_lds_dwordx4 v130, s[48:49]
	s_mov_b32 m0, s55
	s_nop 0
	global_load_lds_dwordx4 v136, s[50:51]
	s_mov_b32 m0, s56
	s_nop 0
	global_load_lds_dwordx4 v132, s[50:51]
	s_waitcnt vmcnt(8)
	s_waitcnt lgkmcnt(0)
	s_barrier
	v_mfma_f32_16x16x32_bf16 v[62:65], v[146:149], v[178:181], v[62:65]
	v_mfma_f32_16x16x32_bf16 v[54:57], v[154:157], v[178:181], v[54:57]
	v_mfma_f32_16x16x32_bf16 v[46:49], v[146:149], v[204:207], v[46:49]
	v_mfma_f32_16x16x32_bf16 v[38:41], v[154:157], v[204:207], v[38:41]
	v_mfma_f32_16x16x32_bf16 v[30:33], v[146:149], v[212:215], v[30:33]
	v_mfma_f32_16x16x32_bf16 v[22:25], v[154:157], v[212:215], v[22:25]
	v_mfma_f32_16x16x32_bf16 v[14:17], v[146:149], v[220:223], v[14:17]
	v_mfma_f32_16x16x32_bf16 v[6:9], v[154:157], v[220:223], v[6:9]
	v_mfma_f32_16x16x32_bf16 v[62:65], v[150:153], v[182:185], v[62:65]
	v_mfma_f32_16x16x32_bf16 v[54:57], v[158:161], v[182:185], v[54:57]
	v_mfma_f32_16x16x32_bf16 v[46:49], v[150:153], v[208:211], v[46:49]
	v_mfma_f32_16x16x32_bf16 v[38:41], v[158:161], v[208:211], v[38:41]
	v_mfma_f32_16x16x32_bf16 v[30:33], v[150:153], v[216:219], v[30:33]
	v_mfma_f32_16x16x32_bf16 v[22:25], v[158:161], v[216:219], v[22:25]
	v_mfma_f32_16x16x32_bf16 v[14:17], v[150:153], v[224:227], v[14:17]
	v_mfma_f32_16x16x32_bf16 v[6:9], v[158:161], v[224:227], v[6:9]
	v_mfma_f32_16x16x32_bf16 v[58:61], v[162:165], v[178:181], v[58:61]
	v_mfma_f32_16x16x32_bf16 v[50:53], v[170:173], v[178:181], v[50:53]
	v_mfma_f32_16x16x32_bf16 v[42:45], v[162:165], v[204:207], v[42:45]
	v_mfma_f32_16x16x32_bf16 v[34:37], v[170:173], v[204:207], v[34:37]
	v_mfma_f32_16x16x32_bf16 v[26:29], v[162:165], v[212:215], v[26:29]
	v_mfma_f32_16x16x32_bf16 v[18:21], v[170:173], v[212:215], v[18:21]
	v_mfma_f32_16x16x32_bf16 v[10:13], v[162:165], v[220:223], v[10:13]
	v_mfma_f32_16x16x32_bf16 v[2:5], v[170:173], v[220:223], v[2:5]
	v_mfma_f32_16x16x32_bf16 v[58:61], v[166:169], v[182:185], v[58:61]
	v_mfma_f32_16x16x32_bf16 v[50:53], v[174:177], v[182:185], v[50:53]
	v_mfma_f32_16x16x32_bf16 v[42:45], v[166:169], v[208:211], v[42:45]
	v_mfma_f32_16x16x32_bf16 v[34:37], v[174:177], v[208:211], v[34:37]
	v_mfma_f32_16x16x32_bf16 v[26:29], v[166:169], v[216:219], v[26:29]
	v_mfma_f32_16x16x32_bf16 v[18:21], v[174:177], v[216:219], v[18:21]
	v_mfma_f32_16x16x32_bf16 v[10:13], v[166:169], v[224:227], v[10:13]
	v_mfma_f32_16x16x32_bf16 v[2:5], v[174:177], v[224:227], v[2:5]
	s_barrier
	s_add_i32 s62, s62, 2
	s_add_u32 s46, s46, 0x100
	s_addc_u32 s47, s47, 0
	s_add_u32 s60, s60, 0x100
	s_addc_u32 s61, s61, 0
	s_cmp_gt_u32 s62, 13
	s_cbranch_scc0 .LBB0_229
	s_and_b64 vcc, exec, s[20:21]
	s_cbranch_vccz .LBB0_232
	s_barrier

.Lrb1_skip:
	s_add_u32 s0, s48, 0x100
	s_addc_u32 s1, s49, 0
	s_add_i32 s51, 0, 0x10000
	s_cmp_eq_u32 s19, 40
	s_cselect_b32 s55, s45, s1
	s_cselect_b32 s54, s44, s0
	v_add_u32_e32 v0, s51, v219
	s_cselect_b32 s53, s47, s18
	s_cselect_b32 s52, s46, s7
	s_add_i32 s66, 0, 0x14000
	ds_read_b128 v[106:109], v0
	ds_read_b128 v[110:113], v0 offset:1024
	ds_read_b128 v[126:129], v0 offset:2048
	ds_read_b128 v[134:137], v0 offset:3072
	v_add_u32_e32 v0, s66, v219
	ds_read_b128 v[146:149], v0
	ds_read_b128 v[150:153], v0 offset:1024
	ds_read_b128 v[154:157], v0 offset:2048
	ds_read_b128 v[158:161], v0 offset:3072
	v_lshl_add_u64 v[216:217], s[48:49], 0, v[212:213]
	s_add_i32 m0, s57, 0xc000
	ds_read_b128 v[162:165], v220
	ds_read_b128 v[166:169], v220 offset:1024
	ds_read_b128 v[170:173], v220 offset:2048
	ds_read_b128 v[174:177], v220 offset:3072
	ds_read_b128 v[178:181], v220 offset:4096
	ds_read_b128 v[182:185], v220 offset:5120
	ds_read_b128 v[222:225], v220 offset:6144
	ds_read_b128 v[226:229], v220 offset:7168
	global_load_lds_dwordx4 v[216:217], off
	v_lshl_add_u64 v[216:217], s[48:49], 0, v[214:215]
	s_add_i32 m0, s57, 0xe000
	s_nop 0
	global_load_lds_dwordx4 v[216:217], off
	s_waitcnt vmcnt(8)
	s_waitcnt lgkmcnt(0)
	s_barrier
	v_mfma_f32_16x16x32_bf16 v[142:145], v[106:109], v[162:165], 0
	v_mfma_f32_16x16x32_bf16 v[138:141], v[126:129], v[162:165], 0
	v_mfma_f32_16x16x32_bf16 v[118:121], v[106:109], v[170:173], 0
	v_mfma_f32_16x16x32_bf16 v[114:117], v[126:129], v[170:173], 0
	v_mfma_f32_16x16x32_bf16 v[94:97], v[106:109], v[178:181], 0
	v_mfma_f32_16x16x32_bf16 v[90:93], v[126:129], v[178:181], 0
	v_mfma_f32_16x16x32_bf16 v[78:81], v[106:109], v[222:225], 0
	v_mfma_f32_16x16x32_bf16 v[74:77], v[126:129], v[222:225], 0
	v_mfma_f32_16x16x32_bf16 v[142:145], v[110:113], v[166:169], v[142:145]
	v_mfma_f32_16x16x32_bf16 v[138:141], v[134:137], v[166:169], v[138:141]
	v_mfma_f32_16x16x32_bf16 v[118:121], v[110:113], v[174:177], v[118:121]
	v_mfma_f32_16x16x32_bf16 v[114:117], v[134:137], v[174:177], v[114:117]
	v_mfma_f32_16x16x32_bf16 v[94:97], v[110:113], v[182:185], v[94:97]
	v_mfma_f32_16x16x32_bf16 v[90:93], v[134:137], v[182:185], v[90:93]
	v_mfma_f32_16x16x32_bf16 v[78:81], v[110:113], v[226:229], v[78:81]
	v_mfma_f32_16x16x32_bf16 v[74:77], v[134:137], v[226:229], v[74:77]
	v_mfma_f32_16x16x32_bf16 v[130:133], v[146:149], v[162:165], 0
	v_mfma_f32_16x16x32_bf16 v[122:125], v[154:157], v[162:165], 0
	v_mfma_f32_16x16x32_bf16 v[102:105], v[146:149], v[170:173], 0
	v_mfma_f32_16x16x32_bf16 v[98:101], v[154:157], v[170:173], 0
	v_mfma_f32_16x16x32_bf16 v[86:89], v[146:149], v[178:181], 0
	v_mfma_f32_16x16x32_bf16 v[82:85], v[154:157], v[178:181], 0
	v_mfma_f32_16x16x32_bf16 v[70:73], v[146:149], v[222:225], 0
	v_mfma_f32_16x16x32_bf16 v[66:69], v[154:157], v[222:225], 0
	v_mfma_f32_16x16x32_bf16 v[130:133], v[150:153], v[166:169], v[130:133]
	v_mfma_f32_16x16x32_bf16 v[122:125], v[158:161], v[166:169], v[122:125]
	v_mfma_f32_16x16x32_bf16 v[102:105], v[150:153], v[174:177], v[102:105]
	v_mfma_f32_16x16x32_bf16 v[98:101], v[158:161], v[174:177], v[98:101]
	v_mfma_f32_16x16x32_bf16 v[86:89], v[150:153], v[182:185], v[86:89]
	v_mfma_f32_16x16x32_bf16 v[82:85], v[158:161], v[182:185], v[82:85]
	v_mfma_f32_16x16x32_bf16 v[70:73], v[150:153], v[226:229], v[70:73]
	v_mfma_f32_16x16x32_bf16 v[66:69], v[158:161], v[226:229], v[66:69]
	s_barrier
	s_add_i32 s48, s51, s56
	v_lshl_add_u64 v[216:217], s[52:53], 0, v[208:209]
	s_mov_b32 m0, s48
	ds_read_b128 v[162:165], v220 offset:16384
	ds_read_b128 v[166:169], v220 offset:17408
	ds_read_b128 v[170:173], v220 offset:18432
	ds_read_b128 v[174:177], v220 offset:19456
	ds_read_b128 v[178:181], v220 offset:20480
	ds_read_b128 v[182:185], v220 offset:21504
	ds_read_b128 v[222:225], v220 offset:22528
	ds_read_b128 v[226:229], v220 offset:23552
	global_load_lds_dwordx4 v[216:217], off
	s_add_i32 m0, s48, 0x2000
	s_add_u32 s48, s52, 0xb0000
	v_lshl_add_u64 v[230:231], s[52:53], 0, v[204:205]
	s_addc_u32 s49, s53, 0
	s_add_i32 s51, s66, s56
	global_load_lds_dwordx4 v[230:231], off
	v_lshl_add_u64 v[240:241], s[48:49], 0, v[208:209]
	s_mov_b32 m0, s51
	v_lshl_add_u64 v[242:243], s[54:55], 0, v[206:207]
	global_load_lds_dwordx4 v[240:241], off
	v_lshl_add_u64 v[240:241], s[48:49], 0, v[204:205]
	s_add_i32 m0, s51, 0x2000
	s_nop 0
	global_load_lds_dwordx4 v[240:241], off
	v_lshl_add_u64 v[240:241], s[54:55], 0, v[210:211]
	s_mov_b32 m0, s57
	s_nop 0
	global_load_lds_dwordx4 v[240:241], off
	s_mov_b32 m0, s58
	s_nop 0
	global_load_lds_dwordx4 v[242:243], off
	s_waitcnt vmcnt(8)
	s_waitcnt lgkmcnt(0)
	s_barrier
	v_mfma_f32_16x16x32_bf16 v[62:65], v[106:109], v[162:165], 0
	v_mfma_f32_16x16x32_bf16 v[58:61], v[126:129], v[162:165], 0
	v_mfma_f32_16x16x32_bf16 v[46:49], v[106:109], v[170:173], 0
	v_mfma_f32_16x16x32_bf16 v[42:45], v[126:129], v[170:173], 0
	v_mfma_f32_16x16x32_bf16 v[30:33], v[106:109], v[178:181], 0
	v_mfma_f32_16x16x32_bf16 v[26:29], v[126:129], v[178:181], 0
	v_mfma_f32_16x16x32_bf16 v[14:17], v[106:109], v[222:225], 0
	v_mfma_f32_16x16x32_bf16 v[10:13], v[126:129], v[222:225], 0
	v_mfma_f32_16x16x32_bf16 v[62:65], v[110:113], v[166:169], v[62:65]
	v_mfma_f32_16x16x32_bf16 v[58:61], v[134:137], v[166:169], v[58:61]
	v_mfma_f32_16x16x32_bf16 v[46:49], v[110:113], v[174:177], v[46:49]
	v_mfma_f32_16x16x32_bf16 v[42:45], v[134:137], v[174:177], v[42:45]
	v_mfma_f32_16x16x32_bf16 v[30:33], v[110:113], v[182:185], v[30:33]
	v_mfma_f32_16x16x32_bf16 v[26:29], v[134:137], v[182:185], v[26:29]
	v_mfma_f32_16x16x32_bf16 v[14:17], v[110:113], v[226:229], v[14:17]
	v_mfma_f32_16x16x32_bf16 v[10:13], v[134:137], v[226:229], v[10:13]
	v_mfma_f32_16x16x32_bf16 v[54:57], v[146:149], v[162:165], 0
	v_mfma_f32_16x16x32_bf16 v[50:53], v[154:157], v[162:165], 0
	v_mfma_f32_16x16x32_bf16 v[38:41], v[146:149], v[170:173], 0
	v_mfma_f32_16x16x32_bf16 v[34:37], v[154:157], v[170:173], 0
	v_mfma_f32_16x16x32_bf16 v[22:25], v[146:149], v[178:181], 0
	v_mfma_f32_16x16x32_bf16 v[18:21], v[154:157], v[178:181], 0
	v_mfma_f32_16x16x32_bf16 v[6:9], v[146:149], v[222:225], 0
	v_mfma_f32_16x16x32_bf16 v[2:5], v[154:157], v[222:225], 0
	v_mfma_f32_16x16x32_bf16 v[54:57], v[150:153], v[166:169], v[54:57]
	v_mfma_f32_16x16x32_bf16 v[50:53], v[158:161], v[166:169], v[50:53]
	v_mfma_f32_16x16x32_bf16 v[38:41], v[150:153], v[174:177], v[38:41]
	v_mfma_f32_16x16x32_bf16 v[34:37], v[158:161], v[174:177], v[34:37]
	v_mfma_f32_16x16x32_bf16 v[22:25], v[150:153], v[182:185], v[22:25]
	v_mfma_f32_16x16x32_bf16 v[18:21], v[158:161], v[182:185], v[18:21]
	v_mfma_f32_16x16x32_bf16 v[6:9], v[150:153], v[226:229], v[6:9]
	v_mfma_f32_16x16x32_bf16 v[2:5], v[158:161], v[226:229], v[2:5]
	s_barrier
	s_add_i32 s51, 0, 0x18000
	v_add_u32_e32 v0, s51, v219
	s_add_i32 s66, 0, 0x1c000
	ds_read_b128 v[106:109], v0
	ds_read_b128 v[110:113], v0 offset:1024
	ds_read_b128 v[126:129], v0 offset:2048
	ds_read_b128 v[134:137], v0 offset:3072
	v_add_u32_e32 v0, s66, v219
	ds_read_b128 v[146:149], v0
	ds_read_b128 v[150:153], v0 offset:1024
	ds_read_b128 v[154:157], v0 offset:2048
	ds_read_b128 v[158:161], v0 offset:3072
	s_add_u32 s48, s54, 0xb0000
	s_addc_u32 s49, s55, 0
	s_mov_b32 m0, s59
	v_lshl_add_u64 v[244:245], s[48:49], 0, v[210:211]
	ds_read_b128 v[162:165], v220 offset:32768
	ds_read_b128 v[166:169], v220 offset:33792
	ds_read_b128 v[170:173], v220 offset:34816
	ds_read_b128 v[174:177], v220 offset:35840
	ds_read_b128 v[178:181], v220 offset:36864
	ds_read_b128 v[182:185], v220 offset:37888
	ds_read_b128 v[222:225], v220 offset:38912
	ds_read_b128 v[226:229], v220 offset:39936
	global_load_lds_dwordx4 v[244:245], off
	v_lshl_add_u64 v[244:245], s[48:49], 0, v[206:207]
	s_mov_b32 m0, s60
	s_nop 0
	global_load_lds_dwordx4 v[244:245], off
	s_waitcnt vmcnt(8)
	s_waitcnt lgkmcnt(0)
	s_barrier
	v_mfma_f32_16x16x32_bf16 v[142:145], v[106:109], v[162:165], v[142:145]
	v_mfma_f32_16x16x32_bf16 v[138:141], v[126:129], v[162:165], v[138:141]
	v_mfma_f32_16x16x32_bf16 v[118:121], v[106:109], v[170:173], v[118:121]
	v_mfma_f32_16x16x32_bf16 v[114:117], v[126:129], v[170:173], v[114:117]
	v_mfma_f32_16x16x32_bf16 v[94:97], v[106:109], v[178:181], v[94:97]
	v_mfma_f32_16x16x32_bf16 v[90:93], v[126:129], v[178:181], v[90:93]
	v_mfma_f32_16x16x32_bf16 v[78:81], v[106:109], v[222:225], v[78:81]
	v_mfma_f32_16x16x32_bf16 v[74:77], v[126:129], v[222:225], v[74:77]
	v_mfma_f32_16x16x32_bf16 v[142:145], v[110:113], v[166:169], v[142:145]
	v_mfma_f32_16x16x32_bf16 v[138:141], v[134:137], v[166:169], v[138:141]
	v_mfma_f32_16x16x32_bf16 v[118:121], v[110:113], v[174:177], v[118:121]
	v_mfma_f32_16x16x32_bf16 v[114:117], v[134:137], v[174:177], v[114:117]
	v_mfma_f32_16x16x32_bf16 v[94:97], v[110:113], v[182:185], v[94:97]
	v_mfma_f32_16x16x32_bf16 v[90:93], v[134:137], v[182:185], v[90:93]
	v_mfma_f32_16x16x32_bf16 v[78:81], v[110:113], v[226:229], v[78:81]
	v_mfma_f32_16x16x32_bf16 v[74:77], v[134:137], v[226:229], v[74:77]
	v_mfma_f32_16x16x32_bf16 v[130:133], v[146:149], v[162:165], v[130:133]
	v_mfma_f32_16x16x32_bf16 v[122:125], v[154:157], v[162:165], v[122:125]
	v_mfma_f32_16x16x32_bf16 v[102:105], v[146:149], v[170:173], v[102:105]
	v_mfma_f32_16x16x32_bf16 v[98:101], v[154:157], v[170:173], v[98:101]
	v_mfma_f32_16x16x32_bf16 v[86:89], v[146:149], v[178:181], v[86:89]
	v_mfma_f32_16x16x32_bf16 v[82:85], v[154:157], v[178:181], v[82:85]
	v_mfma_f32_16x16x32_bf16 v[70:73], v[146:149], v[222:225], v[70:73]
	v_mfma_f32_16x16x32_bf16 v[66:69], v[154:157], v[222:225], v[66:69]
	v_mfma_f32_16x16x32_bf16 v[130:133], v[150:153], v[166:169], v[130:133]
	v_mfma_f32_16x16x32_bf16 v[122:125], v[158:161], v[166:169], v[122:125]
	v_mfma_f32_16x16x32_bf16 v[102:105], v[150:153], v[174:177], v[102:105]
	v_mfma_f32_16x16x32_bf16 v[98:101], v[158:161], v[174:177], v[98:101]
	v_mfma_f32_16x16x32_bf16 v[86:89], v[150:153], v[182:185], v[86:89]
	v_mfma_f32_16x16x32_bf16 v[82:85], v[158:161], v[182:185], v[82:85]
	v_mfma_f32_16x16x32_bf16 v[70:73], v[150:153], v[226:229], v[70:73]
	v_mfma_f32_16x16x32_bf16 v[66:69], v[158:161], v[226:229], v[66:69]
	s_barrier
	s_add_i32 s48, s51, s56
	v_lshl_add_u64 v[216:217], v[216:217], 0, s[16:17]
	s_mov_b32 m0, s48
	ds_read_b128 v[162:165], v220 offset:49152
	ds_read_b128 v[166:169], v220 offset:50176
	ds_read_b128 v[170:173], v220 offset:51200
	ds_read_b128 v[174:177], v220 offset:52224
	ds_read_b128 v[178:181], v220 offset:53248
	ds_read_b128 v[182:185], v220 offset:54272
	ds_read_b128 v[222:225], v220 offset:55296
	ds_read_b128 v[226:229], v220 offset:56320
	global_load_lds_dwordx4 v[216:217], off
	s_add_i32 m0, s48, 0x2000
	s_add_u32 s48, s52, 0xb0080
	v_lshl_add_u64 v[216:217], v[230:231], 0, s[16:17]
	s_addc_u32 s49, s53, 0
	s_add_i32 s51, s66, s56
	global_load_lds_dwordx4 v[216:217], off
	v_lshl_add_u64 v[216:217], s[48:49], 0, v[208:209]
	s_mov_b32 m0, s51
	s_nop 0
	global_load_lds_dwordx4 v[216:217], off
	v_lshl_add_u64 v[216:217], s[48:49], 0, v[204:205]
	s_add_i32 m0, s51, 0x2000
	s_nop 0
	global_load_lds_dwordx4 v[216:217], off
	v_lshl_add_u64 v[216:217], v[240:241], 0, s[16:17]
	s_mov_b32 m0, s63
	s_nop 0
	global_load_lds_dwordx4 v[216:217], off
	v_lshl_add_u64 v[216:217], v[242:243], 0, s[16:17]
	s_mov_b32 m0, s64
	s_nop 0
	global_load_lds_dwordx4 v[216:217], off
	s_waitcnt vmcnt(8)
	s_waitcnt lgkmcnt(0)
	s_barrier
	v_mfma_f32_16x16x32_bf16 v[62:65], v[106:109], v[162:165], v[62:65]
	v_mfma_f32_16x16x32_bf16 v[58:61], v[126:129], v[162:165], v[58:61]
	v_mfma_f32_16x16x32_bf16 v[46:49], v[106:109], v[170:173], v[46:49]
	v_mfma_f32_16x16x32_bf16 v[42:45], v[126:129], v[170:173], v[42:45]
	v_mfma_f32_16x16x32_bf16 v[30:33], v[106:109], v[178:181], v[30:33]
	v_mfma_f32_16x16x32_bf16 v[26:29], v[126:129], v[178:181], v[26:29]
	v_mfma_f32_16x16x32_bf16 v[14:17], v[106:109], v[222:225], v[14:17]
	v_mfma_f32_16x16x32_bf16 v[10:13], v[126:129], v[222:225], v[10:13]
	v_mfma_f32_16x16x32_bf16 v[62:65], v[110:113], v[166:169], v[62:65]
	v_mfma_f32_16x16x32_bf16 v[58:61], v[134:137], v[166:169], v[58:61]
	v_mfma_f32_16x16x32_bf16 v[46:49], v[110:113], v[174:177], v[46:49]
	v_mfma_f32_16x16x32_bf16 v[42:45], v[134:137], v[174:177], v[42:45]
	v_mfma_f32_16x16x32_bf16 v[30:33], v[110:113], v[182:185], v[30:33]
	v_mfma_f32_16x16x32_bf16 v[26:29], v[134:137], v[182:185], v[26:29]
	v_mfma_f32_16x16x32_bf16 v[14:17], v[110:113], v[226:229], v[14:17]
	v_mfma_f32_16x16x32_bf16 v[10:13], v[134:137], v[226:229], v[10:13]
	v_mfma_f32_16x16x32_bf16 v[54:57], v[146:149], v[162:165], v[54:57]
	v_mfma_f32_16x16x32_bf16 v[50:53], v[154:157], v[162:165], v[50:53]
	v_mfma_f32_16x16x32_bf16 v[38:41], v[146:149], v[170:173], v[38:41]
	v_mfma_f32_16x16x32_bf16 v[34:37], v[154:157], v[170:173], v[34:37]
	v_mfma_f32_16x16x32_bf16 v[22:25], v[146:149], v[178:181], v[22:25]
	v_mfma_f32_16x16x32_bf16 v[18:21], v[154:157], v[178:181], v[18:21]
	v_mfma_f32_16x16x32_bf16 v[6:9], v[146:149], v[222:225], v[6:9]
	v_mfma_f32_16x16x32_bf16 v[2:5], v[154:157], v[222:225], v[2:5]
	v_mfma_f32_16x16x32_bf16 v[54:57], v[150:153], v[166:169], v[54:57]
	v_mfma_f32_16x16x32_bf16 v[50:53], v[158:161], v[166:169], v[50:53]
	v_mfma_f32_16x16x32_bf16 v[38:41], v[150:153], v[174:177], v[38:41]
	v_mfma_f32_16x16x32_bf16 v[34:37], v[158:161], v[174:177], v[34:37]
	v_mfma_f32_16x16x32_bf16 v[22:25], v[150:153], v[182:185], v[22:25]
	v_mfma_f32_16x16x32_bf16 v[18:21], v[158:161], v[182:185], v[18:21]
	v_mfma_f32_16x16x32_bf16 v[6:9], v[150:153], v[226:229], v[6:9]
	v_mfma_f32_16x16x32_bf16 v[2:5], v[158:161], v[226:229], v[2:5]
	s_barrier
	s_add_i32 s19, s19, 2
	s_add_u32 s7, s7, 0x100
	s_addc_u32 s18, s18, 0
	s_cmp_gt_u32 s19, 41
	s_mov_b64 s[48:49], s[0:1]
.LBB0_320:
	s_add_u32 s0, s48, 0x100
	s_addc_u32 s1, s49, 0
	s_add_i32 s51, 0, 0x10000
	s_cmp_eq_u32 s19, 40
	s_cselect_b32 s55, s45, s1
	s_cselect_b32 s54, s44, s0
	v_add_u32_e32 v0, s51, v219
	s_cselect_b32 s53, s47, s18
	s_cselect_b32 s52, s46, s7
	s_add_i32 s66, 0, 0x14000
	ds_read_b128 v[106:109], v0
	ds_read_b128 v[110:113], v0 offset:1024
	ds_read_b128 v[126:129], v0 offset:2048
	ds_read_b128 v[134:137], v0 offset:3072
	v_add_u32_e32 v0, s66, v219
	ds_read_b128 v[146:149], v0
	ds_read_b128 v[150:153], v0 offset:1024
	ds_read_b128 v[154:157], v0 offset:2048
	ds_read_b128 v[158:161], v0 offset:3072
	v_lshl_add_u64 v[216:217], s[48:49], 0, v[212:213]
	s_add_i32 m0, s57, 0xc000
	ds_read_b128 v[162:165], v220
	ds_read_b128 v[166:169], v220 offset:1024
	ds_read_b128 v[170:173], v220 offset:2048
	ds_read_b128 v[174:177], v220 offset:3072
	ds_read_b128 v[178:181], v220 offset:4096
	ds_read_b128 v[182:185], v220 offset:5120
	ds_read_b128 v[222:225], v220 offset:6144
	ds_read_b128 v[226:229], v220 offset:7168
	global_load_lds_dwordx4 v[216:217], off
	v_lshl_add_u64 v[216:217], s[48:49], 0, v[214:215]
	s_add_i32 m0, s57, 0xe000
	s_nop 0
	global_load_lds_dwordx4 v[216:217], off
	s_waitcnt vmcnt(8)
	s_waitcnt lgkmcnt(0)
	s_barrier
	v_mfma_f32_16x16x32_bf16 v[142:145], v[106:109], v[162:165], v[142:145]
	v_mfma_f32_16x16x32_bf16 v[138:141], v[126:129], v[162:165], v[138:141]
	v_mfma_f32_16x16x32_bf16 v[118:121], v[106:109], v[170:173], v[118:121]
	v_mfma_f32_16x16x32_bf16 v[114:117], v[126:129], v[170:173], v[114:117]
	v_mfma_f32_16x16x32_bf16 v[94:97], v[106:109], v[178:181], v[94:97]
	v_mfma_f32_16x16x32_bf16 v[90:93], v[126:129], v[178:181], v[90:93]
	v_mfma_f32_16x16x32_bf16 v[78:81], v[106:109], v[222:225], v[78:81]
	v_mfma_f32_16x16x32_bf16 v[74:77], v[126:129], v[222:225], v[74:77]
	v_mfma_f32_16x16x32_bf16 v[142:145], v[110:113], v[166:169], v[142:145]
	v_mfma_f32_16x16x32_bf16 v[138:141], v[134:137], v[166:169], v[138:141]
	v_mfma_f32_16x16x32_bf16 v[118:121], v[110:113], v[174:177], v[118:121]
	v_mfma_f32_16x16x32_bf16 v[114:117], v[134:137], v[174:177], v[114:117]
	v_mfma_f32_16x16x32_bf16 v[94:97], v[110:113], v[182:185], v[94:97]
	v_mfma_f32_16x16x32_bf16 v[90:93], v[134:137], v[182:185], v[90:93]
	v_mfma_f32_16x16x32_bf16 v[78:81], v[110:113], v[226:229], v[78:81]
	v_mfma_f32_16x16x32_bf16 v[74:77], v[134:137], v[226:229], v[74:77]
	v_mfma_f32_16x16x32_bf16 v[130:133], v[146:149], v[162:165], v[130:133]
	v_mfma_f32_16x16x32_bf16 v[122:125], v[154:157], v[162:165], v[122:125]
	v_mfma_f32_16x16x32_bf16 v[102:105], v[146:149], v[170:173], v[102:105]
	v_mfma_f32_16x16x32_bf16 v[98:101], v[154:157], v[170:173], v[98:101]
	v_mfma_f32_16x16x32_bf16 v[86:89], v[146:149], v[178:181], v[86:89]
	v_mfma_f32_16x16x32_bf16 v[82:85], v[154:157], v[178:181], v[82:85]
	v_mfma_f32_16x16x32_bf16 v[70:73], v[146:149], v[222:225], v[70:73]
	v_mfma_f32_16x16x32_bf16 v[66:69], v[154:157], v[222:225], v[66:69]
	v_mfma_f32_16x16x32_bf16 v[130:133], v[150:153], v[166:169], v[130:133]
	v_mfma_f32_16x16x32_bf16 v[122:125], v[158:161], v[166:169], v[122:125]
	v_mfma_f32_16x16x32_bf16 v[102:105], v[150:153], v[174:177], v[102:105]
	v_mfma_f32_16x16x32_bf16 v[98:101], v[158:161], v[174:177], v[98:101]
	v_mfma_f32_16x16x32_bf16 v[86:89], v[150:153], v[182:185], v[86:89]
	v_mfma_f32_16x16x32_bf16 v[82:85], v[158:161], v[182:185], v[82:85]
	v_mfma_f32_16x16x32_bf16 v[70:73], v[150:153], v[226:229], v[70:73]
	v_mfma_f32_16x16x32_bf16 v[66:69], v[158:161], v[226:229], v[66:69]
	s_barrier
	s_add_i32 s48, s51, s56
	v_lshl_add_u64 v[216:217], s[52:53], 0, v[208:209]
	s_mov_b32 m0, s48
	ds_read_b128 v[162:165], v220 offset:16384
	ds_read_b128 v[166:169], v220 offset:17408
	ds_read_b128 v[170:173], v220 offset:18432
	ds_read_b128 v[174:177], v220 offset:19456
	ds_read_b128 v[178:181], v220 offset:20480
	ds_read_b128 v[182:185], v220 offset:21504
	ds_read_b128 v[222:225], v220 offset:22528
	ds_read_b128 v[226:229], v220 offset:23552
	global_load_lds_dwordx4 v[216:217], off
	s_add_i32 m0, s48, 0x2000
	s_add_u32 s48, s52, 0xb0000
	v_lshl_add_u64 v[230:231], s[52:53], 0, v[204:205]
	s_addc_u32 s49, s53, 0
	s_add_i32 s51, s66, s56
	global_load_lds_dwordx4 v[230:231], off
	v_lshl_add_u64 v[240:241], s[48:49], 0, v[208:209]
	s_mov_b32 m0, s51
	v_lshl_add_u64 v[242:243], s[54:55], 0, v[206:207]
	global_load_lds_dwordx4 v[240:241], off
	v_lshl_add_u64 v[240:241], s[48:49], 0, v[204:205]
	s_add_i32 m0, s51, 0x2000
	s_nop 0
	global_load_lds_dwordx4 v[240:241], off
	v_lshl_add_u64 v[240:241], s[54:55], 0, v[210:211]
	s_mov_b32 m0, s57
	s_nop 0
	global_load_lds_dwordx4 v[240:241], off
	s_mov_b32 m0, s58
	s_nop 0
	global_load_lds_dwordx4 v[242:243], off
	s_waitcnt vmcnt(8)
	s_waitcnt lgkmcnt(0)
	s_barrier
	v_mfma_f32_16x16x32_bf16 v[62:65], v[106:109], v[162:165], v[62:65]
	v_mfma_f32_16x16x32_bf16 v[58:61], v[126:129], v[162:165], v[58:61]
	v_mfma_f32_16x16x32_bf16 v[46:49], v[106:109], v[170:173], v[46:49]
	v_mfma_f32_16x16x32_bf16 v[42:45], v[126:129], v[170:173], v[42:45]
	v_mfma_f32_16x16x32_bf16 v[30:33], v[106:109], v[178:181], v[30:33]
	v_mfma_f32_16x16x32_bf16 v[26:29], v[126:129], v[178:181], v[26:29]
	v_mfma_f32_16x16x32_bf16 v[14:17], v[106:109], v[222:225], v[14:17]
	v_mfma_f32_16x16x32_bf16 v[10:13], v[126:129], v[222:225], v[10:13]
	v_mfma_f32_16x16x32_bf16 v[62:65], v[110:113], v[166:169], v[62:65]
	v_mfma_f32_16x16x32_bf16 v[58:61], v[134:137], v[166:169], v[58:61]
	v_mfma_f32_16x16x32_bf16 v[46:49], v[110:113], v[174:177], v[46:49]
	v_mfma_f32_16x16x32_bf16 v[42:45], v[134:137], v[174:177], v[42:45]
	v_mfma_f32_16x16x32_bf16 v[30:33], v[110:113], v[182:185], v[30:33]
	v_mfma_f32_16x16x32_bf16 v[26:29], v[134:137], v[182:185], v[26:29]
	v_mfma_f32_16x16x32_bf16 v[14:17], v[110:113], v[226:229], v[14:17]
	v_mfma_f32_16x16x32_bf16 v[10:13], v[134:137], v[226:229], v[10:13]
	v_mfma_f32_16x16x32_bf16 v[54:57], v[146:149], v[162:165], v[54:57]
	v_mfma_f32_16x16x32_bf16 v[50:53], v[154:157], v[162:165], v[50:53]
	v_mfma_f32_16x16x32_bf16 v[38:41], v[146:149], v[170:173], v[38:41]
	v_mfma_f32_16x16x32_bf16 v[34:37], v[154:157], v[170:173], v[34:37]
	v_mfma_f32_16x16x32_bf16 v[22:25], v[146:149], v[178:181], v[22:25]
	v_mfma_f32_16x16x32_bf16 v[18:21], v[154:157], v[178:181], v[18:21]
	v_mfma_f32_16x16x32_bf16 v[6:9], v[146:149], v[222:225], v[6:9]
	v_mfma_f32_16x16x32_bf16 v[2:5], v[154:157], v[222:225], v[2:5]
	v_mfma_f32_16x16x32_bf16 v[54:57], v[150:153], v[166:169], v[54:57]
	v_mfma_f32_16x16x32_bf16 v[50:53], v[158:161], v[166:169], v[50:53]
	v_mfma_f32_16x16x32_bf16 v[38:41], v[150:153], v[174:177], v[38:41]
	v_mfma_f32_16x16x32_bf16 v[34:37], v[158:161], v[174:177], v[34:37]
	v_mfma_f32_16x16x32_bf16 v[22:25], v[150:153], v[182:185], v[22:25]
	v_mfma_f32_16x16x32_bf16 v[18:21], v[158:161], v[182:185], v[18:21]
	v_mfma_f32_16x16x32_bf16 v[6:9], v[150:153], v[226:229], v[6:9]
	v_mfma_f32_16x16x32_bf16 v[2:5], v[158:161], v[226:229], v[2:5]
	s_barrier
	s_add_i32 s51, 0, 0x18000
	v_add_u32_e32 v0, s51, v219
	s_add_i32 s66, 0, 0x1c000
	ds_read_b128 v[106:109], v0
	ds_read_b128 v[110:113], v0 offset:1024
	ds_read_b128 v[126:129], v0 offset:2048
	ds_read_b128 v[134:137], v0 offset:3072
	v_add_u32_e32 v0, s66, v219
	ds_read_b128 v[146:149], v0
	ds_read_b128 v[150:153], v0 offset:1024
	ds_read_b128 v[154:157], v0 offset:2048
	ds_read_b128 v[158:161], v0 offset:3072
	s_add_u32 s48, s54, 0xb0000
	s_addc_u32 s49, s55, 0
	s_mov_b32 m0, s59
	v_lshl_add_u64 v[244:245], s[48:49], 0, v[210:211]
	ds_read_b128 v[162:165], v220 offset:32768
	ds_read_b128 v[166:169], v220 offset:33792
	ds_read_b128 v[170:173], v220 offset:34816
	ds_read_b128 v[174:177], v220 offset:35840
	ds_read_b128 v[178:181], v220 offset:36864
	ds_read_b128 v[182:185], v220 offset:37888
	ds_read_b128 v[222:225], v220 offset:38912
	ds_read_b128 v[226:229], v220 offset:39936
	global_load_lds_dwordx4 v[244:245], off
	v_lshl_add_u64 v[244:245], s[48:49], 0, v[206:207]
	s_mov_b32 m0, s60
	s_nop 0
	global_load_lds_dwordx4 v[244:245], off
	s_waitcnt vmcnt(8)
	s_waitcnt lgkmcnt(0)
	s_barrier
	v_mfma_f32_16x16x32_bf16 v[142:145], v[106:109], v[162:165], v[142:145]
	v_mfma_f32_16x16x32_bf16 v[138:141], v[126:129], v[162:165], v[138:141]
	v_mfma_f32_16x16x32_bf16 v[118:121], v[106:109], v[170:173], v[118:121]
	v_mfma_f32_16x16x32_bf16 v[114:117], v[126:129], v[170:173], v[114:117]
	v_mfma_f32_16x16x32_bf16 v[94:97], v[106:109], v[178:181], v[94:97]
	v_mfma_f32_16x16x32_bf16 v[90:93], v[126:129], v[178:181], v[90:93]
	v_mfma_f32_16x16x32_bf16 v[78:81], v[106:109], v[222:225], v[78:81]
	v_mfma_f32_16x16x32_bf16 v[74:77], v[126:129], v[222:225], v[74:77]
	v_mfma_f32_16x16x32_bf16 v[142:145], v[110:113], v[166:169], v[142:145]
	v_mfma_f32_16x16x32_bf16 v[138:141], v[134:137], v[166:169], v[138:141]
	v_mfma_f32_16x16x32_bf16 v[118:121], v[110:113], v[174:177], v[118:121]
	v_mfma_f32_16x16x32_bf16 v[114:117], v[134:137], v[174:177], v[114:117]
	v_mfma_f32_16x16x32_bf16 v[94:97], v[110:113], v[182:185], v[94:97]
	v_mfma_f32_16x16x32_bf16 v[90:93], v[134:137], v[182:185], v[90:93]
	v_mfma_f32_16x16x32_bf16 v[78:81], v[110:113], v[226:229], v[78:81]
	v_mfma_f32_16x16x32_bf16 v[74:77], v[134:137], v[226:229], v[74:77]
	v_mfma_f32_16x16x32_bf16 v[130:133], v[146:149], v[162:165], v[130:133]
	v_mfma_f32_16x16x32_bf16 v[122:125], v[154:157], v[162:165], v[122:125]
	v_mfma_f32_16x16x32_bf16 v[102:105], v[146:149], v[170:173], v[102:105]
	v_mfma_f32_16x16x32_bf16 v[98:101], v[154:157], v[170:173], v[98:101]
	v_mfma_f32_16x16x32_bf16 v[86:89], v[146:149], v[178:181], v[86:89]
	v_mfma_f32_16x16x32_bf16 v[82:85], v[154:157], v[178:181], v[82:85]
	v_mfma_f32_16x16x32_bf16 v[70:73], v[146:149], v[222:225], v[70:73]
	v_mfma_f32_16x16x32_bf16 v[66:69], v[154:157], v[222:225], v[66:69]
	v_mfma_f32_16x16x32_bf16 v[130:133], v[150:153], v[166:169], v[130:133]
	v_mfma_f32_16x16x32_bf16 v[122:125], v[158:161], v[166:169], v[122:125]
	v_mfma_f32_16x16x32_bf16 v[102:105], v[150:153], v[174:177], v[102:105]
	v_mfma_f32_16x16x32_bf16 v[98:101], v[158:161], v[174:177], v[98:101]
	v_mfma_f32_16x16x32_bf16 v[86:89], v[150:153], v[182:185], v[86:89]
	v_mfma_f32_16x16x32_bf16 v[82:85], v[158:161], v[182:185], v[82:85]
	v_mfma_f32_16x16x32_bf16 v[70:73], v[150:153], v[226:229], v[70:73]
	v_mfma_f32_16x16x32_bf16 v[66:69], v[158:161], v[226:229], v[66:69]
	s_barrier
	s_add_i32 s48, s51, s56
	v_lshl_add_u64 v[216:217], v[216:217], 0, s[16:17]
	s_mov_b32 m0, s48
	ds_read_b128 v[162:165], v220 offset:49152
	ds_read_b128 v[166:169], v220 offset:50176
	ds_read_b128 v[170:173], v220 offset:51200
	ds_read_b128 v[174:177], v220 offset:52224
	ds_read_b128 v[178:181], v220 offset:53248
	ds_read_b128 v[182:185], v220 offset:54272
	ds_read_b128 v[222:225], v220 offset:55296
	ds_read_b128 v[226:229], v220 offset:56320
	global_load_lds_dwordx4 v[216:217], off
	s_add_i32 m0, s48, 0x2000
	s_add_u32 s48, s52, 0xb0080
	v_lshl_add_u64 v[216:217], v[230:231], 0, s[16:17]
	s_addc_u32 s49, s53, 0
	s_add_i32 s51, s66, s56
	global_load_lds_dwordx4 v[216:217], off
	v_lshl_add_u64 v[216:217], s[48:49], 0, v[208:209]
	s_mov_b32 m0, s51
	s_nop 0
	global_load_lds_dwordx4 v[216:217], off
	v_lshl_add_u64 v[216:217], s[48:49], 0, v[204:205]
	s_add_i32 m0, s51, 0x2000
	s_nop 0
	global_load_lds_dwordx4 v[216:217], off
	v_lshl_add_u64 v[216:217], v[240:241], 0, s[16:17]
	s_mov_b32 m0, s63
	s_nop 0
	global_load_lds_dwordx4 v[216:217], off
	v_lshl_add_u64 v[216:217], v[242:243], 0, s[16:17]
	s_mov_b32 m0, s64
	s_nop 0
	global_load_lds_dwordx4 v[216:217], off
	s_waitcnt vmcnt(8)
	s_waitcnt lgkmcnt(0)
	s_barrier
	v_mfma_f32_16x16x32_bf16 v[62:65], v[106:109], v[162:165], v[62:65]
	v_mfma_f32_16x16x32_bf16 v[58:61], v[126:129], v[162:165], v[58:61]
	v_mfma_f32_16x16x32_bf16 v[46:49], v[106:109], v[170:173], v[46:49]
	v_mfma_f32_16x16x32_bf16 v[42:45], v[126:129], v[170:173], v[42:45]
	v_mfma_f32_16x16x32_bf16 v[30:33], v[106:109], v[178:181], v[30:33]
	v_mfma_f32_16x16x32_bf16 v[26:29], v[126:129], v[178:181], v[26:29]
	v_mfma_f32_16x16x32_bf16 v[14:17], v[106:109], v[222:225], v[14:17]
	v_mfma_f32_16x16x32_bf16 v[10:13], v[126:129], v[222:225], v[10:13]
	v_mfma_f32_16x16x32_bf16 v[62:65], v[110:113], v[166:169], v[62:65]
	v_mfma_f32_16x16x32_bf16 v[58:61], v[134:137], v[166:169], v[58:61]
	v_mfma_f32_16x16x32_bf16 v[46:49], v[110:113], v[174:177], v[46:49]
	v_mfma_f32_16x16x32_bf16 v[42:45], v[134:137], v[174:177], v[42:45]
	v_mfma_f32_16x16x32_bf16 v[30:33], v[110:113], v[182:185], v[30:33]
	v_mfma_f32_16x16x32_bf16 v[26:29], v[134:137], v[182:185], v[26:29]
	v_mfma_f32_16x16x32_bf16 v[14:17], v[110:113], v[226:229], v[14:17]
	v_mfma_f32_16x16x32_bf16 v[10:13], v[134:137], v[226:229], v[10:13]
	v_mfma_f32_16x16x32_bf16 v[54:57], v[146:149], v[162:165], v[54:57]
	v_mfma_f32_16x16x32_bf16 v[50:53], v[154:157], v[162:165], v[50:53]
	v_mfma_f32_16x16x32_bf16 v[38:41], v[146:149], v[170:173], v[38:41]
	v_mfma_f32_16x16x32_bf16 v[34:37], v[154:157], v[170:173], v[34:37]
	v_mfma_f32_16x16x32_bf16 v[22:25], v[146:149], v[178:181], v[22:25]
	v_mfma_f32_16x16x32_bf16 v[18:21], v[154:157], v[178:181], v[18:21]
	v_mfma_f32_16x16x32_bf16 v[6:9], v[146:149], v[222:225], v[6:9]
	v_mfma_f32_16x16x32_bf16 v[2:5], v[154:157], v[222:225], v[2:5]
	v_mfma_f32_16x16x32_bf16 v[54:57], v[150:153], v[166:169], v[54:57]
	v_mfma_f32_16x16x32_bf16 v[50:53], v[158:161], v[166:169], v[50:53]
	v_mfma_f32_16x16x32_bf16 v[38:41], v[150:153], v[174:177], v[38:41]
	v_mfma_f32_16x16x32_bf16 v[34:37], v[158:161], v[174:177], v[34:37]
	v_mfma_f32_16x16x32_bf16 v[22:25], v[150:153], v[182:185], v[22:25]
	v_mfma_f32_16x16x32_bf16 v[18:21], v[158:161], v[182:185], v[18:21]
	v_mfma_f32_16x16x32_bf16 v[6:9], v[150:153], v[226:229], v[6:9]
	v_mfma_f32_16x16x32_bf16 v[2:5], v[158:161], v[226:229], v[2:5]
	s_barrier
	s_add_i32 s19, s19, 2
	s_add_u32 s7, s7, 0x100
	s_addc_u32 s18, s18, 0
	s_cmp_gt_u32 s19, 41
	s_mov_b64 s[48:49], s[0:1]
	s_cbranch_scc0 .LBB0_320
	s_and_b64 vcc, exec, s[40:41]
	s_cbranch_vccz .LBB0_323
	s_barrier

.Lrb2_skip:
	s_add_u32 s54, s52, 0xfffc0080
	s_addc_u32 s55, s53, -1
	s_add_i32 s67, 0, 0x10000
	s_cmp_eq_u32 s66, 12
	s_cselect_b32 s57, s19, s55
	s_cselect_b32 s56, s45, s54
	v_add_u32_e32 v0, s67, v158
	s_cselect_b32 s55, s41, s65
	s_cselect_b32 s54, s51, s64
	s_add_i32 s70, 0, 0x14000
	ds_read_b128 v[142:145], v0
	ds_read_b128 v[146:149], v0 offset:1024
	ds_read_b128 v[150:153], v0 offset:2048
	ds_read_b128 v[160:163], v0 offset:3072
	v_add_u32_e32 v0, s70, v158
	ds_read_b128 v[164:167], v0
	ds_read_b128 v[168:171], v0 offset:1024
	ds_read_b128 v[172:175], v0 offset:2048
	ds_read_b128 v[176:179], v0 offset:3072
	s_add_i32 m0, s59, 0xc000
	ds_read_b128 v[180:183], v159
	ds_read_b128 v[204:207], v159 offset:1024
	ds_read_b128 v[208:211], v159 offset:2048
	ds_read_b128 v[212:215], v159 offset:3072
	ds_read_b128 v[216:219], v159 offset:4096
	ds_read_b128 v[220:223], v159 offset:5120
	ds_read_b128 v[224:227], v159 offset:6144
	ds_read_b128 v[228:231], v159 offset:7168
	global_load_lds_dwordx4 v138, s[52:53]
	s_add_i32 m0, s59, 0xe000
	s_nop 0
	global_load_lds_dwordx4 v140, s[52:53]
	s_waitcnt vmcnt(8)
	s_waitcnt lgkmcnt(0)
	s_barrier
	v_mfma_f32_16x16x32_bf16 v[126:129], v[142:145], v[180:183], 0
	v_mfma_f32_16x16x32_bf16 v[122:125], v[150:153], v[180:183], 0
	v_mfma_f32_16x16x32_bf16 v[110:113], v[142:145], v[208:211], 0
	v_mfma_f32_16x16x32_bf16 v[106:109], v[150:153], v[208:211], 0
	v_mfma_f32_16x16x32_bf16 v[94:97], v[142:145], v[216:219], 0
	v_mfma_f32_16x16x32_bf16 v[90:93], v[150:153], v[216:219], 0
	v_mfma_f32_16x16x32_bf16 v[78:81], v[142:145], v[224:227], 0
	v_mfma_f32_16x16x32_bf16 v[74:77], v[150:153], v[224:227], 0
	v_mfma_f32_16x16x32_bf16 v[126:129], v[146:149], v[204:207], v[126:129]
	v_mfma_f32_16x16x32_bf16 v[122:125], v[160:163], v[204:207], v[122:125]
	v_mfma_f32_16x16x32_bf16 v[110:113], v[146:149], v[212:215], v[110:113]
	v_mfma_f32_16x16x32_bf16 v[106:109], v[160:163], v[212:215], v[106:109]
	v_mfma_f32_16x16x32_bf16 v[94:97], v[146:149], v[220:223], v[94:97]
	v_mfma_f32_16x16x32_bf16 v[90:93], v[160:163], v[220:223], v[90:93]
	v_mfma_f32_16x16x32_bf16 v[78:81], v[146:149], v[228:231], v[78:81]
	v_mfma_f32_16x16x32_bf16 v[74:77], v[160:163], v[228:231], v[74:77]
	v_mfma_f32_16x16x32_bf16 v[118:121], v[164:167], v[180:183], 0
	v_mfma_f32_16x16x32_bf16 v[114:117], v[172:175], v[180:183], 0
	v_mfma_f32_16x16x32_bf16 v[102:105], v[164:167], v[208:211], 0
	v_mfma_f32_16x16x32_bf16 v[98:101], v[172:175], v[208:211], 0
	v_mfma_f32_16x16x32_bf16 v[86:89], v[164:167], v[216:219], 0
	v_mfma_f32_16x16x32_bf16 v[82:85], v[172:175], v[216:219], 0
	v_mfma_f32_16x16x32_bf16 v[70:73], v[164:167], v[224:227], 0
	v_mfma_f32_16x16x32_bf16 v[66:69], v[172:175], v[224:227], 0
	v_mfma_f32_16x16x32_bf16 v[118:121], v[168:171], v[204:207], v[118:121]
	v_mfma_f32_16x16x32_bf16 v[114:117], v[176:179], v[204:207], v[114:117]
	v_mfma_f32_16x16x32_bf16 v[102:105], v[168:171], v[212:215], v[102:105]
	v_mfma_f32_16x16x32_bf16 v[98:101], v[176:179], v[212:215], v[98:101]
	v_mfma_f32_16x16x32_bf16 v[86:89], v[168:171], v[220:223], v[86:89]
	v_mfma_f32_16x16x32_bf16 v[82:85], v[176:179], v[220:223], v[82:85]
	v_mfma_f32_16x16x32_bf16 v[70:73], v[168:171], v[228:231], v[70:73]
	v_mfma_f32_16x16x32_bf16 v[66:69], v[176:179], v[228:231], v[66:69]
	s_barrier
	s_add_i32 s67, s67, s58
	s_mov_b32 m0, s67
	ds_read_b128 v[180:183], v159 offset:16384
	ds_read_b128 v[204:207], v159 offset:17408
	ds_read_b128 v[208:211], v159 offset:18432
	ds_read_b128 v[212:215], v159 offset:19456
	ds_read_b128 v[216:219], v159 offset:20480
	ds_read_b128 v[220:223], v159 offset:21504
	ds_read_b128 v[224:227], v159 offset:22528
	ds_read_b128 v[228:231], v159 offset:23552
	global_load_lds_dwordx4 v134, s[54:55]
	s_add_i32 m0, s67, 0x2000
	s_add_u32 s68, s54, 0x40000
	s_addc_u32 s69, s55, 0
	s_add_i32 s67, s70, s58
	global_load_lds_dwordx4 v130, s[54:55]
	s_mov_b32 m0, s67
	s_nop 0
	global_load_lds_dwordx4 v134, s[68:69]
	s_add_i32 m0, s67, 0x2000
	s_nop 0
	global_load_lds_dwordx4 v130, s[68:69]
	s_mov_b32 m0, s59
	s_nop 0
	global_load_lds_dwordx4 v136, s[56:57]
	s_mov_b32 m0, s60
	s_nop 0
	global_load_lds_dwordx4 v132, s[56:57]
	s_waitcnt vmcnt(8)
	s_waitcnt lgkmcnt(0)
	s_barrier
	v_mfma_f32_16x16x32_bf16 v[62:65], v[142:145], v[180:183], 0
	v_mfma_f32_16x16x32_bf16 v[58:61], v[150:153], v[180:183], 0
	v_mfma_f32_16x16x32_bf16 v[46:49], v[142:145], v[208:211], 0
	v_mfma_f32_16x16x32_bf16 v[42:45], v[150:153], v[208:211], 0
	v_mfma_f32_16x16x32_bf16 v[30:33], v[142:145], v[216:219], 0
	v_mfma_f32_16x16x32_bf16 v[26:29], v[150:153], v[216:219], 0
	v_mfma_f32_16x16x32_bf16 v[14:17], v[142:145], v[224:227], 0
	v_mfma_f32_16x16x32_bf16 v[10:13], v[150:153], v[224:227], 0
	v_mfma_f32_16x16x32_bf16 v[62:65], v[146:149], v[204:207], v[62:65]
	v_mfma_f32_16x16x32_bf16 v[58:61], v[160:163], v[204:207], v[58:61]
	v_mfma_f32_16x16x32_bf16 v[46:49], v[146:149], v[212:215], v[46:49]
	v_mfma_f32_16x16x32_bf16 v[42:45], v[160:163], v[212:215], v[42:45]
	v_mfma_f32_16x16x32_bf16 v[30:33], v[146:149], v[220:223], v[30:33]
	v_mfma_f32_16x16x32_bf16 v[26:29], v[160:163], v[220:223], v[26:29]
	v_mfma_f32_16x16x32_bf16 v[14:17], v[146:149], v[228:231], v[14:17]
	v_mfma_f32_16x16x32_bf16 v[10:13], v[160:163], v[228:231], v[10:13]
	v_mfma_f32_16x16x32_bf16 v[54:57], v[164:167], v[180:183], 0
	v_mfma_f32_16x16x32_bf16 v[50:53], v[172:175], v[180:183], 0
	v_mfma_f32_16x16x32_bf16 v[38:41], v[164:167], v[208:211], 0
	v_mfma_f32_16x16x32_bf16 v[34:37], v[172:175], v[208:211], 0
	v_mfma_f32_16x16x32_bf16 v[22:25], v[164:167], v[216:219], 0
	v_mfma_f32_16x16x32_bf16 v[18:21], v[172:175], v[216:219], 0
	v_mfma_f32_16x16x32_bf16 v[6:9], v[164:167], v[224:227], 0
	v_mfma_f32_16x16x32_bf16 v[2:5], v[172:175], v[224:227], 0
	v_mfma_f32_16x16x32_bf16 v[54:57], v[168:171], v[204:207], v[54:57]
	v_mfma_f32_16x16x32_bf16 v[50:53], v[176:179], v[204:207], v[50:53]
	v_mfma_f32_16x16x32_bf16 v[38:41], v[168:171], v[212:215], v[38:41]
	v_mfma_f32_16x16x32_bf16 v[34:37], v[176:179], v[212:215], v[34:37]
	v_mfma_f32_16x16x32_bf16 v[22:25], v[168:171], v[220:223], v[22:25]
	v_mfma_f32_16x16x32_bf16 v[18:21], v[176:179], v[220:223], v[18:21]
	v_mfma_f32_16x16x32_bf16 v[6:9], v[168:171], v[228:231], v[6:9]
	v_mfma_f32_16x16x32_bf16 v[2:5], v[176:179], v[228:231], v[2:5]
	s_barrier
	s_add_i32 s67, 0, 0x18000
	v_add_u32_e32 v0, s67, v158
	s_add_i32 s68, 0, 0x1c000
	ds_read_b128 v[142:145], v0
	ds_read_b128 v[146:149], v0 offset:1024
	ds_read_b128 v[150:153], v0 offset:2048
	ds_read_b128 v[160:163], v0 offset:3072
	v_add_u32_e32 v0, s68, v158
	ds_read_b128 v[164:167], v0
	ds_read_b128 v[168:171], v0 offset:1024
	ds_read_b128 v[172:175], v0 offset:2048
	ds_read_b128 v[176:179], v0 offset:3072
	s_add_u32 s56, s56, 0x40000
	s_addc_u32 s57, s57, 0
	s_mov_b32 m0, s61
	ds_read_b128 v[180:183], v159 offset:32768
	ds_read_b128 v[204:207], v159 offset:33792
	ds_read_b128 v[208:211], v159 offset:34816
	ds_read_b128 v[212:215], v159 offset:35840
	ds_read_b128 v[216:219], v159 offset:36864
	ds_read_b128 v[220:223], v159 offset:37888
	ds_read_b128 v[224:227], v159 offset:38912
	ds_read_b128 v[228:231], v159 offset:39936
	global_load_lds_dwordx4 v136, s[56:57]
	s_mov_b32 m0, s62
	s_nop 0
	global_load_lds_dwordx4 v132, s[56:57]
	s_waitcnt vmcnt(8)
	s_waitcnt lgkmcnt(0)
	s_barrier
	v_mfma_f32_16x16x32_bf16 v[126:129], v[142:145], v[180:183], v[126:129]
	v_mfma_f32_16x16x32_bf16 v[122:125], v[150:153], v[180:183], v[122:125]
	v_mfma_f32_16x16x32_bf16 v[110:113], v[142:145], v[208:211], v[110:113]
	v_mfma_f32_16x16x32_bf16 v[106:109], v[150:153], v[208:211], v[106:109]
	v_mfma_f32_16x16x32_bf16 v[94:97], v[142:145], v[216:219], v[94:97]
	v_mfma_f32_16x16x32_bf16 v[90:93], v[150:153], v[216:219], v[90:93]
	v_mfma_f32_16x16x32_bf16 v[78:81], v[142:145], v[224:227], v[78:81]
	v_mfma_f32_16x16x32_bf16 v[74:77], v[150:153], v[224:227], v[74:77]
	v_mfma_f32_16x16x32_bf16 v[126:129], v[146:149], v[204:207], v[126:129]
	v_mfma_f32_16x16x32_bf16 v[122:125], v[160:163], v[204:207], v[122:125]
	v_mfma_f32_16x16x32_bf16 v[110:113], v[146:149], v[212:215], v[110:113]
	v_mfma_f32_16x16x32_bf16 v[106:109], v[160:163], v[212:215], v[106:109]
	v_mfma_f32_16x16x32_bf16 v[94:97], v[146:149], v[220:223], v[94:97]
	v_mfma_f32_16x16x32_bf16 v[90:93], v[160:163], v[220:223], v[90:93]
	v_mfma_f32_16x16x32_bf16 v[78:81], v[146:149], v[228:231], v[78:81]
	v_mfma_f32_16x16x32_bf16 v[74:77], v[160:163], v[228:231], v[74:77]
	v_mfma_f32_16x16x32_bf16 v[118:121], v[164:167], v[180:183], v[118:121]
	v_mfma_f32_16x16x32_bf16 v[114:117], v[172:175], v[180:183], v[114:117]
	v_mfma_f32_16x16x32_bf16 v[102:105], v[164:167], v[208:211], v[102:105]
	v_mfma_f32_16x16x32_bf16 v[98:101], v[172:175], v[208:211], v[98:101]
	v_mfma_f32_16x16x32_bf16 v[86:89], v[164:167], v[216:219], v[86:89]
	v_mfma_f32_16x16x32_bf16 v[82:85], v[172:175], v[216:219], v[82:85]
	v_mfma_f32_16x16x32_bf16 v[70:73], v[164:167], v[224:227], v[70:73]
	v_mfma_f32_16x16x32_bf16 v[66:69], v[172:175], v[224:227], v[66:69]
	v_mfma_f32_16x16x32_bf16 v[118:121], v[168:171], v[204:207], v[118:121]
	v_mfma_f32_16x16x32_bf16 v[114:117], v[176:179], v[204:207], v[114:117]
	v_mfma_f32_16x16x32_bf16 v[102:105], v[168:171], v[212:215], v[102:105]
	v_mfma_f32_16x16x32_bf16 v[98:101], v[176:179], v[212:215], v[98:101]
	v_mfma_f32_16x16x32_bf16 v[86:89], v[168:171], v[220:223], v[86:89]
	v_mfma_f32_16x16x32_bf16 v[82:85], v[176:179], v[220:223], v[82:85]
	v_mfma_f32_16x16x32_bf16 v[70:73], v[168:171], v[228:231], v[70:73]
	v_mfma_f32_16x16x32_bf16 v[66:69], v[176:179], v[228:231], v[66:69]
	s_barrier
	s_add_i32 s69, s67, s58
	s_add_u32 s54, s54, 0x80
	s_addc_u32 s55, s55, 0
	s_mov_b32 m0, s69
	ds_read_b128 v[180:183], v159 offset:49152
	ds_read_b128 v[204:207], v159 offset:50176
	ds_read_b128 v[208:211], v159 offset:51200
	ds_read_b128 v[212:215], v159 offset:52224
	ds_read_b128 v[216:219], v159 offset:53248
	ds_read_b128 v[220:223], v159 offset:54272
	ds_read_b128 v[224:227], v159 offset:55296
	ds_read_b128 v[228:231], v159 offset:56320
	global_load_lds_dwordx4 v134, s[54:55]
	s_add_i32 m0, s69, 0x2000
	s_add_i32 s69, s68, s58
	global_load_lds_dwordx4 v130, s[54:55]
	s_add_u32 s54, s54, 0x40000
	s_addc_u32 s55, s55, 0
	s_mov_b32 m0, s69
	s_sub_u32 s56, s56, 0x3ff80
	global_load_lds_dwordx4 v134, s[54:55]
	s_subb_u32 s57, s57, 0
	s_add_i32 m0, s69, 0x2000
	s_nop 0
	global_load_lds_dwordx4 v130, s[54:55]
	s_mov_b32 m0, s5
	s_nop 0
	global_load_lds_dwordx4 v136, s[56:57]
	s_mov_b32 m0, s6
	s_nop 0
	global_load_lds_dwordx4 v132, s[56:57]
	s_waitcnt vmcnt(8)
	s_waitcnt lgkmcnt(0)
	s_barrier
	v_mfma_f32_16x16x32_bf16 v[62:65], v[142:145], v[180:183], v[62:65]
	v_mfma_f32_16x16x32_bf16 v[58:61], v[150:153], v[180:183], v[58:61]
	v_mfma_f32_16x16x32_bf16 v[46:49], v[142:145], v[208:211], v[46:49]
	v_mfma_f32_16x16x32_bf16 v[42:45], v[150:153], v[208:211], v[42:45]
	v_mfma_f32_16x16x32_bf16 v[30:33], v[142:145], v[216:219], v[30:33]
	v_mfma_f32_16x16x32_bf16 v[26:29], v[150:153], v[216:219], v[26:29]
	v_mfma_f32_16x16x32_bf16 v[14:17], v[142:145], v[224:227], v[14:17]
	v_mfma_f32_16x16x32_bf16 v[10:13], v[150:153], v[224:227], v[10:13]
	v_mfma_f32_16x16x32_bf16 v[62:65], v[146:149], v[204:207], v[62:65]
	v_mfma_f32_16x16x32_bf16 v[58:61], v[160:163], v[204:207], v[58:61]
	v_mfma_f32_16x16x32_bf16 v[46:49], v[146:149], v[212:215], v[46:49]
	v_mfma_f32_16x16x32_bf16 v[42:45], v[160:163], v[212:215], v[42:45]
	v_mfma_f32_16x16x32_bf16 v[30:33], v[146:149], v[220:223], v[30:33]
	v_mfma_f32_16x16x32_bf16 v[26:29], v[160:163], v[220:223], v[26:29]
	v_mfma_f32_16x16x32_bf16 v[14:17], v[146:149], v[228:231], v[14:17]
	v_mfma_f32_16x16x32_bf16 v[10:13], v[160:163], v[228:231], v[10:13]
	v_mfma_f32_16x16x32_bf16 v[54:57], v[164:167], v[180:183], v[54:57]
	v_mfma_f32_16x16x32_bf16 v[50:53], v[172:175], v[180:183], v[50:53]
	v_mfma_f32_16x16x32_bf16 v[38:41], v[164:167], v[208:211], v[38:41]
	v_mfma_f32_16x16x32_bf16 v[34:37], v[172:175], v[208:211], v[34:37]
	v_mfma_f32_16x16x32_bf16 v[22:25], v[164:167], v[216:219], v[22:25]
	v_mfma_f32_16x16x32_bf16 v[18:21], v[172:175], v[216:219], v[18:21]
	v_mfma_f32_16x16x32_bf16 v[6:9], v[164:167], v[224:227], v[6:9]
	v_mfma_f32_16x16x32_bf16 v[2:5], v[172:175], v[224:227], v[2:5]
	v_mfma_f32_16x16x32_bf16 v[54:57], v[168:171], v[204:207], v[54:57]
	v_mfma_f32_16x16x32_bf16 v[50:53], v[176:179], v[204:207], v[50:53]
	v_mfma_f32_16x16x32_bf16 v[38:41], v[168:171], v[212:215], v[38:41]
	v_mfma_f32_16x16x32_bf16 v[34:37], v[176:179], v[212:215], v[34:37]
	v_mfma_f32_16x16x32_bf16 v[22:25], v[168:171], v[220:223], v[22:25]
	v_mfma_f32_16x16x32_bf16 v[18:21], v[176:179], v[220:223], v[18:21]
	v_mfma_f32_16x16x32_bf16 v[6:9], v[168:171], v[228:231], v[6:9]
	v_mfma_f32_16x16x32_bf16 v[2:5], v[176:179], v[228:231], v[2:5]
	s_barrier
	s_add_i32 s66, s66, 2
	s_add_u32 s52, s52, 0x100
	s_addc_u32 s53, s53, 0
	s_add_u32 s64, s64, 0x100
	s_addc_u32 s65, s65, 0
	s_cmp_gt_u32 s66, 13
.LBB0_422:
	s_add_u32 s54, s52, 0xfffc0080
	s_addc_u32 s55, s53, -1
	s_add_i32 s67, 0, 0x10000
	s_cmp_eq_u32 s66, 12
	s_cselect_b32 s57, s19, s55
	s_cselect_b32 s56, s45, s54
	v_add_u32_e32 v0, s67, v158
	s_cselect_b32 s55, s41, s65
	s_cselect_b32 s54, s51, s64
	s_add_i32 s70, 0, 0x14000
	ds_read_b128 v[142:145], v0
	ds_read_b128 v[146:149], v0 offset:1024
	ds_read_b128 v[150:153], v0 offset:2048
	ds_read_b128 v[160:163], v0 offset:3072
	v_add_u32_e32 v0, s70, v158
	ds_read_b128 v[164:167], v0
	ds_read_b128 v[168:171], v0 offset:1024
	ds_read_b128 v[172:175], v0 offset:2048
	ds_read_b128 v[176:179], v0 offset:3072
	s_add_i32 m0, s59, 0xc000
	ds_read_b128 v[180:183], v159
	ds_read_b128 v[204:207], v159 offset:1024
	ds_read_b128 v[208:211], v159 offset:2048
	ds_read_b128 v[212:215], v159 offset:3072
	ds_read_b128 v[216:219], v159 offset:4096
	ds_read_b128 v[220:223], v159 offset:5120
	ds_read_b128 v[224:227], v159 offset:6144
	ds_read_b128 v[228:231], v159 offset:7168
	global_load_lds_dwordx4 v138, s[52:53]
	s_add_i32 m0, s59, 0xe000
	s_nop 0
	global_load_lds_dwordx4 v140, s[52:53]
	s_waitcnt vmcnt(8)
	s_waitcnt lgkmcnt(0)
	s_barrier
	v_mfma_f32_16x16x32_bf16 v[126:129], v[142:145], v[180:183], v[126:129]
	v_mfma_f32_16x16x32_bf16 v[122:125], v[150:153], v[180:183], v[122:125]
	v_mfma_f32_16x16x32_bf16 v[110:113], v[142:145], v[208:211], v[110:113]
	v_mfma_f32_16x16x32_bf16 v[106:109], v[150:153], v[208:211], v[106:109]
	v_mfma_f32_16x16x32_bf16 v[94:97], v[142:145], v[216:219], v[94:97]
	v_mfma_f32_16x16x32_bf16 v[90:93], v[150:153], v[216:219], v[90:93]
	v_mfma_f32_16x16x32_bf16 v[78:81], v[142:145], v[224:227], v[78:81]
	v_mfma_f32_16x16x32_bf16 v[74:77], v[150:153], v[224:227], v[74:77]
	v_mfma_f32_16x16x32_bf16 v[126:129], v[146:149], v[204:207], v[126:129]
	v_mfma_f32_16x16x32_bf16 v[122:125], v[160:163], v[204:207], v[122:125]
	v_mfma_f32_16x16x32_bf16 v[110:113], v[146:149], v[212:215], v[110:113]
	v_mfma_f32_16x16x32_bf16 v[106:109], v[160:163], v[212:215], v[106:109]
	v_mfma_f32_16x16x32_bf16 v[94:97], v[146:149], v[220:223], v[94:97]
	v_mfma_f32_16x16x32_bf16 v[90:93], v[160:163], v[220:223], v[90:93]
	v_mfma_f32_16x16x32_bf16 v[78:81], v[146:149], v[228:231], v[78:81]
	v_mfma_f32_16x16x32_bf16 v[74:77], v[160:163], v[228:231], v[74:77]
	v_mfma_f32_16x16x32_bf16 v[118:121], v[164:167], v[180:183], v[118:121]
	v_mfma_f32_16x16x32_bf16 v[114:117], v[172:175], v[180:183], v[114:117]
	v_mfma_f32_16x16x32_bf16 v[102:105], v[164:167], v[208:211], v[102:105]
	v_mfma_f32_16x16x32_bf16 v[98:101], v[172:175], v[208:211], v[98:101]
	v_mfma_f32_16x16x32_bf16 v[86:89], v[164:167], v[216:219], v[86:89]
	v_mfma_f32_16x16x32_bf16 v[82:85], v[172:175], v[216:219], v[82:85]
	v_mfma_f32_16x16x32_bf16 v[70:73], v[164:167], v[224:227], v[70:73]
	v_mfma_f32_16x16x32_bf16 v[66:69], v[172:175], v[224:227], v[66:69]
	v_mfma_f32_16x16x32_bf16 v[118:121], v[168:171], v[204:207], v[118:121]
	v_mfma_f32_16x16x32_bf16 v[114:117], v[176:179], v[204:207], v[114:117]
	v_mfma_f32_16x16x32_bf16 v[102:105], v[168:171], v[212:215], v[102:105]
	v_mfma_f32_16x16x32_bf16 v[98:101], v[176:179], v[212:215], v[98:101]
	v_mfma_f32_16x16x32_bf16 v[86:89], v[168:171], v[220:223], v[86:89]
	v_mfma_f32_16x16x32_bf16 v[82:85], v[176:179], v[220:223], v[82:85]
	v_mfma_f32_16x16x32_bf16 v[70:73], v[168:171], v[228:231], v[70:73]
	v_mfma_f32_16x16x32_bf16 v[66:69], v[176:179], v[228:231], v[66:69]
	s_barrier
	s_add_i32 s67, s67, s58
	s_mov_b32 m0, s67
	ds_read_b128 v[180:183], v159 offset:16384
	ds_read_b128 v[204:207], v159 offset:17408
	ds_read_b128 v[208:211], v159 offset:18432
	ds_read_b128 v[212:215], v159 offset:19456
	ds_read_b128 v[216:219], v159 offset:20480
	ds_read_b128 v[220:223], v159 offset:21504
	ds_read_b128 v[224:227], v159 offset:22528
	ds_read_b128 v[228:231], v159 offset:23552
	global_load_lds_dwordx4 v134, s[54:55]
	s_add_i32 m0, s67, 0x2000
	s_add_u32 s68, s54, 0x40000
	s_addc_u32 s69, s55, 0
	s_add_i32 s67, s70, s58
	global_load_lds_dwordx4 v130, s[54:55]
	s_mov_b32 m0, s67
	s_nop 0
	global_load_lds_dwordx4 v134, s[68:69]
	s_add_i32 m0, s67, 0x2000
	s_nop 0
	global_load_lds_dwordx4 v130, s[68:69]
	s_mov_b32 m0, s59
	s_nop 0
	global_load_lds_dwordx4 v136, s[56:57]
	s_mov_b32 m0, s60
	s_nop 0
	global_load_lds_dwordx4 v132, s[56:57]
	s_waitcnt vmcnt(8)
	s_waitcnt lgkmcnt(0)
	s_barrier
	v_mfma_f32_16x16x32_bf16 v[62:65], v[142:145], v[180:183], v[62:65]
	v_mfma_f32_16x16x32_bf16 v[58:61], v[150:153], v[180:183], v[58:61]
	v_mfma_f32_16x16x32_bf16 v[46:49], v[142:145], v[208:211], v[46:49]
	v_mfma_f32_16x16x32_bf16 v[42:45], v[150:153], v[208:211], v[42:45]
	v_mfma_f32_16x16x32_bf16 v[30:33], v[142:145], v[216:219], v[30:33]
	v_mfma_f32_16x16x32_bf16 v[26:29], v[150:153], v[216:219], v[26:29]
	v_mfma_f32_16x16x32_bf16 v[14:17], v[142:145], v[224:227], v[14:17]
	v_mfma_f32_16x16x32_bf16 v[10:13], v[150:153], v[224:227], v[10:13]
	v_mfma_f32_16x16x32_bf16 v[62:65], v[146:149], v[204:207], v[62:65]
	v_mfma_f32_16x16x32_bf16 v[58:61], v[160:163], v[204:207], v[58:61]
	v_mfma_f32_16x16x32_bf16 v[46:49], v[146:149], v[212:215], v[46:49]
	v_mfma_f32_16x16x32_bf16 v[42:45], v[160:163], v[212:215], v[42:45]
	v_mfma_f32_16x16x32_bf16 v[30:33], v[146:149], v[220:223], v[30:33]
	v_mfma_f32_16x16x32_bf16 v[26:29], v[160:163], v[220:223], v[26:29]
	v_mfma_f32_16x16x32_bf16 v[14:17], v[146:149], v[228:231], v[14:17]
	v_mfma_f32_16x16x32_bf16 v[10:13], v[160:163], v[228:231], v[10:13]
	v_mfma_f32_16x16x32_bf16 v[54:57], v[164:167], v[180:183], v[54:57]
	v_mfma_f32_16x16x32_bf16 v[50:53], v[172:175], v[180:183], v[50:53]
	v_mfma_f32_16x16x32_bf16 v[38:41], v[164:167], v[208:211], v[38:41]
	v_mfma_f32_16x16x32_bf16 v[34:37], v[172:175], v[208:211], v[34:37]
	v_mfma_f32_16x16x32_bf16 v[22:25], v[164:167], v[216:219], v[22:25]
	v_mfma_f32_16x16x32_bf16 v[18:21], v[172:175], v[216:219], v[18:21]
	v_mfma_f32_16x16x32_bf16 v[6:9], v[164:167], v[224:227], v[6:9]
	v_mfma_f32_16x16x32_bf16 v[2:5], v[172:175], v[224:227], v[2:5]
	v_mfma_f32_16x16x32_bf16 v[54:57], v[168:171], v[204:207], v[54:57]
	v_mfma_f32_16x16x32_bf16 v[50:53], v[176:179], v[204:207], v[50:53]
	v_mfma_f32_16x16x32_bf16 v[38:41], v[168:171], v[212:215], v[38:41]
	v_mfma_f32_16x16x32_bf16 v[34:37], v[176:179], v[212:215], v[34:37]
	v_mfma_f32_16x16x32_bf16 v[22:25], v[168:171], v[220:223], v[22:25]
	v_mfma_f32_16x16x32_bf16 v[18:21], v[176:179], v[220:223], v[18:21]
	v_mfma_f32_16x16x32_bf16 v[6:9], v[168:171], v[228:231], v[6:9]
	v_mfma_f32_16x16x32_bf16 v[2:5], v[176:179], v[228:231], v[2:5]
	s_barrier
	s_add_i32 s67, 0, 0x18000
	v_add_u32_e32 v0, s67, v158
	s_add_i32 s68, 0, 0x1c000
	ds_read_b128 v[142:145], v0
	ds_read_b128 v[146:149], v0 offset:1024
	ds_read_b128 v[150:153], v0 offset:2048
	ds_read_b128 v[160:163], v0 offset:3072
	v_add_u32_e32 v0, s68, v158
	ds_read_b128 v[164:167], v0
	ds_read_b128 v[168:171], v0 offset:1024
	ds_read_b128 v[172:175], v0 offset:2048
	ds_read_b128 v[176:179], v0 offset:3072
	s_add_u32 s56, s56, 0x40000
	s_addc_u32 s57, s57, 0
	s_mov_b32 m0, s61
	ds_read_b128 v[180:183], v159 offset:32768
	ds_read_b128 v[204:207], v159 offset:33792
	ds_read_b128 v[208:211], v159 offset:34816
	ds_read_b128 v[212:215], v159 offset:35840
	ds_read_b128 v[216:219], v159 offset:36864
	ds_read_b128 v[220:223], v159 offset:37888
	ds_read_b128 v[224:227], v159 offset:38912
	ds_read_b128 v[228:231], v159 offset:39936
	global_load_lds_dwordx4 v136, s[56:57]
	s_mov_b32 m0, s62
	s_nop 0
	global_load_lds_dwordx4 v132, s[56:57]
	s_waitcnt vmcnt(8)
	s_waitcnt lgkmcnt(0)
	s_barrier
	v_mfma_f32_16x16x32_bf16 v[126:129], v[142:145], v[180:183], v[126:129]
	v_mfma_f32_16x16x32_bf16 v[122:125], v[150:153], v[180:183], v[122:125]
	v_mfma_f32_16x16x32_bf16 v[110:113], v[142:145], v[208:211], v[110:113]
	v_mfma_f32_16x16x32_bf16 v[106:109], v[150:153], v[208:211], v[106:109]
	v_mfma_f32_16x16x32_bf16 v[94:97], v[142:145], v[216:219], v[94:97]
	v_mfma_f32_16x16x32_bf16 v[90:93], v[150:153], v[216:219], v[90:93]
	v_mfma_f32_16x16x32_bf16 v[78:81], v[142:145], v[224:227], v[78:81]
	v_mfma_f32_16x16x32_bf16 v[74:77], v[150:153], v[224:227], v[74:77]
	v_mfma_f32_16x16x32_bf16 v[126:129], v[146:149], v[204:207], v[126:129]
	v_mfma_f32_16x16x32_bf16 v[122:125], v[160:163], v[204:207], v[122:125]
	v_mfma_f32_16x16x32_bf16 v[110:113], v[146:149], v[212:215], v[110:113]
	v_mfma_f32_16x16x32_bf16 v[106:109], v[160:163], v[212:215], v[106:109]
	v_mfma_f32_16x16x32_bf16 v[94:97], v[146:149], v[220:223], v[94:97]
	v_mfma_f32_16x16x32_bf16 v[90:93], v[160:163], v[220:223], v[90:93]
	v_mfma_f32_16x16x32_bf16 v[78:81], v[146:149], v[228:231], v[78:81]
	v_mfma_f32_16x16x32_bf16 v[74:77], v[160:163], v[228:231], v[74:77]
	v_mfma_f32_16x16x32_bf16 v[118:121], v[164:167], v[180:183], v[118:121]
	v_mfma_f32_16x16x32_bf16 v[114:117], v[172:175], v[180:183], v[114:117]
	v_mfma_f32_16x16x32_bf16 v[102:105], v[164:167], v[208:211], v[102:105]
	v_mfma_f32_16x16x32_bf16 v[98:101], v[172:175], v[208:211], v[98:101]
	v_mfma_f32_16x16x32_bf16 v[86:89], v[164:167], v[216:219], v[86:89]
	v_mfma_f32_16x16x32_bf16 v[82:85], v[172:175], v[216:219], v[82:85]
	v_mfma_f32_16x16x32_bf16 v[70:73], v[164:167], v[224:227], v[70:73]
	v_mfma_f32_16x16x32_bf16 v[66:69], v[172:175], v[224:227], v[66:69]
	v_mfma_f32_16x16x32_bf16 v[118:121], v[168:171], v[204:207], v[118:121]
	v_mfma_f32_16x16x32_bf16 v[114:117], v[176:179], v[204:207], v[114:117]
	v_mfma_f32_16x16x32_bf16 v[102:105], v[168:171], v[212:215], v[102:105]
	v_mfma_f32_16x16x32_bf16 v[98:101], v[176:179], v[212:215], v[98:101]
	v_mfma_f32_16x16x32_bf16 v[86:89], v[168:171], v[220:223], v[86:89]
	v_mfma_f32_16x16x32_bf16 v[82:85], v[176:179], v[220:223], v[82:85]
	v_mfma_f32_16x16x32_bf16 v[70:73], v[168:171], v[228:231], v[70:73]
	v_mfma_f32_16x16x32_bf16 v[66:69], v[176:179], v[228:231], v[66:69]
	s_barrier
	s_add_i32 s69, s67, s58
	s_add_u32 s54, s54, 0x80
	s_addc_u32 s55, s55, 0
	s_mov_b32 m0, s69
	ds_read_b128 v[180:183], v159 offset:49152
	ds_read_b128 v[204:207], v159 offset:50176
	ds_read_b128 v[208:211], v159 offset:51200
	ds_read_b128 v[212:215], v159 offset:52224
	ds_read_b128 v[216:219], v159 offset:53248
	ds_read_b128 v[220:223], v159 offset:54272
	ds_read_b128 v[224:227], v159 offset:55296
	ds_read_b128 v[228:231], v159 offset:56320
	global_load_lds_dwordx4 v134, s[54:55]
	s_add_i32 m0, s69, 0x2000
	s_add_i32 s69, s68, s58
	global_load_lds_dwordx4 v130, s[54:55]
	s_add_u32 s54, s54, 0x40000
	s_addc_u32 s55, s55, 0
	s_mov_b32 m0, s69
	s_sub_u32 s56, s56, 0x3ff80
	global_load_lds_dwordx4 v134, s[54:55]
	s_subb_u32 s57, s57, 0
	s_add_i32 m0, s69, 0x2000
	s_nop 0
	global_load_lds_dwordx4 v130, s[54:55]
	s_mov_b32 m0, s5
	s_nop 0
	global_load_lds_dwordx4 v136, s[56:57]
	s_mov_b32 m0, s6
	s_nop 0
	global_load_lds_dwordx4 v132, s[56:57]
	s_waitcnt vmcnt(8)
	s_waitcnt lgkmcnt(0)
	s_barrier
	v_mfma_f32_16x16x32_bf16 v[62:65], v[142:145], v[180:183], v[62:65]
	v_mfma_f32_16x16x32_bf16 v[58:61], v[150:153], v[180:183], v[58:61]
	v_mfma_f32_16x16x32_bf16 v[46:49], v[142:145], v[208:211], v[46:49]
	v_mfma_f32_16x16x32_bf16 v[42:45], v[150:153], v[208:211], v[42:45]
	v_mfma_f32_16x16x32_bf16 v[30:33], v[142:145], v[216:219], v[30:33]
	v_mfma_f32_16x16x32_bf16 v[26:29], v[150:153], v[216:219], v[26:29]
	v_mfma_f32_16x16x32_bf16 v[14:17], v[142:145], v[224:227], v[14:17]
	v_mfma_f32_16x16x32_bf16 v[10:13], v[150:153], v[224:227], v[10:13]
	v_mfma_f32_16x16x32_bf16 v[62:65], v[146:149], v[204:207], v[62:65]
	v_mfma_f32_16x16x32_bf16 v[58:61], v[160:163], v[204:207], v[58:61]
	v_mfma_f32_16x16x32_bf16 v[46:49], v[146:149], v[212:215], v[46:49]
	v_mfma_f32_16x16x32_bf16 v[42:45], v[160:163], v[212:215], v[42:45]
	v_mfma_f32_16x16x32_bf16 v[30:33], v[146:149], v[220:223], v[30:33]
	v_mfma_f32_16x16x32_bf16 v[26:29], v[160:163], v[220:223], v[26:29]
	v_mfma_f32_16x16x32_bf16 v[14:17], v[146:149], v[228:231], v[14:17]
	v_mfma_f32_16x16x32_bf16 v[10:13], v[160:163], v[228:231], v[10:13]
	v_mfma_f32_16x16x32_bf16 v[54:57], v[164:167], v[180:183], v[54:57]
	v_mfma_f32_16x16x32_bf16 v[50:53], v[172:175], v[180:183], v[50:53]
	v_mfma_f32_16x16x32_bf16 v[38:41], v[164:167], v[208:211], v[38:41]
	v_mfma_f32_16x16x32_bf16 v[34:37], v[172:175], v[208:211], v[34:37]
	v_mfma_f32_16x16x32_bf16 v[22:25], v[164:167], v[216:219], v[22:25]
	v_mfma_f32_16x16x32_bf16 v[18:21], v[172:175], v[216:219], v[18:21]
	v_mfma_f32_16x16x32_bf16 v[6:9], v[164:167], v[224:227], v[6:9]
	v_mfma_f32_16x16x32_bf16 v[2:5], v[172:175], v[224:227], v[2:5]
	v_mfma_f32_16x16x32_bf16 v[54:57], v[168:171], v[204:207], v[54:57]
	v_mfma_f32_16x16x32_bf16 v[50:53], v[176:179], v[204:207], v[50:53]
	v_mfma_f32_16x16x32_bf16 v[38:41], v[168:171], v[212:215], v[38:41]
	v_mfma_f32_16x16x32_bf16 v[34:37], v[176:179], v[212:215], v[34:37]
	v_mfma_f32_16x16x32_bf16 v[22:25], v[168:171], v[220:223], v[22:25]
	v_mfma_f32_16x16x32_bf16 v[18:21], v[176:179], v[220:223], v[18:21]
	v_mfma_f32_16x16x32_bf16 v[6:9], v[168:171], v[228:231], v[6:9]
	v_mfma_f32_16x16x32_bf16 v[2:5], v[176:179], v[228:231], v[2:5]
	s_barrier
	s_add_i32 s66, s66, 2
	s_add_u32 s52, s52, 0x100
	s_addc_u32 s53, s53, 0
	s_add_u32 s64, s64, 0x100
	s_addc_u32 s65, s65, 0
	s_cmp_gt_u32 s66, 13
	s_cbranch_scc0 .LBB0_422
	s_and_b64 vcc, exec, s[38:39]
	s_cbranch_vccz .LBB0_425
	s_barrier

.Lrb3_skip:
	s_add_u32 s54, s52, 0xfffc0080
	s_addc_u32 s55, s53, -1
	s_add_i32 s61, 0, 0x10000
	s_cmp_eq_u32 s60, 12
	s_cselect_b32 s57, s19, s55
	s_cselect_b32 s56, s45, s54
	v_add_u32_e32 v0, s61, v160
	s_cselect_b32 s55, s41, s59
	s_cselect_b32 s54, s47, s58
	s_add_i32 s64, 0, 0x14000
	ds_read_b128 v[142:145], v0
	ds_read_b128 v[146:149], v0 offset:1024
	ds_read_b128 v[150:153], v0 offset:2048
	ds_read_b128 v[154:157], v0 offset:3072
	v_add_u32_e32 v0, s64, v160
	ds_read_b128 v[162:165], v0
	ds_read_b128 v[166:169], v0 offset:1024
	ds_read_b128 v[170:173], v0 offset:2048
	ds_read_b128 v[174:177], v0 offset:3072
	s_add_i32 m0, s71, 0xc000
	ds_read_b128 v[178:181], v161
	ds_read_b128 v[182:185], v161 offset:1024
	ds_read_b128 v[204:207], v161 offset:2048
	ds_read_b128 v[208:211], v161 offset:3072
	ds_read_b128 v[212:215], v161 offset:4096
	ds_read_b128 v[216:219], v161 offset:5120
	ds_read_b128 v[220:223], v161 offset:6144
	ds_read_b128 v[224:227], v161 offset:7168
	global_load_lds_dwordx4 v138, s[52:53]
	s_add_i32 m0, s71, 0xe000
	s_nop 0
	global_load_lds_dwordx4 v140, s[52:53]
	s_waitcnt vmcnt(8)
	s_waitcnt lgkmcnt(0)
	s_barrier
	v_mfma_f32_16x16x32_bf16 v[126:129], v[142:145], v[178:181], 0
	v_mfma_f32_16x16x32_bf16 v[122:125], v[150:153], v[178:181], 0
	v_mfma_f32_16x16x32_bf16 v[110:113], v[142:145], v[204:207], 0
	v_mfma_f32_16x16x32_bf16 v[106:109], v[150:153], v[204:207], 0
	v_mfma_f32_16x16x32_bf16 v[94:97], v[142:145], v[212:215], 0
	v_mfma_f32_16x16x32_bf16 v[90:93], v[150:153], v[212:215], 0
	v_mfma_f32_16x16x32_bf16 v[78:81], v[142:145], v[220:223], 0
	v_mfma_f32_16x16x32_bf16 v[74:77], v[150:153], v[220:223], 0
	v_mfma_f32_16x16x32_bf16 v[126:129], v[146:149], v[182:185], v[126:129]
	v_mfma_f32_16x16x32_bf16 v[122:125], v[154:157], v[182:185], v[122:125]
	v_mfma_f32_16x16x32_bf16 v[110:113], v[146:149], v[208:211], v[110:113]
	v_mfma_f32_16x16x32_bf16 v[106:109], v[154:157], v[208:211], v[106:109]
	v_mfma_f32_16x16x32_bf16 v[94:97], v[146:149], v[216:219], v[94:97]
	v_mfma_f32_16x16x32_bf16 v[90:93], v[154:157], v[216:219], v[90:93]
	v_mfma_f32_16x16x32_bf16 v[78:81], v[146:149], v[224:227], v[78:81]
	v_mfma_f32_16x16x32_bf16 v[74:77], v[154:157], v[224:227], v[74:77]
	v_mfma_f32_16x16x32_bf16 v[118:121], v[162:165], v[178:181], 0
	v_mfma_f32_16x16x32_bf16 v[114:117], v[170:173], v[178:181], 0
	v_mfma_f32_16x16x32_bf16 v[102:105], v[162:165], v[204:207], 0
	v_mfma_f32_16x16x32_bf16 v[98:101], v[170:173], v[204:207], 0
	v_mfma_f32_16x16x32_bf16 v[86:89], v[162:165], v[212:215], 0
	v_mfma_f32_16x16x32_bf16 v[82:85], v[170:173], v[212:215], 0
	v_mfma_f32_16x16x32_bf16 v[70:73], v[162:165], v[220:223], 0
	v_mfma_f32_16x16x32_bf16 v[66:69], v[170:173], v[220:223], 0
	v_mfma_f32_16x16x32_bf16 v[118:121], v[166:169], v[182:185], v[118:121]
	v_mfma_f32_16x16x32_bf16 v[114:117], v[174:177], v[182:185], v[114:117]
	v_mfma_f32_16x16x32_bf16 v[102:105], v[166:169], v[208:211], v[102:105]
	v_mfma_f32_16x16x32_bf16 v[98:101], v[174:177], v[208:211], v[98:101]
	v_mfma_f32_16x16x32_bf16 v[86:89], v[166:169], v[216:219], v[86:89]
	v_mfma_f32_16x16x32_bf16 v[82:85], v[174:177], v[216:219], v[82:85]
	v_mfma_f32_16x16x32_bf16 v[70:73], v[166:169], v[224:227], v[70:73]
	v_mfma_f32_16x16x32_bf16 v[66:69], v[174:177], v[224:227], v[66:69]
	s_barrier
	s_add_i32 s61, s61, s70
	s_mov_b32 m0, s61
	ds_read_b128 v[178:181], v161 offset:16384
	ds_read_b128 v[182:185], v161 offset:17408
	ds_read_b128 v[204:207], v161 offset:18432
	ds_read_b128 v[208:211], v161 offset:19456
	ds_read_b128 v[212:215], v161 offset:20480
	ds_read_b128 v[216:219], v161 offset:21504
	ds_read_b128 v[220:223], v161 offset:22528
	ds_read_b128 v[224:227], v161 offset:23552
	global_load_lds_dwordx4 v134, s[54:55]
	s_add_i32 m0, s61, 0x2000
	s_add_u32 s62, s54, 0x40000
	s_addc_u32 s63, s55, 0
	s_add_i32 s61, s64, s70
	global_load_lds_dwordx4 v130, s[54:55]
	s_mov_b32 m0, s61
	s_nop 0
	global_load_lds_dwordx4 v134, s[62:63]
	s_add_i32 m0, s61, 0x2000
	s_nop 0
	global_load_lds_dwordx4 v130, s[62:63]
	s_mov_b32 m0, s71
	s_nop 0
	global_load_lds_dwordx4 v136, s[56:57]
	s_mov_b32 m0, s72
	s_nop 0
	global_load_lds_dwordx4 v132, s[56:57]
	s_waitcnt vmcnt(8)
	s_waitcnt lgkmcnt(0)
	s_barrier
	v_mfma_f32_16x16x32_bf16 v[62:65], v[142:145], v[178:181], 0
	v_mfma_f32_16x16x32_bf16 v[58:61], v[150:153], v[178:181], 0
	v_mfma_f32_16x16x32_bf16 v[46:49], v[142:145], v[204:207], 0
	v_mfma_f32_16x16x32_bf16 v[42:45], v[150:153], v[204:207], 0
	v_mfma_f32_16x16x32_bf16 v[30:33], v[142:145], v[212:215], 0
	v_mfma_f32_16x16x32_bf16 v[26:29], v[150:153], v[212:215], 0
	v_mfma_f32_16x16x32_bf16 v[14:17], v[142:145], v[220:223], 0
	v_mfma_f32_16x16x32_bf16 v[10:13], v[150:153], v[220:223], 0
	v_mfma_f32_16x16x32_bf16 v[62:65], v[146:149], v[182:185], v[62:65]
	v_mfma_f32_16x16x32_bf16 v[58:61], v[154:157], v[182:185], v[58:61]
	v_mfma_f32_16x16x32_bf16 v[46:49], v[146:149], v[208:211], v[46:49]
	v_mfma_f32_16x16x32_bf16 v[42:45], v[154:157], v[208:211], v[42:45]
	v_mfma_f32_16x16x32_bf16 v[30:33], v[146:149], v[216:219], v[30:33]
	v_mfma_f32_16x16x32_bf16 v[26:29], v[154:157], v[216:219], v[26:29]
	v_mfma_f32_16x16x32_bf16 v[14:17], v[146:149], v[224:227], v[14:17]
	v_mfma_f32_16x16x32_bf16 v[10:13], v[154:157], v[224:227], v[10:13]
	v_mfma_f32_16x16x32_bf16 v[54:57], v[162:165], v[178:181], 0
	v_mfma_f32_16x16x32_bf16 v[50:53], v[170:173], v[178:181], 0
	v_mfma_f32_16x16x32_bf16 v[38:41], v[162:165], v[204:207], 0
	v_mfma_f32_16x16x32_bf16 v[34:37], v[170:173], v[204:207], 0
	v_mfma_f32_16x16x32_bf16 v[22:25], v[162:165], v[212:215], 0
	v_mfma_f32_16x16x32_bf16 v[18:21], v[170:173], v[212:215], 0
	v_mfma_f32_16x16x32_bf16 v[6:9], v[162:165], v[220:223], 0
	v_mfma_f32_16x16x32_bf16 v[2:5], v[170:173], v[220:223], 0
	v_mfma_f32_16x16x32_bf16 v[54:57], v[166:169], v[182:185], v[54:57]
	v_mfma_f32_16x16x32_bf16 v[50:53], v[174:177], v[182:185], v[50:53]
	v_mfma_f32_16x16x32_bf16 v[38:41], v[166:169], v[208:211], v[38:41]
	v_mfma_f32_16x16x32_bf16 v[34:37], v[174:177], v[208:211], v[34:37]
	v_mfma_f32_16x16x32_bf16 v[22:25], v[166:169], v[216:219], v[22:25]
	v_mfma_f32_16x16x32_bf16 v[18:21], v[174:177], v[216:219], v[18:21]
	v_mfma_f32_16x16x32_bf16 v[6:9], v[166:169], v[224:227], v[6:9]
	v_mfma_f32_16x16x32_bf16 v[2:5], v[174:177], v[224:227], v[2:5]
	s_barrier
	s_add_i32 s61, 0, 0x18000
	v_add_u32_e32 v0, s61, v160
	s_add_i32 s62, 0, 0x1c000
	ds_read_b128 v[142:145], v0
	ds_read_b128 v[146:149], v0 offset:1024
	ds_read_b128 v[150:153], v0 offset:2048
	ds_read_b128 v[154:157], v0 offset:3072
	v_add_u32_e32 v0, s62, v160
	ds_read_b128 v[162:165], v0
	ds_read_b128 v[166:169], v0 offset:1024
	ds_read_b128 v[170:173], v0 offset:2048
	ds_read_b128 v[174:177], v0 offset:3072
	s_add_u32 s56, s56, 0x40000
	s_addc_u32 s57, s57, 0
	s_mov_b32 m0, s73
	ds_read_b128 v[178:181], v161 offset:32768
	ds_read_b128 v[182:185], v161 offset:33792
	ds_read_b128 v[204:207], v161 offset:34816
	ds_read_b128 v[208:211], v161 offset:35840
	ds_read_b128 v[212:215], v161 offset:36864
	ds_read_b128 v[216:219], v161 offset:37888
	ds_read_b128 v[220:223], v161 offset:38912
	ds_read_b128 v[224:227], v161 offset:39936
	global_load_lds_dwordx4 v136, s[56:57]
	s_mov_b32 m0, s74
	s_nop 0
	global_load_lds_dwordx4 v132, s[56:57]
	s_waitcnt vmcnt(8)
	s_waitcnt lgkmcnt(0)
	s_barrier
	v_mfma_f32_16x16x32_bf16 v[126:129], v[142:145], v[178:181], v[126:129]
	v_mfma_f32_16x16x32_bf16 v[122:125], v[150:153], v[178:181], v[122:125]
	v_mfma_f32_16x16x32_bf16 v[110:113], v[142:145], v[204:207], v[110:113]
	v_mfma_f32_16x16x32_bf16 v[106:109], v[150:153], v[204:207], v[106:109]
	v_mfma_f32_16x16x32_bf16 v[94:97], v[142:145], v[212:215], v[94:97]
	v_mfma_f32_16x16x32_bf16 v[90:93], v[150:153], v[212:215], v[90:93]
	v_mfma_f32_16x16x32_bf16 v[78:81], v[142:145], v[220:223], v[78:81]
	v_mfma_f32_16x16x32_bf16 v[74:77], v[150:153], v[220:223], v[74:77]
	v_mfma_f32_16x16x32_bf16 v[126:129], v[146:149], v[182:185], v[126:129]
	v_mfma_f32_16x16x32_bf16 v[122:125], v[154:157], v[182:185], v[122:125]
	v_mfma_f32_16x16x32_bf16 v[110:113], v[146:149], v[208:211], v[110:113]
	v_mfma_f32_16x16x32_bf16 v[106:109], v[154:157], v[208:211], v[106:109]
	v_mfma_f32_16x16x32_bf16 v[94:97], v[146:149], v[216:219], v[94:97]
	v_mfma_f32_16x16x32_bf16 v[90:93], v[154:157], v[216:219], v[90:93]
	v_mfma_f32_16x16x32_bf16 v[78:81], v[146:149], v[224:227], v[78:81]
	v_mfma_f32_16x16x32_bf16 v[74:77], v[154:157], v[224:227], v[74:77]
	v_mfma_f32_16x16x32_bf16 v[118:121], v[162:165], v[178:181], v[118:121]
	v_mfma_f32_16x16x32_bf16 v[114:117], v[170:173], v[178:181], v[114:117]
	v_mfma_f32_16x16x32_bf16 v[102:105], v[162:165], v[204:207], v[102:105]
	v_mfma_f32_16x16x32_bf16 v[98:101], v[170:173], v[204:207], v[98:101]
	v_mfma_f32_16x16x32_bf16 v[86:89], v[162:165], v[212:215], v[86:89]
	v_mfma_f32_16x16x32_bf16 v[82:85], v[170:173], v[212:215], v[82:85]
	v_mfma_f32_16x16x32_bf16 v[70:73], v[162:165], v[220:223], v[70:73]
	v_mfma_f32_16x16x32_bf16 v[66:69], v[170:173], v[220:223], v[66:69]
	v_mfma_f32_16x16x32_bf16 v[118:121], v[166:169], v[182:185], v[118:121]
	v_mfma_f32_16x16x32_bf16 v[114:117], v[174:177], v[182:185], v[114:117]
	v_mfma_f32_16x16x32_bf16 v[102:105], v[166:169], v[208:211], v[102:105]
	v_mfma_f32_16x16x32_bf16 v[98:101], v[174:177], v[208:211], v[98:101]
	v_mfma_f32_16x16x32_bf16 v[86:89], v[166:169], v[216:219], v[86:89]
	v_mfma_f32_16x16x32_bf16 v[82:85], v[174:177], v[216:219], v[82:85]
	v_mfma_f32_16x16x32_bf16 v[70:73], v[166:169], v[224:227], v[70:73]
	v_mfma_f32_16x16x32_bf16 v[66:69], v[174:177], v[224:227], v[66:69]
	s_barrier
	s_add_i32 s63, s61, s70
	s_add_u32 s54, s54, 0x80
	s_addc_u32 s55, s55, 0
	s_mov_b32 m0, s63
	ds_read_b128 v[178:181], v161 offset:49152
	ds_read_b128 v[182:185], v161 offset:50176
	ds_read_b128 v[204:207], v161 offset:51200
	ds_read_b128 v[208:211], v161 offset:52224
	ds_read_b128 v[212:215], v161 offset:53248
	ds_read_b128 v[216:219], v161 offset:54272
	ds_read_b128 v[220:223], v161 offset:55296
	ds_read_b128 v[224:227], v161 offset:56320
	global_load_lds_dwordx4 v134, s[54:55]
	s_add_i32 m0, s63, 0x2000
	s_add_i32 s63, s62, s70
	global_load_lds_dwordx4 v130, s[54:55]
	s_add_u32 s54, s54, 0x40000
	s_addc_u32 s55, s55, 0
	s_mov_b32 m0, s63
	s_sub_u32 s56, s56, 0x3ff80
	global_load_lds_dwordx4 v134, s[54:55]
	s_subb_u32 s57, s57, 0
	s_add_i32 m0, s63, 0x2000
	s_nop 0
	global_load_lds_dwordx4 v130, s[54:55]
	s_mov_b32 m0, s86
	s_nop 0
	global_load_lds_dwordx4 v136, s[56:57]
	s_mov_b32 m0, s87
	s_nop 0
	global_load_lds_dwordx4 v132, s[56:57]
	s_waitcnt vmcnt(8)
	s_waitcnt lgkmcnt(0)
	s_barrier
	v_mfma_f32_16x16x32_bf16 v[62:65], v[142:145], v[178:181], v[62:65]
	v_mfma_f32_16x16x32_bf16 v[58:61], v[150:153], v[178:181], v[58:61]
	v_mfma_f32_16x16x32_bf16 v[46:49], v[142:145], v[204:207], v[46:49]
	v_mfma_f32_16x16x32_bf16 v[42:45], v[150:153], v[204:207], v[42:45]
	v_mfma_f32_16x16x32_bf16 v[30:33], v[142:145], v[212:215], v[30:33]
	v_mfma_f32_16x16x32_bf16 v[26:29], v[150:153], v[212:215], v[26:29]
	v_mfma_f32_16x16x32_bf16 v[14:17], v[142:145], v[220:223], v[14:17]
	v_mfma_f32_16x16x32_bf16 v[10:13], v[150:153], v[220:223], v[10:13]
	v_mfma_f32_16x16x32_bf16 v[62:65], v[146:149], v[182:185], v[62:65]
	v_mfma_f32_16x16x32_bf16 v[58:61], v[154:157], v[182:185], v[58:61]
	v_mfma_f32_16x16x32_bf16 v[46:49], v[146:149], v[208:211], v[46:49]
	v_mfma_f32_16x16x32_bf16 v[42:45], v[154:157], v[208:211], v[42:45]
	v_mfma_f32_16x16x32_bf16 v[30:33], v[146:149], v[216:219], v[30:33]
	v_mfma_f32_16x16x32_bf16 v[26:29], v[154:157], v[216:219], v[26:29]
	v_mfma_f32_16x16x32_bf16 v[14:17], v[146:149], v[224:227], v[14:17]
	v_mfma_f32_16x16x32_bf16 v[10:13], v[154:157], v[224:227], v[10:13]
	v_mfma_f32_16x16x32_bf16 v[54:57], v[162:165], v[178:181], v[54:57]
	v_mfma_f32_16x16x32_bf16 v[50:53], v[170:173], v[178:181], v[50:53]
	v_mfma_f32_16x16x32_bf16 v[38:41], v[162:165], v[204:207], v[38:41]
	v_mfma_f32_16x16x32_bf16 v[34:37], v[170:173], v[204:207], v[34:37]
	v_mfma_f32_16x16x32_bf16 v[22:25], v[162:165], v[212:215], v[22:25]
	v_mfma_f32_16x16x32_bf16 v[18:21], v[170:173], v[212:215], v[18:21]
	v_mfma_f32_16x16x32_bf16 v[6:9], v[162:165], v[220:223], v[6:9]
	v_mfma_f32_16x16x32_bf16 v[2:5], v[170:173], v[220:223], v[2:5]
	v_mfma_f32_16x16x32_bf16 v[54:57], v[166:169], v[182:185], v[54:57]
	v_mfma_f32_16x16x32_bf16 v[50:53], v[174:177], v[182:185], v[50:53]
	v_mfma_f32_16x16x32_bf16 v[38:41], v[166:169], v[208:211], v[38:41]
	v_mfma_f32_16x16x32_bf16 v[34:37], v[174:177], v[208:211], v[34:37]
	v_mfma_f32_16x16x32_bf16 v[22:25], v[166:169], v[216:219], v[22:25]
	v_mfma_f32_16x16x32_bf16 v[18:21], v[174:177], v[216:219], v[18:21]
	v_mfma_f32_16x16x32_bf16 v[6:9], v[166:169], v[224:227], v[6:9]
	v_mfma_f32_16x16x32_bf16 v[2:5], v[174:177], v[224:227], v[2:5]
	s_barrier
	s_add_i32 s60, s60, 2
	s_add_u32 s52, s52, 0x100
	s_addc_u32 s53, s53, 0
	s_add_u32 s58, s58, 0x100
	s_addc_u32 s59, s59, 0
	s_cmp_gt_u32 s60, 13
.LBB0_479:
	s_add_u32 s54, s52, 0xfffc0080
	s_addc_u32 s55, s53, -1
	s_add_i32 s61, 0, 0x10000
	s_cmp_eq_u32 s60, 12
	s_cselect_b32 s57, s19, s55
	s_cselect_b32 s56, s45, s54
	v_add_u32_e32 v0, s61, v160
	s_cselect_b32 s55, s41, s59
	s_cselect_b32 s54, s47, s58
	s_add_i32 s64, 0, 0x14000
	ds_read_b128 v[142:145], v0
	ds_read_b128 v[146:149], v0 offset:1024
	ds_read_b128 v[150:153], v0 offset:2048
	ds_read_b128 v[154:157], v0 offset:3072
	v_add_u32_e32 v0, s64, v160
	ds_read_b128 v[162:165], v0
	ds_read_b128 v[166:169], v0 offset:1024
	ds_read_b128 v[170:173], v0 offset:2048
	ds_read_b128 v[174:177], v0 offset:3072
	s_add_i32 m0, s71, 0xc000
	ds_read_b128 v[178:181], v161
	ds_read_b128 v[182:185], v161 offset:1024
	ds_read_b128 v[204:207], v161 offset:2048
	ds_read_b128 v[208:211], v161 offset:3072
	ds_read_b128 v[212:215], v161 offset:4096
	ds_read_b128 v[216:219], v161 offset:5120
	ds_read_b128 v[220:223], v161 offset:6144
	ds_read_b128 v[224:227], v161 offset:7168
	global_load_lds_dwordx4 v138, s[52:53]
	s_add_i32 m0, s71, 0xe000
	s_nop 0
	global_load_lds_dwordx4 v140, s[52:53]
	s_waitcnt vmcnt(8)
	s_waitcnt lgkmcnt(0)
	s_barrier
	v_mfma_f32_16x16x32_bf16 v[126:129], v[142:145], v[178:181], v[126:129]
	v_mfma_f32_16x16x32_bf16 v[122:125], v[150:153], v[178:181], v[122:125]
	v_mfma_f32_16x16x32_bf16 v[110:113], v[142:145], v[204:207], v[110:113]
	v_mfma_f32_16x16x32_bf16 v[106:109], v[150:153], v[204:207], v[106:109]
	v_mfma_f32_16x16x32_bf16 v[94:97], v[142:145], v[212:215], v[94:97]
	v_mfma_f32_16x16x32_bf16 v[90:93], v[150:153], v[212:215], v[90:93]
	v_mfma_f32_16x16x32_bf16 v[78:81], v[142:145], v[220:223], v[78:81]
	v_mfma_f32_16x16x32_bf16 v[74:77], v[150:153], v[220:223], v[74:77]
	v_mfma_f32_16x16x32_bf16 v[126:129], v[146:149], v[182:185], v[126:129]
	v_mfma_f32_16x16x32_bf16 v[122:125], v[154:157], v[182:185], v[122:125]
	v_mfma_f32_16x16x32_bf16 v[110:113], v[146:149], v[208:211], v[110:113]
	v_mfma_f32_16x16x32_bf16 v[106:109], v[154:157], v[208:211], v[106:109]
	v_mfma_f32_16x16x32_bf16 v[94:97], v[146:149], v[216:219], v[94:97]
	v_mfma_f32_16x16x32_bf16 v[90:93], v[154:157], v[216:219], v[90:93]
	v_mfma_f32_16x16x32_bf16 v[78:81], v[146:149], v[224:227], v[78:81]
	v_mfma_f32_16x16x32_bf16 v[74:77], v[154:157], v[224:227], v[74:77]
	v_mfma_f32_16x16x32_bf16 v[118:121], v[162:165], v[178:181], v[118:121]
	v_mfma_f32_16x16x32_bf16 v[114:117], v[170:173], v[178:181], v[114:117]
	v_mfma_f32_16x16x32_bf16 v[102:105], v[162:165], v[204:207], v[102:105]
	v_mfma_f32_16x16x32_bf16 v[98:101], v[170:173], v[204:207], v[98:101]
	v_mfma_f32_16x16x32_bf16 v[86:89], v[162:165], v[212:215], v[86:89]
	v_mfma_f32_16x16x32_bf16 v[82:85], v[170:173], v[212:215], v[82:85]
	v_mfma_f32_16x16x32_bf16 v[70:73], v[162:165], v[220:223], v[70:73]
	v_mfma_f32_16x16x32_bf16 v[66:69], v[170:173], v[220:223], v[66:69]
	v_mfma_f32_16x16x32_bf16 v[118:121], v[166:169], v[182:185], v[118:121]
	v_mfma_f32_16x16x32_bf16 v[114:117], v[174:177], v[182:185], v[114:117]
	v_mfma_f32_16x16x32_bf16 v[102:105], v[166:169], v[208:211], v[102:105]
	v_mfma_f32_16x16x32_bf16 v[98:101], v[174:177], v[208:211], v[98:101]
	v_mfma_f32_16x16x32_bf16 v[86:89], v[166:169], v[216:219], v[86:89]
	v_mfma_f32_16x16x32_bf16 v[82:85], v[174:177], v[216:219], v[82:85]
	v_mfma_f32_16x16x32_bf16 v[70:73], v[166:169], v[224:227], v[70:73]
	v_mfma_f32_16x16x32_bf16 v[66:69], v[174:177], v[224:227], v[66:69]
	s_barrier
	s_add_i32 s61, s61, s70
	s_mov_b32 m0, s61
	ds_read_b128 v[178:181], v161 offset:16384
	ds_read_b128 v[182:185], v161 offset:17408
	ds_read_b128 v[204:207], v161 offset:18432
	ds_read_b128 v[208:211], v161 offset:19456
	ds_read_b128 v[212:215], v161 offset:20480
	ds_read_b128 v[216:219], v161 offset:21504
	ds_read_b128 v[220:223], v161 offset:22528
	ds_read_b128 v[224:227], v161 offset:23552
	global_load_lds_dwordx4 v134, s[54:55]
	s_add_i32 m0, s61, 0x2000
	s_add_u32 s62, s54, 0x40000
	s_addc_u32 s63, s55, 0
	s_add_i32 s61, s64, s70
	global_load_lds_dwordx4 v130, s[54:55]
	s_mov_b32 m0, s61
	s_nop 0
	global_load_lds_dwordx4 v134, s[62:63]
	s_add_i32 m0, s61, 0x2000
	s_nop 0
	global_load_lds_dwordx4 v130, s[62:63]
	s_mov_b32 m0, s71
	s_nop 0
	global_load_lds_dwordx4 v136, s[56:57]
	s_mov_b32 m0, s72
	s_nop 0
	global_load_lds_dwordx4 v132, s[56:57]
	s_waitcnt vmcnt(8)
	s_waitcnt lgkmcnt(0)
	s_barrier
	v_mfma_f32_16x16x32_bf16 v[62:65], v[142:145], v[178:181], v[62:65]
	v_mfma_f32_16x16x32_bf16 v[58:61], v[150:153], v[178:181], v[58:61]
	v_mfma_f32_16x16x32_bf16 v[46:49], v[142:145], v[204:207], v[46:49]
	v_mfma_f32_16x16x32_bf16 v[42:45], v[150:153], v[204:207], v[42:45]
	v_mfma_f32_16x16x32_bf16 v[30:33], v[142:145], v[212:215], v[30:33]
	v_mfma_f32_16x16x32_bf16 v[26:29], v[150:153], v[212:215], v[26:29]
	v_mfma_f32_16x16x32_bf16 v[14:17], v[142:145], v[220:223], v[14:17]
	v_mfma_f32_16x16x32_bf16 v[10:13], v[150:153], v[220:223], v[10:13]
	v_mfma_f32_16x16x32_bf16 v[62:65], v[146:149], v[182:185], v[62:65]
	v_mfma_f32_16x16x32_bf16 v[58:61], v[154:157], v[182:185], v[58:61]
	v_mfma_f32_16x16x32_bf16 v[46:49], v[146:149], v[208:211], v[46:49]
	v_mfma_f32_16x16x32_bf16 v[42:45], v[154:157], v[208:211], v[42:45]
	v_mfma_f32_16x16x32_bf16 v[30:33], v[146:149], v[216:219], v[30:33]
	v_mfma_f32_16x16x32_bf16 v[26:29], v[154:157], v[216:219], v[26:29]
	v_mfma_f32_16x16x32_bf16 v[14:17], v[146:149], v[224:227], v[14:17]
	v_mfma_f32_16x16x32_bf16 v[10:13], v[154:157], v[224:227], v[10:13]
	v_mfma_f32_16x16x32_bf16 v[54:57], v[162:165], v[178:181], v[54:57]
	v_mfma_f32_16x16x32_bf16 v[50:53], v[170:173], v[178:181], v[50:53]
	v_mfma_f32_16x16x32_bf16 v[38:41], v[162:165], v[204:207], v[38:41]
	v_mfma_f32_16x16x32_bf16 v[34:37], v[170:173], v[204:207], v[34:37]
	v_mfma_f32_16x16x32_bf16 v[22:25], v[162:165], v[212:215], v[22:25]
	v_mfma_f32_16x16x32_bf16 v[18:21], v[170:173], v[212:215], v[18:21]
	v_mfma_f32_16x16x32_bf16 v[6:9], v[162:165], v[220:223], v[6:9]
	v_mfma_f32_16x16x32_bf16 v[2:5], v[170:173], v[220:223], v[2:5]
	v_mfma_f32_16x16x32_bf16 v[54:57], v[166:169], v[182:185], v[54:57]
	v_mfma_f32_16x16x32_bf16 v[50:53], v[174:177], v[182:185], v[50:53]
	v_mfma_f32_16x16x32_bf16 v[38:41], v[166:169], v[208:211], v[38:41]
	v_mfma_f32_16x16x32_bf16 v[34:37], v[174:177], v[208:211], v[34:37]
	v_mfma_f32_16x16x32_bf16 v[22:25], v[166:169], v[216:219], v[22:25]
	v_mfma_f32_16x16x32_bf16 v[18:21], v[174:177], v[216:219], v[18:21]
	v_mfma_f32_16x16x32_bf16 v[6:9], v[166:169], v[224:227], v[6:9]
	v_mfma_f32_16x16x32_bf16 v[2:5], v[174:177], v[224:227], v[2:5]
	s_barrier
	s_add_i32 s61, 0, 0x18000
	v_add_u32_e32 v0, s61, v160
	s_add_i32 s62, 0, 0x1c000
	ds_read_b128 v[142:145], v0
	ds_read_b128 v[146:149], v0 offset:1024
	ds_read_b128 v[150:153], v0 offset:2048
	ds_read_b128 v[154:157], v0 offset:3072
	v_add_u32_e32 v0, s62, v160
	ds_read_b128 v[162:165], v0
	ds_read_b128 v[166:169], v0 offset:1024
	ds_read_b128 v[170:173], v0 offset:2048
	ds_read_b128 v[174:177], v0 offset:3072
	s_add_u32 s56, s56, 0x40000
	s_addc_u32 s57, s57, 0
	s_mov_b32 m0, s73
	ds_read_b128 v[178:181], v161 offset:32768
	ds_read_b128 v[182:185], v161 offset:33792
	ds_read_b128 v[204:207], v161 offset:34816
	ds_read_b128 v[208:211], v161 offset:35840
	ds_read_b128 v[212:215], v161 offset:36864
	ds_read_b128 v[216:219], v161 offset:37888
	ds_read_b128 v[220:223], v161 offset:38912
	ds_read_b128 v[224:227], v161 offset:39936
	global_load_lds_dwordx4 v136, s[56:57]
	s_mov_b32 m0, s74
	s_nop 0
	global_load_lds_dwordx4 v132, s[56:57]
	s_waitcnt vmcnt(8)
	s_waitcnt lgkmcnt(0)
	s_barrier
	v_mfma_f32_16x16x32_bf16 v[126:129], v[142:145], v[178:181], v[126:129]
	v_mfma_f32_16x16x32_bf16 v[122:125], v[150:153], v[178:181], v[122:125]
	v_mfma_f32_16x16x32_bf16 v[110:113], v[142:145], v[204:207], v[110:113]
	v_mfma_f32_16x16x32_bf16 v[106:109], v[150:153], v[204:207], v[106:109]
	v_mfma_f32_16x16x32_bf16 v[94:97], v[142:145], v[212:215], v[94:97]
	v_mfma_f32_16x16x32_bf16 v[90:93], v[150:153], v[212:215], v[90:93]
	v_mfma_f32_16x16x32_bf16 v[78:81], v[142:145], v[220:223], v[78:81]
	v_mfma_f32_16x16x32_bf16 v[74:77], v[150:153], v[220:223], v[74:77]
	v_mfma_f32_16x16x32_bf16 v[126:129], v[146:149], v[182:185], v[126:129]
	v_mfma_f32_16x16x32_bf16 v[122:125], v[154:157], v[182:185], v[122:125]
	v_mfma_f32_16x16x32_bf16 v[110:113], v[146:149], v[208:211], v[110:113]
	v_mfma_f32_16x16x32_bf16 v[106:109], v[154:157], v[208:211], v[106:109]
	v_mfma_f32_16x16x32_bf16 v[94:97], v[146:149], v[216:219], v[94:97]
	v_mfma_f32_16x16x32_bf16 v[90:93], v[154:157], v[216:219], v[90:93]
	v_mfma_f32_16x16x32_bf16 v[78:81], v[146:149], v[224:227], v[78:81]
	v_mfma_f32_16x16x32_bf16 v[74:77], v[154:157], v[224:227], v[74:77]
	v_mfma_f32_16x16x32_bf16 v[118:121], v[162:165], v[178:181], v[118:121]
	v_mfma_f32_16x16x32_bf16 v[114:117], v[170:173], v[178:181], v[114:117]
	v_mfma_f32_16x16x32_bf16 v[102:105], v[162:165], v[204:207], v[102:105]
	v_mfma_f32_16x16x32_bf16 v[98:101], v[170:173], v[204:207], v[98:101]
	v_mfma_f32_16x16x32_bf16 v[86:89], v[162:165], v[212:215], v[86:89]
	v_mfma_f32_16x16x32_bf16 v[82:85], v[170:173], v[212:215], v[82:85]
	v_mfma_f32_16x16x32_bf16 v[70:73], v[162:165], v[220:223], v[70:73]
	v_mfma_f32_16x16x32_bf16 v[66:69], v[170:173], v[220:223], v[66:69]
	v_mfma_f32_16x16x32_bf16 v[118:121], v[166:169], v[182:185], v[118:121]
	v_mfma_f32_16x16x32_bf16 v[114:117], v[174:177], v[182:185], v[114:117]
	v_mfma_f32_16x16x32_bf16 v[102:105], v[166:169], v[208:211], v[102:105]
	v_mfma_f32_16x16x32_bf16 v[98:101], v[174:177], v[208:211], v[98:101]
	v_mfma_f32_16x16x32_bf16 v[86:89], v[166:169], v[216:219], v[86:89]
	v_mfma_f32_16x16x32_bf16 v[82:85], v[174:177], v[216:219], v[82:85]
	v_mfma_f32_16x16x32_bf16 v[70:73], v[166:169], v[224:227], v[70:73]
	v_mfma_f32_16x16x32_bf16 v[66:69], v[174:177], v[224:227], v[66:69]
	s_barrier
	s_add_i32 s63, s61, s70
	s_add_u32 s54, s54, 0x80
	s_addc_u32 s55, s55, 0
	s_mov_b32 m0, s63
	ds_read_b128 v[178:181], v161 offset:49152
	ds_read_b128 v[182:185], v161 offset:50176
	ds_read_b128 v[204:207], v161 offset:51200
	ds_read_b128 v[208:211], v161 offset:52224
	ds_read_b128 v[212:215], v161 offset:53248
	ds_read_b128 v[216:219], v161 offset:54272
	ds_read_b128 v[220:223], v161 offset:55296
	ds_read_b128 v[224:227], v161 offset:56320
	global_load_lds_dwordx4 v134, s[54:55]
	s_add_i32 m0, s63, 0x2000
	s_add_i32 s63, s62, s70
	global_load_lds_dwordx4 v130, s[54:55]
	s_add_u32 s54, s54, 0x40000
	s_addc_u32 s55, s55, 0
	s_mov_b32 m0, s63
	s_sub_u32 s56, s56, 0x3ff80
	global_load_lds_dwordx4 v134, s[54:55]
	s_subb_u32 s57, s57, 0
	s_add_i32 m0, s63, 0x2000
	s_nop 0
	global_load_lds_dwordx4 v130, s[54:55]
	s_mov_b32 m0, s86
	s_nop 0
	global_load_lds_dwordx4 v136, s[56:57]
	s_mov_b32 m0, s87
	s_nop 0
	global_load_lds_dwordx4 v132, s[56:57]
	s_waitcnt vmcnt(8)
	s_waitcnt lgkmcnt(0)
	s_barrier
	v_mfma_f32_16x16x32_bf16 v[62:65], v[142:145], v[178:181], v[62:65]
	v_mfma_f32_16x16x32_bf16 v[58:61], v[150:153], v[178:181], v[58:61]
	v_mfma_f32_16x16x32_bf16 v[46:49], v[142:145], v[204:207], v[46:49]
	v_mfma_f32_16x16x32_bf16 v[42:45], v[150:153], v[204:207], v[42:45]
	v_mfma_f32_16x16x32_bf16 v[30:33], v[142:145], v[212:215], v[30:33]
	v_mfma_f32_16x16x32_bf16 v[26:29], v[150:153], v[212:215], v[26:29]
	v_mfma_f32_16x16x32_bf16 v[14:17], v[142:145], v[220:223], v[14:17]
	v_mfma_f32_16x16x32_bf16 v[10:13], v[150:153], v[220:223], v[10:13]
	v_mfma_f32_16x16x32_bf16 v[62:65], v[146:149], v[182:185], v[62:65]
	v_mfma_f32_16x16x32_bf16 v[58:61], v[154:157], v[182:185], v[58:61]
	v_mfma_f32_16x16x32_bf16 v[46:49], v[146:149], v[208:211], v[46:49]
	v_mfma_f32_16x16x32_bf16 v[42:45], v[154:157], v[208:211], v[42:45]
	v_mfma_f32_16x16x32_bf16 v[30:33], v[146:149], v[216:219], v[30:33]
	v_mfma_f32_16x16x32_bf16 v[26:29], v[154:157], v[216:219], v[26:29]
	v_mfma_f32_16x16x32_bf16 v[14:17], v[146:149], v[224:227], v[14:17]
	v_mfma_f32_16x16x32_bf16 v[10:13], v[154:157], v[224:227], v[10:13]
	v_mfma_f32_16x16x32_bf16 v[54:57], v[162:165], v[178:181], v[54:57]
	v_mfma_f32_16x16x32_bf16 v[50:53], v[170:173], v[178:181], v[50:53]
	v_mfma_f32_16x16x32_bf16 v[38:41], v[162:165], v[204:207], v[38:41]
	v_mfma_f32_16x16x32_bf16 v[34:37], v[170:173], v[204:207], v[34:37]
	v_mfma_f32_16x16x32_bf16 v[22:25], v[162:165], v[212:215], v[22:25]
	v_mfma_f32_16x16x32_bf16 v[18:21], v[170:173], v[212:215], v[18:21]
	v_mfma_f32_16x16x32_bf16 v[6:9], v[162:165], v[220:223], v[6:9]
	v_mfma_f32_16x16x32_bf16 v[2:5], v[170:173], v[220:223], v[2:5]
	v_mfma_f32_16x16x32_bf16 v[54:57], v[166:169], v[182:185], v[54:57]
	v_mfma_f32_16x16x32_bf16 v[50:53], v[174:177], v[182:185], v[50:53]
	v_mfma_f32_16x16x32_bf16 v[38:41], v[166:169], v[208:211], v[38:41]
	v_mfma_f32_16x16x32_bf16 v[34:37], v[174:177], v[208:211], v[34:37]
	v_mfma_f32_16x16x32_bf16 v[22:25], v[166:169], v[216:219], v[22:25]
	v_mfma_f32_16x16x32_bf16 v[18:21], v[174:177], v[216:219], v[18:21]
	v_mfma_f32_16x16x32_bf16 v[6:9], v[166:169], v[224:227], v[6:9]
	v_mfma_f32_16x16x32_bf16 v[2:5], v[174:177], v[224:227], v[2:5]
	s_barrier
	s_add_i32 s60, s60, 2
	s_add_u32 s52, s52, 0x100
	s_addc_u32 s53, s53, 0
	s_add_u32 s58, s58, 0x100
	s_addc_u32 s59, s59, 0
	s_cmp_gt_u32 s60, 13
	s_cbranch_scc0 .LBB0_479
	s_and_b64 vcc, exec, s[38:39]
	s_cbranch_vccz .LBB0_482
	s_barrier

.Lrb4_skip:
	s_add_u32 s47, s52, 0xfffc0080
	s_addc_u32 s54, s53, -1
	s_add_i32 s68, 0, 0x10000
	s_cmp_eq_u32 s45, 12
	s_cselect_b32 s57, s1, s54
	s_cselect_b32 s56, s5, s47
	v_add_u32_e32 v0, s68, v221
	s_cselect_b32 s55, s6, s19
	s_cselect_b32 s54, s7, s18
	s_add_i32 s47, 0, 0x14000
	ds_read_b128 v[106:109], v0
	ds_read_b128 v[110:113], v0 offset:1024
	ds_read_b128 v[126:129], v0 offset:2048
	ds_read_b128 v[134:137], v0 offset:3072
	v_add_u32_e32 v0, s47, v221
	ds_read_b128 v[146:149], v0
	ds_read_b128 v[150:153], v0 offset:1024
	ds_read_b128 v[154:157], v0 offset:2048
	ds_read_b128 v[158:161], v0 offset:3072
	v_lshl_add_u64 v[216:217], s[52:53], 0, v[212:213]
	s_add_i32 m0, s59, 0xc000
	ds_read_b128 v[162:165], v222
	ds_read_b128 v[166:169], v222 offset:1024
	ds_read_b128 v[170:173], v222 offset:2048
	ds_read_b128 v[174:177], v222 offset:3072
	ds_read_b128 v[178:181], v222 offset:4096
	ds_read_b128 v[182:185], v222 offset:5120
	ds_read_b128 v[224:227], v222 offset:6144
	ds_read_b128 v[228:231], v222 offset:7168
	global_load_lds_dwordx4 v[216:217], off
	v_lshl_add_u64 v[216:217], s[52:53], 0, v[214:215]
	s_add_i32 m0, s59, 0xe000
	s_nop 0
	global_load_lds_dwordx4 v[216:217], off
	s_waitcnt vmcnt(8)
	s_waitcnt lgkmcnt(0)
	s_barrier
	v_mfma_f32_16x16x32_bf16 v[142:145], v[106:109], v[162:165], 0
	v_mfma_f32_16x16x32_bf16 v[138:141], v[126:129], v[162:165], 0
	v_mfma_f32_16x16x32_bf16 v[118:121], v[106:109], v[170:173], 0
	v_mfma_f32_16x16x32_bf16 v[114:117], v[126:129], v[170:173], 0
	v_mfma_f32_16x16x32_bf16 v[94:97], v[106:109], v[178:181], 0
	v_mfma_f32_16x16x32_bf16 v[90:93], v[126:129], v[178:181], 0
	v_mfma_f32_16x16x32_bf16 v[78:81], v[106:109], v[224:227], 0
	v_mfma_f32_16x16x32_bf16 v[74:77], v[126:129], v[224:227], 0
	v_mfma_f32_16x16x32_bf16 v[142:145], v[110:113], v[166:169], v[142:145]
	v_mfma_f32_16x16x32_bf16 v[138:141], v[134:137], v[166:169], v[138:141]
	v_mfma_f32_16x16x32_bf16 v[118:121], v[110:113], v[174:177], v[118:121]
	v_mfma_f32_16x16x32_bf16 v[114:117], v[134:137], v[174:177], v[114:117]
	v_mfma_f32_16x16x32_bf16 v[94:97], v[110:113], v[182:185], v[94:97]
	v_mfma_f32_16x16x32_bf16 v[90:93], v[134:137], v[182:185], v[90:93]
	v_mfma_f32_16x16x32_bf16 v[78:81], v[110:113], v[228:231], v[78:81]
	v_mfma_f32_16x16x32_bf16 v[74:77], v[134:137], v[228:231], v[74:77]
	v_mfma_f32_16x16x32_bf16 v[130:133], v[146:149], v[162:165], 0
	v_mfma_f32_16x16x32_bf16 v[122:125], v[154:157], v[162:165], 0
	v_mfma_f32_16x16x32_bf16 v[102:105], v[146:149], v[170:173], 0
	v_mfma_f32_16x16x32_bf16 v[98:101], v[154:157], v[170:173], 0
	v_mfma_f32_16x16x32_bf16 v[86:89], v[146:149], v[178:181], 0
	v_mfma_f32_16x16x32_bf16 v[82:85], v[154:157], v[178:181], 0
	v_mfma_f32_16x16x32_bf16 v[70:73], v[146:149], v[224:227], 0
	v_mfma_f32_16x16x32_bf16 v[66:69], v[154:157], v[224:227], 0
	v_mfma_f32_16x16x32_bf16 v[130:133], v[150:153], v[166:169], v[130:133]
	v_mfma_f32_16x16x32_bf16 v[122:125], v[158:161], v[166:169], v[122:125]
	v_mfma_f32_16x16x32_bf16 v[102:105], v[150:153], v[174:177], v[102:105]
	v_mfma_f32_16x16x32_bf16 v[98:101], v[158:161], v[174:177], v[98:101]
	v_mfma_f32_16x16x32_bf16 v[86:89], v[150:153], v[182:185], v[86:89]
	v_mfma_f32_16x16x32_bf16 v[82:85], v[158:161], v[182:185], v[82:85]
	v_mfma_f32_16x16x32_bf16 v[70:73], v[150:153], v[228:231], v[70:73]
	v_mfma_f32_16x16x32_bf16 v[66:69], v[158:161], v[228:231], v[66:69]
	s_barrier
	s_add_i32 s68, s68, s58
	v_lshl_add_u64 v[216:217], s[54:55], 0, v[208:209]
	s_mov_b32 m0, s68
	ds_read_b128 v[162:165], v222 offset:16384
	ds_read_b128 v[166:169], v222 offset:17408
	ds_read_b128 v[170:173], v222 offset:18432
	ds_read_b128 v[174:177], v222 offset:19456
	ds_read_b128 v[178:181], v222 offset:20480
	ds_read_b128 v[182:185], v222 offset:21504
	ds_read_b128 v[224:227], v222 offset:22528
	ds_read_b128 v[228:231], v222 offset:23552
	global_load_lds_dwordx4 v[216:217], off
	s_add_i32 m0, s68, 0x2000
	s_add_u32 s68, s54, 0x40000
	v_lshl_add_u64 v[240:241], s[54:55], 0, v[204:205]
	s_addc_u32 s69, s55, 0
	s_add_i32 s47, s47, s58
	global_load_lds_dwordx4 v[240:241], off
	v_lshl_add_u64 v[242:243], s[68:69], 0, v[208:209]
	s_mov_b32 m0, s47
	v_lshl_add_u64 v[244:245], s[56:57], 0, v[206:207]
	global_load_lds_dwordx4 v[242:243], off
	v_lshl_add_u64 v[242:243], s[68:69], 0, v[204:205]
	s_add_i32 m0, s47, 0x2000
	s_nop 0
	global_load_lds_dwordx4 v[242:243], off
	v_lshl_add_u64 v[242:243], s[56:57], 0, v[210:211]
	s_mov_b32 m0, s59
	s_nop 0
	global_load_lds_dwordx4 v[242:243], off
	s_mov_b32 m0, s60
	s_nop 0
	global_load_lds_dwordx4 v[244:245], off
	s_waitcnt vmcnt(8)
	s_waitcnt lgkmcnt(0)
	s_barrier
	v_mfma_f32_16x16x32_bf16 v[62:65], v[106:109], v[162:165], 0
	v_mfma_f32_16x16x32_bf16 v[58:61], v[126:129], v[162:165], 0
	v_mfma_f32_16x16x32_bf16 v[46:49], v[106:109], v[170:173], 0
	v_mfma_f32_16x16x32_bf16 v[42:45], v[126:129], v[170:173], 0
	v_mfma_f32_16x16x32_bf16 v[30:33], v[106:109], v[178:181], 0
	v_mfma_f32_16x16x32_bf16 v[26:29], v[126:129], v[178:181], 0
	v_mfma_f32_16x16x32_bf16 v[14:17], v[106:109], v[224:227], 0
	v_mfma_f32_16x16x32_bf16 v[10:13], v[126:129], v[224:227], 0
	v_mfma_f32_16x16x32_bf16 v[62:65], v[110:113], v[166:169], v[62:65]
	v_mfma_f32_16x16x32_bf16 v[58:61], v[134:137], v[166:169], v[58:61]
	v_mfma_f32_16x16x32_bf16 v[46:49], v[110:113], v[174:177], v[46:49]
	v_mfma_f32_16x16x32_bf16 v[42:45], v[134:137], v[174:177], v[42:45]
	v_mfma_f32_16x16x32_bf16 v[30:33], v[110:113], v[182:185], v[30:33]
	v_mfma_f32_16x16x32_bf16 v[26:29], v[134:137], v[182:185], v[26:29]
	v_mfma_f32_16x16x32_bf16 v[14:17], v[110:113], v[228:231], v[14:17]
	v_mfma_f32_16x16x32_bf16 v[10:13], v[134:137], v[228:231], v[10:13]
	v_mfma_f32_16x16x32_bf16 v[54:57], v[146:149], v[162:165], 0
	v_mfma_f32_16x16x32_bf16 v[50:53], v[154:157], v[162:165], 0
	v_mfma_f32_16x16x32_bf16 v[38:41], v[146:149], v[170:173], 0
	v_mfma_f32_16x16x32_bf16 v[34:37], v[154:157], v[170:173], 0
	v_mfma_f32_16x16x32_bf16 v[22:25], v[146:149], v[178:181], 0
	v_mfma_f32_16x16x32_bf16 v[18:21], v[154:157], v[178:181], 0
	v_mfma_f32_16x16x32_bf16 v[6:9], v[146:149], v[224:227], 0
	v_mfma_f32_16x16x32_bf16 v[2:5], v[154:157], v[224:227], 0
	v_mfma_f32_16x16x32_bf16 v[54:57], v[150:153], v[166:169], v[54:57]
	v_mfma_f32_16x16x32_bf16 v[50:53], v[158:161], v[166:169], v[50:53]
	v_mfma_f32_16x16x32_bf16 v[38:41], v[150:153], v[174:177], v[38:41]
	v_mfma_f32_16x16x32_bf16 v[34:37], v[158:161], v[174:177], v[34:37]
	v_mfma_f32_16x16x32_bf16 v[22:25], v[150:153], v[182:185], v[22:25]
	v_mfma_f32_16x16x32_bf16 v[18:21], v[158:161], v[182:185], v[18:21]
	v_mfma_f32_16x16x32_bf16 v[6:9], v[150:153], v[228:231], v[6:9]
	v_mfma_f32_16x16x32_bf16 v[2:5], v[158:161], v[228:231], v[2:5]
	s_barrier
	s_add_i32 s47, 0, 0x18000
	v_add_u32_e32 v0, s47, v221
	s_add_i32 s68, 0, 0x1c000
	ds_read_b128 v[106:109], v0
	ds_read_b128 v[110:113], v0 offset:1024
	ds_read_b128 v[126:129], v0 offset:2048
	ds_read_b128 v[134:137], v0 offset:3072
	v_add_u32_e32 v0, s68, v221
	ds_read_b128 v[146:149], v0
	ds_read_b128 v[150:153], v0 offset:1024
	ds_read_b128 v[154:157], v0 offset:2048
	ds_read_b128 v[158:161], v0 offset:3072
	s_add_u32 s56, s56, 0x40000
	s_addc_u32 s57, s57, 0
	s_mov_b32 m0, s61
	v_lshl_add_u64 v[246:247], s[56:57], 0, v[210:211]
	ds_read_b128 v[162:165], v222 offset:32768
	ds_read_b128 v[166:169], v222 offset:33792
	ds_read_b128 v[170:173], v222 offset:34816
	ds_read_b128 v[174:177], v222 offset:35840
	ds_read_b128 v[178:181], v222 offset:36864
	ds_read_b128 v[182:185], v222 offset:37888
	ds_read_b128 v[224:227], v222 offset:38912
	ds_read_b128 v[228:231], v222 offset:39936
	global_load_lds_dwordx4 v[246:247], off
	v_lshl_add_u64 v[246:247], s[56:57], 0, v[206:207]
	s_mov_b32 m0, s62
	s_nop 0
	global_load_lds_dwordx4 v[246:247], off
	s_waitcnt vmcnt(8)
	s_waitcnt lgkmcnt(0)
	s_barrier
	v_mfma_f32_16x16x32_bf16 v[142:145], v[106:109], v[162:165], v[142:145]
	v_mfma_f32_16x16x32_bf16 v[138:141], v[126:129], v[162:165], v[138:141]
	v_mfma_f32_16x16x32_bf16 v[118:121], v[106:109], v[170:173], v[118:121]
	v_mfma_f32_16x16x32_bf16 v[114:117], v[126:129], v[170:173], v[114:117]
	v_mfma_f32_16x16x32_bf16 v[94:97], v[106:109], v[178:181], v[94:97]
	v_mfma_f32_16x16x32_bf16 v[90:93], v[126:129], v[178:181], v[90:93]
	v_mfma_f32_16x16x32_bf16 v[78:81], v[106:109], v[224:227], v[78:81]
	v_mfma_f32_16x16x32_bf16 v[74:77], v[126:129], v[224:227], v[74:77]
	v_mfma_f32_16x16x32_bf16 v[142:145], v[110:113], v[166:169], v[142:145]
	v_mfma_f32_16x16x32_bf16 v[138:141], v[134:137], v[166:169], v[138:141]
	v_mfma_f32_16x16x32_bf16 v[118:121], v[110:113], v[174:177], v[118:121]
	v_mfma_f32_16x16x32_bf16 v[114:117], v[134:137], v[174:177], v[114:117]
	v_mfma_f32_16x16x32_bf16 v[94:97], v[110:113], v[182:185], v[94:97]
	v_mfma_f32_16x16x32_bf16 v[90:93], v[134:137], v[182:185], v[90:93]
	v_mfma_f32_16x16x32_bf16 v[78:81], v[110:113], v[228:231], v[78:81]
	v_mfma_f32_16x16x32_bf16 v[74:77], v[134:137], v[228:231], v[74:77]
	v_mfma_f32_16x16x32_bf16 v[130:133], v[146:149], v[162:165], v[130:133]
	v_mfma_f32_16x16x32_bf16 v[122:125], v[154:157], v[162:165], v[122:125]
	v_mfma_f32_16x16x32_bf16 v[102:105], v[146:149], v[170:173], v[102:105]
	v_mfma_f32_16x16x32_bf16 v[98:101], v[154:157], v[170:173], v[98:101]
	v_mfma_f32_16x16x32_bf16 v[86:89], v[146:149], v[178:181], v[86:89]
	v_mfma_f32_16x16x32_bf16 v[82:85], v[154:157], v[178:181], v[82:85]
	v_mfma_f32_16x16x32_bf16 v[70:73], v[146:149], v[224:227], v[70:73]
	v_mfma_f32_16x16x32_bf16 v[66:69], v[154:157], v[224:227], v[66:69]
	v_mfma_f32_16x16x32_bf16 v[130:133], v[150:153], v[166:169], v[130:133]
	v_mfma_f32_16x16x32_bf16 v[122:125], v[158:161], v[166:169], v[122:125]
	v_mfma_f32_16x16x32_bf16 v[102:105], v[150:153], v[174:177], v[102:105]
	v_mfma_f32_16x16x32_bf16 v[98:101], v[158:161], v[174:177], v[98:101]
	v_mfma_f32_16x16x32_bf16 v[86:89], v[150:153], v[182:185], v[86:89]
	v_mfma_f32_16x16x32_bf16 v[82:85], v[158:161], v[182:185], v[82:85]
	v_mfma_f32_16x16x32_bf16 v[70:73], v[150:153], v[228:231], v[70:73]
	v_mfma_f32_16x16x32_bf16 v[66:69], v[158:161], v[228:231], v[66:69]
	s_barrier
	s_add_i32 s47, s47, s58
	v_lshl_add_u64 v[216:217], v[216:217], 0, s[16:17]
	s_mov_b32 m0, s47
	ds_read_b128 v[162:165], v222 offset:49152
	ds_read_b128 v[166:169], v222 offset:50176
	ds_read_b128 v[170:173], v222 offset:51200
	ds_read_b128 v[174:177], v222 offset:52224
	ds_read_b128 v[178:181], v222 offset:53248
	ds_read_b128 v[182:185], v222 offset:54272
	ds_read_b128 v[224:227], v222 offset:55296
	ds_read_b128 v[228:231], v222 offset:56320
	global_load_lds_dwordx4 v[216:217], off
	s_add_i32 m0, s47, 0x2000
	s_add_u32 s54, s54, 0x40080
	v_lshl_add_u64 v[216:217], v[240:241], 0, s[16:17]
	s_addc_u32 s55, s55, 0
	s_add_i32 s47, s68, s58
	global_load_lds_dwordx4 v[216:217], off
	v_lshl_add_u64 v[216:217], s[54:55], 0, v[208:209]
	s_mov_b32 m0, s47
	s_nop 0
	global_load_lds_dwordx4 v[216:217], off
	v_lshl_add_u64 v[216:217], s[54:55], 0, v[204:205]
	s_add_i32 m0, s47, 0x2000
	s_nop 0
	global_load_lds_dwordx4 v[216:217], off
	v_lshl_add_u64 v[216:217], v[242:243], 0, s[16:17]
	s_mov_b32 m0, s65
	s_nop 0
	global_load_lds_dwordx4 v[216:217], off
	v_lshl_add_u64 v[216:217], v[244:245], 0, s[16:17]
	s_mov_b32 m0, s66
	s_nop 0
	global_load_lds_dwordx4 v[216:217], off
	s_waitcnt vmcnt(8)
	s_waitcnt lgkmcnt(0)
	s_barrier
	v_mfma_f32_16x16x32_bf16 v[62:65], v[106:109], v[162:165], v[62:65]
	v_mfma_f32_16x16x32_bf16 v[58:61], v[126:129], v[162:165], v[58:61]
	v_mfma_f32_16x16x32_bf16 v[46:49], v[106:109], v[170:173], v[46:49]
	v_mfma_f32_16x16x32_bf16 v[42:45], v[126:129], v[170:173], v[42:45]
	v_mfma_f32_16x16x32_bf16 v[30:33], v[106:109], v[178:181], v[30:33]
	v_mfma_f32_16x16x32_bf16 v[26:29], v[126:129], v[178:181], v[26:29]
	v_mfma_f32_16x16x32_bf16 v[14:17], v[106:109], v[224:227], v[14:17]
	v_mfma_f32_16x16x32_bf16 v[10:13], v[126:129], v[224:227], v[10:13]
	v_mfma_f32_16x16x32_bf16 v[62:65], v[110:113], v[166:169], v[62:65]
	v_mfma_f32_16x16x32_bf16 v[58:61], v[134:137], v[166:169], v[58:61]
	v_mfma_f32_16x16x32_bf16 v[46:49], v[110:113], v[174:177], v[46:49]
	v_mfma_f32_16x16x32_bf16 v[42:45], v[134:137], v[174:177], v[42:45]
	v_mfma_f32_16x16x32_bf16 v[30:33], v[110:113], v[182:185], v[30:33]
	v_mfma_f32_16x16x32_bf16 v[26:29], v[134:137], v[182:185], v[26:29]
	v_mfma_f32_16x16x32_bf16 v[14:17], v[110:113], v[228:231], v[14:17]
	v_mfma_f32_16x16x32_bf16 v[10:13], v[134:137], v[228:231], v[10:13]
	v_mfma_f32_16x16x32_bf16 v[54:57], v[146:149], v[162:165], v[54:57]
	v_mfma_f32_16x16x32_bf16 v[50:53], v[154:157], v[162:165], v[50:53]
	v_mfma_f32_16x16x32_bf16 v[38:41], v[146:149], v[170:173], v[38:41]
	v_mfma_f32_16x16x32_bf16 v[34:37], v[154:157], v[170:173], v[34:37]
	v_mfma_f32_16x16x32_bf16 v[22:25], v[146:149], v[178:181], v[22:25]
	v_mfma_f32_16x16x32_bf16 v[18:21], v[154:157], v[178:181], v[18:21]
	v_mfma_f32_16x16x32_bf16 v[6:9], v[146:149], v[224:227], v[6:9]
	v_mfma_f32_16x16x32_bf16 v[2:5], v[154:157], v[224:227], v[2:5]
	v_mfma_f32_16x16x32_bf16 v[54:57], v[150:153], v[166:169], v[54:57]
	v_mfma_f32_16x16x32_bf16 v[50:53], v[158:161], v[166:169], v[50:53]
	v_mfma_f32_16x16x32_bf16 v[38:41], v[150:153], v[174:177], v[38:41]
	v_mfma_f32_16x16x32_bf16 v[34:37], v[158:161], v[174:177], v[34:37]
	v_mfma_f32_16x16x32_bf16 v[22:25], v[150:153], v[182:185], v[22:25]
	v_mfma_f32_16x16x32_bf16 v[18:21], v[158:161], v[182:185], v[18:21]
	v_mfma_f32_16x16x32_bf16 v[6:9], v[150:153], v[228:231], v[6:9]
	v_mfma_f32_16x16x32_bf16 v[2:5], v[158:161], v[228:231], v[2:5]
	s_barrier
	s_add_i32 s45, s45, 2
	s_add_u32 s52, s52, 0x100
	s_addc_u32 s53, s53, 0
	s_add_u32 s18, s18, 0x100
	s_addc_u32 s19, s19, 0
	s_cmp_gt_u32 s45, 13
.LBB0_900:
	s_add_u32 s47, s52, 0xfffc0080
	s_addc_u32 s54, s53, -1
	s_add_i32 s68, 0, 0x10000
	s_cmp_eq_u32 s45, 12
	s_cselect_b32 s57, s1, s54
	s_cselect_b32 s56, s5, s47
	v_add_u32_e32 v0, s68, v221
	s_cselect_b32 s55, s6, s19
	s_cselect_b32 s54, s7, s18
	s_add_i32 s47, 0, 0x14000
	ds_read_b128 v[106:109], v0
	ds_read_b128 v[110:113], v0 offset:1024
	ds_read_b128 v[126:129], v0 offset:2048
	ds_read_b128 v[134:137], v0 offset:3072
	v_add_u32_e32 v0, s47, v221
	ds_read_b128 v[146:149], v0
	ds_read_b128 v[150:153], v0 offset:1024
	ds_read_b128 v[154:157], v0 offset:2048
	ds_read_b128 v[158:161], v0 offset:3072
	v_lshl_add_u64 v[216:217], s[52:53], 0, v[212:213]
	s_add_i32 m0, s59, 0xc000
	ds_read_b128 v[162:165], v222
	ds_read_b128 v[166:169], v222 offset:1024
	ds_read_b128 v[170:173], v222 offset:2048
	ds_read_b128 v[174:177], v222 offset:3072
	ds_read_b128 v[178:181], v222 offset:4096
	ds_read_b128 v[182:185], v222 offset:5120
	ds_read_b128 v[224:227], v222 offset:6144
	ds_read_b128 v[228:231], v222 offset:7168
	global_load_lds_dwordx4 v[216:217], off
	v_lshl_add_u64 v[216:217], s[52:53], 0, v[214:215]
	s_add_i32 m0, s59, 0xe000
	s_nop 0
	global_load_lds_dwordx4 v[216:217], off
	s_waitcnt vmcnt(8)
	s_waitcnt lgkmcnt(0)
	s_barrier
	v_mfma_f32_16x16x32_bf16 v[142:145], v[106:109], v[162:165], v[142:145]
	v_mfma_f32_16x16x32_bf16 v[138:141], v[126:129], v[162:165], v[138:141]
	v_mfma_f32_16x16x32_bf16 v[118:121], v[106:109], v[170:173], v[118:121]
	v_mfma_f32_16x16x32_bf16 v[114:117], v[126:129], v[170:173], v[114:117]
	v_mfma_f32_16x16x32_bf16 v[94:97], v[106:109], v[178:181], v[94:97]
	v_mfma_f32_16x16x32_bf16 v[90:93], v[126:129], v[178:181], v[90:93]
	v_mfma_f32_16x16x32_bf16 v[78:81], v[106:109], v[224:227], v[78:81]
	v_mfma_f32_16x16x32_bf16 v[74:77], v[126:129], v[224:227], v[74:77]
	v_mfma_f32_16x16x32_bf16 v[142:145], v[110:113], v[166:169], v[142:145]
	v_mfma_f32_16x16x32_bf16 v[138:141], v[134:137], v[166:169], v[138:141]
	v_mfma_f32_16x16x32_bf16 v[118:121], v[110:113], v[174:177], v[118:121]
	v_mfma_f32_16x16x32_bf16 v[114:117], v[134:137], v[174:177], v[114:117]
	v_mfma_f32_16x16x32_bf16 v[94:97], v[110:113], v[182:185], v[94:97]
	v_mfma_f32_16x16x32_bf16 v[90:93], v[134:137], v[182:185], v[90:93]
	v_mfma_f32_16x16x32_bf16 v[78:81], v[110:113], v[228:231], v[78:81]
	v_mfma_f32_16x16x32_bf16 v[74:77], v[134:137], v[228:231], v[74:77]
	v_mfma_f32_16x16x32_bf16 v[130:133], v[146:149], v[162:165], v[130:133]
	v_mfma_f32_16x16x32_bf16 v[122:125], v[154:157], v[162:165], v[122:125]
	v_mfma_f32_16x16x32_bf16 v[102:105], v[146:149], v[170:173], v[102:105]
	v_mfma_f32_16x16x32_bf16 v[98:101], v[154:157], v[170:173], v[98:101]
	v_mfma_f32_16x16x32_bf16 v[86:89], v[146:149], v[178:181], v[86:89]
	v_mfma_f32_16x16x32_bf16 v[82:85], v[154:157], v[178:181], v[82:85]
	v_mfma_f32_16x16x32_bf16 v[70:73], v[146:149], v[224:227], v[70:73]
	v_mfma_f32_16x16x32_bf16 v[66:69], v[154:157], v[224:227], v[66:69]
	v_mfma_f32_16x16x32_bf16 v[130:133], v[150:153], v[166:169], v[130:133]
	v_mfma_f32_16x16x32_bf16 v[122:125], v[158:161], v[166:169], v[122:125]
	v_mfma_f32_16x16x32_bf16 v[102:105], v[150:153], v[174:177], v[102:105]
	v_mfma_f32_16x16x32_bf16 v[98:101], v[158:161], v[174:177], v[98:101]
	v_mfma_f32_16x16x32_bf16 v[86:89], v[150:153], v[182:185], v[86:89]
	v_mfma_f32_16x16x32_bf16 v[82:85], v[158:161], v[182:185], v[82:85]
	v_mfma_f32_16x16x32_bf16 v[70:73], v[150:153], v[228:231], v[70:73]
	v_mfma_f32_16x16x32_bf16 v[66:69], v[158:161], v[228:231], v[66:69]
	s_barrier
	s_add_i32 s68, s68, s58
	v_lshl_add_u64 v[216:217], s[54:55], 0, v[208:209]
	s_mov_b32 m0, s68
	ds_read_b128 v[162:165], v222 offset:16384
	ds_read_b128 v[166:169], v222 offset:17408
	ds_read_b128 v[170:173], v222 offset:18432
	ds_read_b128 v[174:177], v222 offset:19456
	ds_read_b128 v[178:181], v222 offset:20480
	ds_read_b128 v[182:185], v222 offset:21504
	ds_read_b128 v[224:227], v222 offset:22528
	ds_read_b128 v[228:231], v222 offset:23552
	global_load_lds_dwordx4 v[216:217], off
	s_add_i32 m0, s68, 0x2000
	s_add_u32 s68, s54, 0x40000
	v_lshl_add_u64 v[240:241], s[54:55], 0, v[204:205]
	s_addc_u32 s69, s55, 0
	s_add_i32 s47, s47, s58
	global_load_lds_dwordx4 v[240:241], off
	v_lshl_add_u64 v[242:243], s[68:69], 0, v[208:209]
	s_mov_b32 m0, s47
	v_lshl_add_u64 v[244:245], s[56:57], 0, v[206:207]
	global_load_lds_dwordx4 v[242:243], off
	v_lshl_add_u64 v[242:243], s[68:69], 0, v[204:205]
	s_add_i32 m0, s47, 0x2000
	s_nop 0
	global_load_lds_dwordx4 v[242:243], off
	v_lshl_add_u64 v[242:243], s[56:57], 0, v[210:211]
	s_mov_b32 m0, s59
	s_nop 0
	global_load_lds_dwordx4 v[242:243], off
	s_mov_b32 m0, s60
	s_nop 0
	global_load_lds_dwordx4 v[244:245], off
	s_waitcnt vmcnt(8)
	s_waitcnt lgkmcnt(0)
	s_barrier
	v_mfma_f32_16x16x32_bf16 v[62:65], v[106:109], v[162:165], v[62:65]
	v_mfma_f32_16x16x32_bf16 v[58:61], v[126:129], v[162:165], v[58:61]
	v_mfma_f32_16x16x32_bf16 v[46:49], v[106:109], v[170:173], v[46:49]
	v_mfma_f32_16x16x32_bf16 v[42:45], v[126:129], v[170:173], v[42:45]
	v_mfma_f32_16x16x32_bf16 v[30:33], v[106:109], v[178:181], v[30:33]
	v_mfma_f32_16x16x32_bf16 v[26:29], v[126:129], v[178:181], v[26:29]
	v_mfma_f32_16x16x32_bf16 v[14:17], v[106:109], v[224:227], v[14:17]
	v_mfma_f32_16x16x32_bf16 v[10:13], v[126:129], v[224:227], v[10:13]
	v_mfma_f32_16x16x32_bf16 v[62:65], v[110:113], v[166:169], v[62:65]
	v_mfma_f32_16x16x32_bf16 v[58:61], v[134:137], v[166:169], v[58:61]
	v_mfma_f32_16x16x32_bf16 v[46:49], v[110:113], v[174:177], v[46:49]
	v_mfma_f32_16x16x32_bf16 v[42:45], v[134:137], v[174:177], v[42:45]
	v_mfma_f32_16x16x32_bf16 v[30:33], v[110:113], v[182:185], v[30:33]
	v_mfma_f32_16x16x32_bf16 v[26:29], v[134:137], v[182:185], v[26:29]
	v_mfma_f32_16x16x32_bf16 v[14:17], v[110:113], v[228:231], v[14:17]
	v_mfma_f32_16x16x32_bf16 v[10:13], v[134:137], v[228:231], v[10:13]
	v_mfma_f32_16x16x32_bf16 v[54:57], v[146:149], v[162:165], v[54:57]
	v_mfma_f32_16x16x32_bf16 v[50:53], v[154:157], v[162:165], v[50:53]
	v_mfma_f32_16x16x32_bf16 v[38:41], v[146:149], v[170:173], v[38:41]
	v_mfma_f32_16x16x32_bf16 v[34:37], v[154:157], v[170:173], v[34:37]
	v_mfma_f32_16x16x32_bf16 v[22:25], v[146:149], v[178:181], v[22:25]
	v_mfma_f32_16x16x32_bf16 v[18:21], v[154:157], v[178:181], v[18:21]
	v_mfma_f32_16x16x32_bf16 v[6:9], v[146:149], v[224:227], v[6:9]
	v_mfma_f32_16x16x32_bf16 v[2:5], v[154:157], v[224:227], v[2:5]
	v_mfma_f32_16x16x32_bf16 v[54:57], v[150:153], v[166:169], v[54:57]
	v_mfma_f32_16x16x32_bf16 v[50:53], v[158:161], v[166:169], v[50:53]
	v_mfma_f32_16x16x32_bf16 v[38:41], v[150:153], v[174:177], v[38:41]
	v_mfma_f32_16x16x32_bf16 v[34:37], v[158:161], v[174:177], v[34:37]
	v_mfma_f32_16x16x32_bf16 v[22:25], v[150:153], v[182:185], v[22:25]
	v_mfma_f32_16x16x32_bf16 v[18:21], v[158:161], v[182:185], v[18:21]
	v_mfma_f32_16x16x32_bf16 v[6:9], v[150:153], v[228:231], v[6:9]
	v_mfma_f32_16x16x32_bf16 v[2:5], v[158:161], v[228:231], v[2:5]
	s_barrier
	s_add_i32 s47, 0, 0x18000
	v_add_u32_e32 v0, s47, v221
	s_add_i32 s68, 0, 0x1c000
	ds_read_b128 v[106:109], v0
	ds_read_b128 v[110:113], v0 offset:1024
	ds_read_b128 v[126:129], v0 offset:2048
	ds_read_b128 v[134:137], v0 offset:3072
	v_add_u32_e32 v0, s68, v221
	ds_read_b128 v[146:149], v0
	ds_read_b128 v[150:153], v0 offset:1024
	ds_read_b128 v[154:157], v0 offset:2048
	ds_read_b128 v[158:161], v0 offset:3072
	s_add_u32 s56, s56, 0x40000
	s_addc_u32 s57, s57, 0
	s_mov_b32 m0, s61
	v_lshl_add_u64 v[246:247], s[56:57], 0, v[210:211]
	ds_read_b128 v[162:165], v222 offset:32768
	ds_read_b128 v[166:169], v222 offset:33792
	ds_read_b128 v[170:173], v222 offset:34816
	ds_read_b128 v[174:177], v222 offset:35840
	ds_read_b128 v[178:181], v222 offset:36864
	ds_read_b128 v[182:185], v222 offset:37888
	ds_read_b128 v[224:227], v222 offset:38912
	ds_read_b128 v[228:231], v222 offset:39936
	global_load_lds_dwordx4 v[246:247], off
	v_lshl_add_u64 v[246:247], s[56:57], 0, v[206:207]
	s_mov_b32 m0, s62
	s_nop 0
	global_load_lds_dwordx4 v[246:247], off
	s_waitcnt vmcnt(8)
	s_waitcnt lgkmcnt(0)
	s_barrier
	v_mfma_f32_16x16x32_bf16 v[142:145], v[106:109], v[162:165], v[142:145]
	v_mfma_f32_16x16x32_bf16 v[138:141], v[126:129], v[162:165], v[138:141]
	v_mfma_f32_16x16x32_bf16 v[118:121], v[106:109], v[170:173], v[118:121]
	v_mfma_f32_16x16x32_bf16 v[114:117], v[126:129], v[170:173], v[114:117]
	v_mfma_f32_16x16x32_bf16 v[94:97], v[106:109], v[178:181], v[94:97]
	v_mfma_f32_16x16x32_bf16 v[90:93], v[126:129], v[178:181], v[90:93]
	v_mfma_f32_16x16x32_bf16 v[78:81], v[106:109], v[224:227], v[78:81]
	v_mfma_f32_16x16x32_bf16 v[74:77], v[126:129], v[224:227], v[74:77]
	v_mfma_f32_16x16x32_bf16 v[142:145], v[110:113], v[166:169], v[142:145]
	v_mfma_f32_16x16x32_bf16 v[138:141], v[134:137], v[166:169], v[138:141]
	v_mfma_f32_16x16x32_bf16 v[118:121], v[110:113], v[174:177], v[118:121]
	v_mfma_f32_16x16x32_bf16 v[114:117], v[134:137], v[174:177], v[114:117]
	v_mfma_f32_16x16x32_bf16 v[94:97], v[110:113], v[182:185], v[94:97]
	v_mfma_f32_16x16x32_bf16 v[90:93], v[134:137], v[182:185], v[90:93]
	v_mfma_f32_16x16x32_bf16 v[78:81], v[110:113], v[228:231], v[78:81]
	v_mfma_f32_16x16x32_bf16 v[74:77], v[134:137], v[228:231], v[74:77]
	v_mfma_f32_16x16x32_bf16 v[130:133], v[146:149], v[162:165], v[130:133]
	v_mfma_f32_16x16x32_bf16 v[122:125], v[154:157], v[162:165], v[122:125]
	v_mfma_f32_16x16x32_bf16 v[102:105], v[146:149], v[170:173], v[102:105]
	v_mfma_f32_16x16x32_bf16 v[98:101], v[154:157], v[170:173], v[98:101]
	v_mfma_f32_16x16x32_bf16 v[86:89], v[146:149], v[178:181], v[86:89]
	v_mfma_f32_16x16x32_bf16 v[82:85], v[154:157], v[178:181], v[82:85]
	v_mfma_f32_16x16x32_bf16 v[70:73], v[146:149], v[224:227], v[70:73]
	v_mfma_f32_16x16x32_bf16 v[66:69], v[154:157], v[224:227], v[66:69]
	v_mfma_f32_16x16x32_bf16 v[130:133], v[150:153], v[166:169], v[130:133]
	v_mfma_f32_16x16x32_bf16 v[122:125], v[158:161], v[166:169], v[122:125]
	v_mfma_f32_16x16x32_bf16 v[102:105], v[150:153], v[174:177], v[102:105]
	v_mfma_f32_16x16x32_bf16 v[98:101], v[158:161], v[174:177], v[98:101]
	v_mfma_f32_16x16x32_bf16 v[86:89], v[150:153], v[182:185], v[86:89]
	v_mfma_f32_16x16x32_bf16 v[82:85], v[158:161], v[182:185], v[82:85]
	v_mfma_f32_16x16x32_bf16 v[70:73], v[150:153], v[228:231], v[70:73]
	v_mfma_f32_16x16x32_bf16 v[66:69], v[158:161], v[228:231], v[66:69]
	s_barrier
	s_add_i32 s47, s47, s58
	v_lshl_add_u64 v[216:217], v[216:217], 0, s[16:17]
	s_mov_b32 m0, s47
	ds_read_b128 v[162:165], v222 offset:49152
	ds_read_b128 v[166:169], v222 offset:50176
	ds_read_b128 v[170:173], v222 offset:51200
	ds_read_b128 v[174:177], v222 offset:52224
	ds_read_b128 v[178:181], v222 offset:53248
	ds_read_b128 v[182:185], v222 offset:54272
	ds_read_b128 v[224:227], v222 offset:55296
	ds_read_b128 v[228:231], v222 offset:56320
	global_load_lds_dwordx4 v[216:217], off
	s_add_i32 m0, s47, 0x2000
	s_add_u32 s54, s54, 0x40080
	v_lshl_add_u64 v[216:217], v[240:241], 0, s[16:17]
	s_addc_u32 s55, s55, 0
	s_add_i32 s47, s68, s58
	global_load_lds_dwordx4 v[216:217], off
	v_lshl_add_u64 v[216:217], s[54:55], 0, v[208:209]
	s_mov_b32 m0, s47
	s_nop 0
	global_load_lds_dwordx4 v[216:217], off
	v_lshl_add_u64 v[216:217], s[54:55], 0, v[204:205]
	s_add_i32 m0, s47, 0x2000
	s_nop 0
	global_load_lds_dwordx4 v[216:217], off
	v_lshl_add_u64 v[216:217], v[242:243], 0, s[16:17]
	s_mov_b32 m0, s65
	s_nop 0
	global_load_lds_dwordx4 v[216:217], off
	v_lshl_add_u64 v[216:217], v[244:245], 0, s[16:17]
	s_mov_b32 m0, s66
	s_nop 0
	global_load_lds_dwordx4 v[216:217], off
	s_waitcnt vmcnt(8)
	s_waitcnt lgkmcnt(0)
	s_barrier
	v_mfma_f32_16x16x32_bf16 v[62:65], v[106:109], v[162:165], v[62:65]
	v_mfma_f32_16x16x32_bf16 v[58:61], v[126:129], v[162:165], v[58:61]
	v_mfma_f32_16x16x32_bf16 v[46:49], v[106:109], v[170:173], v[46:49]
	v_mfma_f32_16x16x32_bf16 v[42:45], v[126:129], v[170:173], v[42:45]
	v_mfma_f32_16x16x32_bf16 v[30:33], v[106:109], v[178:181], v[30:33]
	v_mfma_f32_16x16x32_bf16 v[26:29], v[126:129], v[178:181], v[26:29]
	v_mfma_f32_16x16x32_bf16 v[14:17], v[106:109], v[224:227], v[14:17]
	v_mfma_f32_16x16x32_bf16 v[10:13], v[126:129], v[224:227], v[10:13]
	v_mfma_f32_16x16x32_bf16 v[62:65], v[110:113], v[166:169], v[62:65]
	v_mfma_f32_16x16x32_bf16 v[58:61], v[134:137], v[166:169], v[58:61]
	v_mfma_f32_16x16x32_bf16 v[46:49], v[110:113], v[174:177], v[46:49]
	v_mfma_f32_16x16x32_bf16 v[42:45], v[134:137], v[174:177], v[42:45]
	v_mfma_f32_16x16x32_bf16 v[30:33], v[110:113], v[182:185], v[30:33]
	v_mfma_f32_16x16x32_bf16 v[26:29], v[134:137], v[182:185], v[26:29]
	v_mfma_f32_16x16x32_bf16 v[14:17], v[110:113], v[228:231], v[14:17]
	v_mfma_f32_16x16x32_bf16 v[10:13], v[134:137], v[228:231], v[10:13]
	v_mfma_f32_16x16x32_bf16 v[54:57], v[146:149], v[162:165], v[54:57]
	v_mfma_f32_16x16x32_bf16 v[50:53], v[154:157], v[162:165], v[50:53]
	v_mfma_f32_16x16x32_bf16 v[38:41], v[146:149], v[170:173], v[38:41]
	v_mfma_f32_16x16x32_bf16 v[34:37], v[154:157], v[170:173], v[34:37]
	v_mfma_f32_16x16x32_bf16 v[22:25], v[146:149], v[178:181], v[22:25]
	v_mfma_f32_16x16x32_bf16 v[18:21], v[154:157], v[178:181], v[18:21]
	v_mfma_f32_16x16x32_bf16 v[6:9], v[146:149], v[224:227], v[6:9]
	v_mfma_f32_16x16x32_bf16 v[2:5], v[154:157], v[224:227], v[2:5]
	v_mfma_f32_16x16x32_bf16 v[54:57], v[150:153], v[166:169], v[54:57]
	v_mfma_f32_16x16x32_bf16 v[50:53], v[158:161], v[166:169], v[50:53]
	v_mfma_f32_16x16x32_bf16 v[38:41], v[150:153], v[174:177], v[38:41]
	v_mfma_f32_16x16x32_bf16 v[34:37], v[158:161], v[174:177], v[34:37]
	v_mfma_f32_16x16x32_bf16 v[22:25], v[150:153], v[182:185], v[22:25]
	v_mfma_f32_16x16x32_bf16 v[18:21], v[158:161], v[182:185], v[18:21]
	v_mfma_f32_16x16x32_bf16 v[6:9], v[150:153], v[228:231], v[6:9]
	v_mfma_f32_16x16x32_bf16 v[2:5], v[158:161], v[228:231], v[2:5]
	s_barrier
	s_add_i32 s45, s45, 2
	s_add_u32 s52, s52, 0x100
	s_addc_u32 s53, s53, 0
	s_add_u32 s18, s18, 0x100
	s_addc_u32 s19, s19, 0
	s_cmp_gt_u32 s45, 13
	s_cbranch_scc0 .LBB0_900
	s_and_b64 vcc, exec, s[40:41]
	s_cbranch_vccz .LBB0_903
	s_barrier

.Lrb5_skip:
	s_add_u32 s52, s50, 0xfffc0080
	s_addc_u32 s53, s51, -1
	s_add_i32 s67, 0, 0x10000
	s_cmp_eq_u32 s66, 12
	s_cselect_b32 s55, s45, s53
	s_cselect_b32 s54, s62, s52
	v_add_u32_e32 v0, s67, v144
	s_cselect_b32 s53, s43, s65
	s_cselect_b32 s52, s63, s64
	s_add_i32 s70, 0, 0x14000
	ds_read_b128 v[146:149], v0
	ds_read_b128 v[150:153], v0 offset:1024
	ds_read_b128 v[154:157], v0 offset:2048
	ds_read_b128 v[158:161], v0 offset:3072
	v_add_u32_e32 v0, s70, v144
	ds_read_b128 v[162:165], v0
	ds_read_b128 v[166:169], v0 offset:1024
	ds_read_b128 v[170:173], v0 offset:2048
	ds_read_b128 v[174:177], v0 offset:3072
	s_add_i32 m0, s5, 0xc000
	ds_read_b128 v[178:181], v145
	ds_read_b128 v[182:185], v145 offset:1024
	ds_read_b128 v[204:207], v145 offset:2048
	ds_read_b128 v[208:211], v145 offset:3072
	ds_read_b128 v[212:215], v145 offset:4096
	ds_read_b128 v[220:223], v145 offset:5120
	ds_read_b128 v[224:227], v145 offset:6144
	ds_read_b128 v[228:231], v145 offset:7168
	global_load_lds_dwordx4 v138, s[50:51]
	s_add_i32 m0, s5, 0xe000
	s_nop 0
	global_load_lds_dwordx4 v140, s[50:51]
	s_waitcnt vmcnt(8)
	s_waitcnt lgkmcnt(0)
	s_barrier
	v_mfma_f32_16x16x32_bf16 v[118:121], v[146:149], v[178:181], 0
	v_mfma_f32_16x16x32_bf16 v[114:117], v[154:157], v[178:181], 0
	v_mfma_f32_16x16x32_bf16 v[110:113], v[146:149], v[204:207], 0
	v_mfma_f32_16x16x32_bf16 v[102:105], v[154:157], v[204:207], 0
	v_mfma_f32_16x16x32_bf16 v[94:97], v[146:149], v[212:215], 0
	v_mfma_f32_16x16x32_bf16 v[86:89], v[154:157], v[212:215], 0
	v_mfma_f32_16x16x32_bf16 v[78:81], v[146:149], v[224:227], 0
	v_mfma_f32_16x16x32_bf16 v[70:73], v[154:157], v[224:227], 0
	v_mfma_f32_16x16x32_bf16 v[118:121], v[150:153], v[182:185], v[118:121]
	v_mfma_f32_16x16x32_bf16 v[114:117], v[158:161], v[182:185], v[114:117]
	v_mfma_f32_16x16x32_bf16 v[110:113], v[150:153], v[208:211], v[110:113]
	v_mfma_f32_16x16x32_bf16 v[102:105], v[158:161], v[208:211], v[102:105]
	v_mfma_f32_16x16x32_bf16 v[94:97], v[150:153], v[220:223], v[94:97]
	v_mfma_f32_16x16x32_bf16 v[86:89], v[158:161], v[220:223], v[86:89]
	v_mfma_f32_16x16x32_bf16 v[78:81], v[150:153], v[228:231], v[78:81]
	v_mfma_f32_16x16x32_bf16 v[70:73], v[158:161], v[228:231], v[70:73]
	v_mfma_f32_16x16x32_bf16 v[126:129], v[162:165], v[178:181], 0
	v_mfma_f32_16x16x32_bf16 v[122:125], v[170:173], v[178:181], 0
	v_mfma_f32_16x16x32_bf16 v[106:109], v[162:165], v[204:207], 0
	v_mfma_f32_16x16x32_bf16 v[98:101], v[170:173], v[204:207], 0
	v_mfma_f32_16x16x32_bf16 v[90:93], v[162:165], v[212:215], 0
	v_mfma_f32_16x16x32_bf16 v[82:85], v[170:173], v[212:215], 0
	v_mfma_f32_16x16x32_bf16 v[74:77], v[162:165], v[224:227], 0
	v_mfma_f32_16x16x32_bf16 v[66:69], v[170:173], v[224:227], 0
	v_mfma_f32_16x16x32_bf16 v[126:129], v[166:169], v[182:185], v[126:129]
	v_mfma_f32_16x16x32_bf16 v[122:125], v[174:177], v[182:185], v[122:125]
	v_mfma_f32_16x16x32_bf16 v[106:109], v[166:169], v[208:211], v[106:109]
	v_mfma_f32_16x16x32_bf16 v[98:101], v[174:177], v[208:211], v[98:101]
	v_mfma_f32_16x16x32_bf16 v[90:93], v[166:169], v[220:223], v[90:93]
	v_mfma_f32_16x16x32_bf16 v[82:85], v[174:177], v[220:223], v[82:85]
	v_mfma_f32_16x16x32_bf16 v[74:77], v[166:169], v[228:231], v[74:77]
	v_mfma_f32_16x16x32_bf16 v[66:69], v[174:177], v[228:231], v[66:69]
	s_barrier
	s_add_i32 s67, s67, s4
	s_mov_b32 m0, s67
	ds_read_b128 v[178:181], v145 offset:16384
	ds_read_b128 v[182:185], v145 offset:17408
	ds_read_b128 v[204:207], v145 offset:18432
	ds_read_b128 v[208:211], v145 offset:19456
	ds_read_b128 v[212:215], v145 offset:20480
	ds_read_b128 v[220:223], v145 offset:21504
	ds_read_b128 v[224:227], v145 offset:22528
	ds_read_b128 v[228:231], v145 offset:23552
	global_load_lds_dwordx4 v134, s[52:53]
	s_add_i32 m0, s67, 0x2000
	s_add_u32 s68, s52, 0x40000
	s_addc_u32 s69, s53, 0
	s_add_i32 s67, s70, s4
	global_load_lds_dwordx4 v130, s[52:53]
	s_mov_b32 m0, s67
	s_nop 0
	global_load_lds_dwordx4 v134, s[68:69]
	s_add_i32 m0, s67, 0x2000
	s_nop 0
	global_load_lds_dwordx4 v130, s[68:69]
	s_mov_b32 m0, s5
	s_nop 0
	global_load_lds_dwordx4 v136, s[54:55]
	s_mov_b32 m0, s6
	s_nop 0
	global_load_lds_dwordx4 v132, s[54:55]
	s_waitcnt vmcnt(8)
	s_waitcnt lgkmcnt(0)
	s_barrier
	v_mfma_f32_16x16x32_bf16 v[62:65], v[146:149], v[178:181], 0
	v_mfma_f32_16x16x32_bf16 v[54:57], v[154:157], v[178:181], 0
	v_mfma_f32_16x16x32_bf16 v[46:49], v[146:149], v[204:207], 0
	v_mfma_f32_16x16x32_bf16 v[38:41], v[154:157], v[204:207], 0
	v_mfma_f32_16x16x32_bf16 v[30:33], v[146:149], v[212:215], 0
	v_mfma_f32_16x16x32_bf16 v[22:25], v[154:157], v[212:215], 0
	v_mfma_f32_16x16x32_bf16 v[14:17], v[146:149], v[224:227], 0
	v_mfma_f32_16x16x32_bf16 v[6:9], v[154:157], v[224:227], 0
	v_mfma_f32_16x16x32_bf16 v[62:65], v[150:153], v[182:185], v[62:65]
	v_mfma_f32_16x16x32_bf16 v[54:57], v[158:161], v[182:185], v[54:57]
	v_mfma_f32_16x16x32_bf16 v[46:49], v[150:153], v[208:211], v[46:49]
	v_mfma_f32_16x16x32_bf16 v[38:41], v[158:161], v[208:211], v[38:41]
	v_mfma_f32_16x16x32_bf16 v[30:33], v[150:153], v[220:223], v[30:33]
	v_mfma_f32_16x16x32_bf16 v[22:25], v[158:161], v[220:223], v[22:25]
	v_mfma_f32_16x16x32_bf16 v[14:17], v[150:153], v[228:231], v[14:17]
	v_mfma_f32_16x16x32_bf16 v[6:9], v[158:161], v[228:231], v[6:9]
	v_mfma_f32_16x16x32_bf16 v[58:61], v[162:165], v[178:181], 0
	v_mfma_f32_16x16x32_bf16 v[50:53], v[170:173], v[178:181], 0
	v_mfma_f32_16x16x32_bf16 v[42:45], v[162:165], v[204:207], 0
	v_mfma_f32_16x16x32_bf16 v[34:37], v[170:173], v[204:207], 0
	v_mfma_f32_16x16x32_bf16 v[26:29], v[162:165], v[212:215], 0
	v_mfma_f32_16x16x32_bf16 v[18:21], v[170:173], v[212:215], 0
	v_mfma_f32_16x16x32_bf16 v[10:13], v[162:165], v[224:227], 0
	v_mfma_f32_16x16x32_bf16 v[2:5], v[170:173], v[224:227], 0
	v_mfma_f32_16x16x32_bf16 v[58:61], v[166:169], v[182:185], v[58:61]
	v_mfma_f32_16x16x32_bf16 v[50:53], v[174:177], v[182:185], v[50:53]
	v_mfma_f32_16x16x32_bf16 v[42:45], v[166:169], v[208:211], v[42:45]
	v_mfma_f32_16x16x32_bf16 v[34:37], v[174:177], v[208:211], v[34:37]
	v_mfma_f32_16x16x32_bf16 v[26:29], v[166:169], v[220:223], v[26:29]
	v_mfma_f32_16x16x32_bf16 v[18:21], v[174:177], v[220:223], v[18:21]
	v_mfma_f32_16x16x32_bf16 v[10:13], v[166:169], v[228:231], v[10:13]
	v_mfma_f32_16x16x32_bf16 v[2:5], v[174:177], v[228:231], v[2:5]
	s_barrier
	s_add_i32 s67, 0, 0x18000
	v_add_u32_e32 v0, s67, v144
	s_add_i32 s68, 0, 0x1c000
	ds_read_b128 v[146:149], v0
	ds_read_b128 v[150:153], v0 offset:1024
	ds_read_b128 v[154:157], v0 offset:2048
	ds_read_b128 v[158:161], v0 offset:3072
	v_add_u32_e32 v0, s68, v144
	ds_read_b128 v[162:165], v0
	ds_read_b128 v[166:169], v0 offset:1024
	ds_read_b128 v[170:173], v0 offset:2048
	ds_read_b128 v[174:177], v0 offset:3072
	s_add_u32 s54, s54, 0x40000
	s_addc_u32 s55, s55, 0
	s_mov_b32 m0, s7
	ds_read_b128 v[178:181], v145 offset:32768
	ds_read_b128 v[182:185], v145 offset:33792
	ds_read_b128 v[204:207], v145 offset:34816
	ds_read_b128 v[208:211], v145 offset:35840
	ds_read_b128 v[212:215], v145 offset:36864
	ds_read_b128 v[220:223], v145 offset:37888
	ds_read_b128 v[224:227], v145 offset:38912
	ds_read_b128 v[228:231], v145 offset:39936
	global_load_lds_dwordx4 v136, s[54:55]
	s_mov_b32 m0, s56
	s_nop 0
	global_load_lds_dwordx4 v132, s[54:55]
	s_waitcnt vmcnt(8)
	s_waitcnt lgkmcnt(0)
	s_barrier
	v_mfma_f32_16x16x32_bf16 v[118:121], v[146:149], v[178:181], v[118:121]
	v_mfma_f32_16x16x32_bf16 v[114:117], v[154:157], v[178:181], v[114:117]
	v_mfma_f32_16x16x32_bf16 v[110:113], v[146:149], v[204:207], v[110:113]
	v_mfma_f32_16x16x32_bf16 v[102:105], v[154:157], v[204:207], v[102:105]
	v_mfma_f32_16x16x32_bf16 v[94:97], v[146:149], v[212:215], v[94:97]
	v_mfma_f32_16x16x32_bf16 v[86:89], v[154:157], v[212:215], v[86:89]
	v_mfma_f32_16x16x32_bf16 v[78:81], v[146:149], v[224:227], v[78:81]
	v_mfma_f32_16x16x32_bf16 v[70:73], v[154:157], v[224:227], v[70:73]
	v_mfma_f32_16x16x32_bf16 v[118:121], v[150:153], v[182:185], v[118:121]
	v_mfma_f32_16x16x32_bf16 v[114:117], v[158:161], v[182:185], v[114:117]
	v_mfma_f32_16x16x32_bf16 v[110:113], v[150:153], v[208:211], v[110:113]
	v_mfma_f32_16x16x32_bf16 v[102:105], v[158:161], v[208:211], v[102:105]
	v_mfma_f32_16x16x32_bf16 v[94:97], v[150:153], v[220:223], v[94:97]
	v_mfma_f32_16x16x32_bf16 v[86:89], v[158:161], v[220:223], v[86:89]
	v_mfma_f32_16x16x32_bf16 v[78:81], v[150:153], v[228:231], v[78:81]
	v_mfma_f32_16x16x32_bf16 v[70:73], v[158:161], v[228:231], v[70:73]
	v_mfma_f32_16x16x32_bf16 v[126:129], v[162:165], v[178:181], v[126:129]
	v_mfma_f32_16x16x32_bf16 v[122:125], v[170:173], v[178:181], v[122:125]
	v_mfma_f32_16x16x32_bf16 v[106:109], v[162:165], v[204:207], v[106:109]
	v_mfma_f32_16x16x32_bf16 v[98:101], v[170:173], v[204:207], v[98:101]
	v_mfma_f32_16x16x32_bf16 v[90:93], v[162:165], v[212:215], v[90:93]
	v_mfma_f32_16x16x32_bf16 v[82:85], v[170:173], v[212:215], v[82:85]
	v_mfma_f32_16x16x32_bf16 v[74:77], v[162:165], v[224:227], v[74:77]
	v_mfma_f32_16x16x32_bf16 v[66:69], v[170:173], v[224:227], v[66:69]
	v_mfma_f32_16x16x32_bf16 v[126:129], v[166:169], v[182:185], v[126:129]
	v_mfma_f32_16x16x32_bf16 v[122:125], v[174:177], v[182:185], v[122:125]
	v_mfma_f32_16x16x32_bf16 v[106:109], v[166:169], v[208:211], v[106:109]
	v_mfma_f32_16x16x32_bf16 v[98:101], v[174:177], v[208:211], v[98:101]
	v_mfma_f32_16x16x32_bf16 v[90:93], v[166:169], v[220:223], v[90:93]
	v_mfma_f32_16x16x32_bf16 v[82:85], v[174:177], v[220:223], v[82:85]
	v_mfma_f32_16x16x32_bf16 v[74:77], v[166:169], v[228:231], v[74:77]
	v_mfma_f32_16x16x32_bf16 v[66:69], v[174:177], v[228:231], v[66:69]
	s_barrier
	s_add_i32 s69, s67, s4
	s_add_u32 s52, s52, 0x80
	s_addc_u32 s53, s53, 0
	s_mov_b32 m0, s69
	ds_read_b128 v[178:181], v145 offset:49152
	ds_read_b128 v[182:185], v145 offset:50176
	ds_read_b128 v[204:207], v145 offset:51200
	ds_read_b128 v[208:211], v145 offset:52224
	ds_read_b128 v[212:215], v145 offset:53248
	ds_read_b128 v[220:223], v145 offset:54272
	ds_read_b128 v[224:227], v145 offset:55296
	ds_read_b128 v[228:231], v145 offset:56320
	global_load_lds_dwordx4 v134, s[52:53]
	s_add_i32 m0, s69, 0x2000
	s_add_i32 s69, s68, s4
	global_load_lds_dwordx4 v130, s[52:53]
	s_add_u32 s52, s52, 0x40000
	s_addc_u32 s53, s53, 0
	s_mov_b32 m0, s69
	s_sub_u32 s54, s54, 0x3ff80
	global_load_lds_dwordx4 v134, s[52:53]
	s_subb_u32 s55, s55, 0
	s_add_i32 m0, s69, 0x2000
	s_nop 0
	global_load_lds_dwordx4 v130, s[52:53]
	s_mov_b32 m0, s59
	s_nop 0
	global_load_lds_dwordx4 v136, s[54:55]
	s_mov_b32 m0, s60
	s_nop 0
	global_load_lds_dwordx4 v132, s[54:55]
	s_waitcnt vmcnt(8)
	s_waitcnt lgkmcnt(0)
	s_barrier
	v_mfma_f32_16x16x32_bf16 v[62:65], v[146:149], v[178:181], v[62:65]
	v_mfma_f32_16x16x32_bf16 v[54:57], v[154:157], v[178:181], v[54:57]
	v_mfma_f32_16x16x32_bf16 v[46:49], v[146:149], v[204:207], v[46:49]
	v_mfma_f32_16x16x32_bf16 v[38:41], v[154:157], v[204:207], v[38:41]
	v_mfma_f32_16x16x32_bf16 v[30:33], v[146:149], v[212:215], v[30:33]
	v_mfma_f32_16x16x32_bf16 v[22:25], v[154:157], v[212:215], v[22:25]
	v_mfma_f32_16x16x32_bf16 v[14:17], v[146:149], v[224:227], v[14:17]
	v_mfma_f32_16x16x32_bf16 v[6:9], v[154:157], v[224:227], v[6:9]
	v_mfma_f32_16x16x32_bf16 v[62:65], v[150:153], v[182:185], v[62:65]
	v_mfma_f32_16x16x32_bf16 v[54:57], v[158:161], v[182:185], v[54:57]
	v_mfma_f32_16x16x32_bf16 v[46:49], v[150:153], v[208:211], v[46:49]
	v_mfma_f32_16x16x32_bf16 v[38:41], v[158:161], v[208:211], v[38:41]
	v_mfma_f32_16x16x32_bf16 v[30:33], v[150:153], v[220:223], v[30:33]
	v_mfma_f32_16x16x32_bf16 v[22:25], v[158:161], v[220:223], v[22:25]
	v_mfma_f32_16x16x32_bf16 v[14:17], v[150:153], v[228:231], v[14:17]
	v_mfma_f32_16x16x32_bf16 v[6:9], v[158:161], v[228:231], v[6:9]
	v_mfma_f32_16x16x32_bf16 v[58:61], v[162:165], v[178:181], v[58:61]
	v_mfma_f32_16x16x32_bf16 v[50:53], v[170:173], v[178:181], v[50:53]
	v_mfma_f32_16x16x32_bf16 v[42:45], v[162:165], v[204:207], v[42:45]
	v_mfma_f32_16x16x32_bf16 v[34:37], v[170:173], v[204:207], v[34:37]
	v_mfma_f32_16x16x32_bf16 v[26:29], v[162:165], v[212:215], v[26:29]
	v_mfma_f32_16x16x32_bf16 v[18:21], v[170:173], v[212:215], v[18:21]
	v_mfma_f32_16x16x32_bf16 v[10:13], v[162:165], v[224:227], v[10:13]
	v_mfma_f32_16x16x32_bf16 v[2:5], v[170:173], v[224:227], v[2:5]
	v_mfma_f32_16x16x32_bf16 v[58:61], v[166:169], v[182:185], v[58:61]
	v_mfma_f32_16x16x32_bf16 v[50:53], v[174:177], v[182:185], v[50:53]
	v_mfma_f32_16x16x32_bf16 v[42:45], v[166:169], v[208:211], v[42:45]
	v_mfma_f32_16x16x32_bf16 v[34:37], v[174:177], v[208:211], v[34:37]
	v_mfma_f32_16x16x32_bf16 v[26:29], v[166:169], v[220:223], v[26:29]
	v_mfma_f32_16x16x32_bf16 v[18:21], v[174:177], v[220:223], v[18:21]
	v_mfma_f32_16x16x32_bf16 v[10:13], v[166:169], v[228:231], v[10:13]
	v_mfma_f32_16x16x32_bf16 v[2:5], v[174:177], v[228:231], v[2:5]
	s_barrier
	s_add_i32 s66, s66, 2
	s_add_u32 s50, s50, 0x100
	s_addc_u32 s51, s51, 0
	s_add_u32 s64, s64, 0x100
	s_addc_u32 s65, s65, 0
	s_cmp_gt_u32 s66, 13
.LBB0_997:
	s_add_u32 s52, s50, 0xfffc0080
	s_addc_u32 s53, s51, -1
	s_add_i32 s67, 0, 0x10000
	s_cmp_eq_u32 s66, 12
	s_cselect_b32 s55, s45, s53
	s_cselect_b32 s54, s62, s52
	v_add_u32_e32 v0, s67, v144
	s_cselect_b32 s53, s43, s65
	s_cselect_b32 s52, s63, s64
	s_add_i32 s70, 0, 0x14000
	ds_read_b128 v[146:149], v0
	ds_read_b128 v[150:153], v0 offset:1024
	ds_read_b128 v[154:157], v0 offset:2048
	ds_read_b128 v[158:161], v0 offset:3072
	v_add_u32_e32 v0, s70, v144
	ds_read_b128 v[162:165], v0
	ds_read_b128 v[166:169], v0 offset:1024
	ds_read_b128 v[170:173], v0 offset:2048
	ds_read_b128 v[174:177], v0 offset:3072
	s_add_i32 m0, s5, 0xc000
	ds_read_b128 v[178:181], v145
	ds_read_b128 v[182:185], v145 offset:1024
	ds_read_b128 v[204:207], v145 offset:2048
	ds_read_b128 v[208:211], v145 offset:3072
	ds_read_b128 v[212:215], v145 offset:4096
	ds_read_b128 v[220:223], v145 offset:5120
	ds_read_b128 v[224:227], v145 offset:6144
	ds_read_b128 v[228:231], v145 offset:7168
	global_load_lds_dwordx4 v138, s[50:51]
	s_add_i32 m0, s5, 0xe000
	s_nop 0
	global_load_lds_dwordx4 v140, s[50:51]
	s_waitcnt vmcnt(8)
	s_waitcnt lgkmcnt(0)
	s_barrier
	v_mfma_f32_16x16x32_bf16 v[118:121], v[146:149], v[178:181], v[118:121]
	v_mfma_f32_16x16x32_bf16 v[114:117], v[154:157], v[178:181], v[114:117]
	v_mfma_f32_16x16x32_bf16 v[110:113], v[146:149], v[204:207], v[110:113]
	v_mfma_f32_16x16x32_bf16 v[102:105], v[154:157], v[204:207], v[102:105]
	v_mfma_f32_16x16x32_bf16 v[94:97], v[146:149], v[212:215], v[94:97]
	v_mfma_f32_16x16x32_bf16 v[86:89], v[154:157], v[212:215], v[86:89]
	v_mfma_f32_16x16x32_bf16 v[78:81], v[146:149], v[224:227], v[78:81]
	v_mfma_f32_16x16x32_bf16 v[70:73], v[154:157], v[224:227], v[70:73]
	v_mfma_f32_16x16x32_bf16 v[118:121], v[150:153], v[182:185], v[118:121]
	v_mfma_f32_16x16x32_bf16 v[114:117], v[158:161], v[182:185], v[114:117]
	v_mfma_f32_16x16x32_bf16 v[110:113], v[150:153], v[208:211], v[110:113]
	v_mfma_f32_16x16x32_bf16 v[102:105], v[158:161], v[208:211], v[102:105]
	v_mfma_f32_16x16x32_bf16 v[94:97], v[150:153], v[220:223], v[94:97]
	v_mfma_f32_16x16x32_bf16 v[86:89], v[158:161], v[220:223], v[86:89]
	v_mfma_f32_16x16x32_bf16 v[78:81], v[150:153], v[228:231], v[78:81]
	v_mfma_f32_16x16x32_bf16 v[70:73], v[158:161], v[228:231], v[70:73]
	v_mfma_f32_16x16x32_bf16 v[126:129], v[162:165], v[178:181], v[126:129]
	v_mfma_f32_16x16x32_bf16 v[122:125], v[170:173], v[178:181], v[122:125]
	v_mfma_f32_16x16x32_bf16 v[106:109], v[162:165], v[204:207], v[106:109]
	v_mfma_f32_16x16x32_bf16 v[98:101], v[170:173], v[204:207], v[98:101]
	v_mfma_f32_16x16x32_bf16 v[90:93], v[162:165], v[212:215], v[90:93]
	v_mfma_f32_16x16x32_bf16 v[82:85], v[170:173], v[212:215], v[82:85]
	v_mfma_f32_16x16x32_bf16 v[74:77], v[162:165], v[224:227], v[74:77]
	v_mfma_f32_16x16x32_bf16 v[66:69], v[170:173], v[224:227], v[66:69]
	v_mfma_f32_16x16x32_bf16 v[126:129], v[166:169], v[182:185], v[126:129]
	v_mfma_f32_16x16x32_bf16 v[122:125], v[174:177], v[182:185], v[122:125]
	v_mfma_f32_16x16x32_bf16 v[106:109], v[166:169], v[208:211], v[106:109]
	v_mfma_f32_16x16x32_bf16 v[98:101], v[174:177], v[208:211], v[98:101]
	v_mfma_f32_16x16x32_bf16 v[90:93], v[166:169], v[220:223], v[90:93]
	v_mfma_f32_16x16x32_bf16 v[82:85], v[174:177], v[220:223], v[82:85]
	v_mfma_f32_16x16x32_bf16 v[74:77], v[166:169], v[228:231], v[74:77]
	v_mfma_f32_16x16x32_bf16 v[66:69], v[174:177], v[228:231], v[66:69]
	s_barrier
	s_add_i32 s67, s67, s4
	s_mov_b32 m0, s67
	ds_read_b128 v[178:181], v145 offset:16384
	ds_read_b128 v[182:185], v145 offset:17408
	ds_read_b128 v[204:207], v145 offset:18432
	ds_read_b128 v[208:211], v145 offset:19456
	ds_read_b128 v[212:215], v145 offset:20480
	ds_read_b128 v[220:223], v145 offset:21504
	ds_read_b128 v[224:227], v145 offset:22528
	ds_read_b128 v[228:231], v145 offset:23552
	global_load_lds_dwordx4 v134, s[52:53]
	s_add_i32 m0, s67, 0x2000
	s_add_u32 s68, s52, 0x40000
	s_addc_u32 s69, s53, 0
	s_add_i32 s67, s70, s4
	global_load_lds_dwordx4 v130, s[52:53]
	s_mov_b32 m0, s67
	s_nop 0
	global_load_lds_dwordx4 v134, s[68:69]
	s_add_i32 m0, s67, 0x2000
	s_nop 0
	global_load_lds_dwordx4 v130, s[68:69]
	s_mov_b32 m0, s5
	s_nop 0
	global_load_lds_dwordx4 v136, s[54:55]
	s_mov_b32 m0, s6
	s_nop 0
	global_load_lds_dwordx4 v132, s[54:55]
	s_waitcnt vmcnt(8)
	s_waitcnt lgkmcnt(0)
	s_barrier
	v_mfma_f32_16x16x32_bf16 v[62:65], v[146:149], v[178:181], v[62:65]
	v_mfma_f32_16x16x32_bf16 v[54:57], v[154:157], v[178:181], v[54:57]
	v_mfma_f32_16x16x32_bf16 v[46:49], v[146:149], v[204:207], v[46:49]
	v_mfma_f32_16x16x32_bf16 v[38:41], v[154:157], v[204:207], v[38:41]
	v_mfma_f32_16x16x32_bf16 v[30:33], v[146:149], v[212:215], v[30:33]
	v_mfma_f32_16x16x32_bf16 v[22:25], v[154:157], v[212:215], v[22:25]
	v_mfma_f32_16x16x32_bf16 v[14:17], v[146:149], v[224:227], v[14:17]
	v_mfma_f32_16x16x32_bf16 v[6:9], v[154:157], v[224:227], v[6:9]
	v_mfma_f32_16x16x32_bf16 v[62:65], v[150:153], v[182:185], v[62:65]
	v_mfma_f32_16x16x32_bf16 v[54:57], v[158:161], v[182:185], v[54:57]
	v_mfma_f32_16x16x32_bf16 v[46:49], v[150:153], v[208:211], v[46:49]
	v_mfma_f32_16x16x32_bf16 v[38:41], v[158:161], v[208:211], v[38:41]
	v_mfma_f32_16x16x32_bf16 v[30:33], v[150:153], v[220:223], v[30:33]
	v_mfma_f32_16x16x32_bf16 v[22:25], v[158:161], v[220:223], v[22:25]
	v_mfma_f32_16x16x32_bf16 v[14:17], v[150:153], v[228:231], v[14:17]
	v_mfma_f32_16x16x32_bf16 v[6:9], v[158:161], v[228:231], v[6:9]
	v_mfma_f32_16x16x32_bf16 v[58:61], v[162:165], v[178:181], v[58:61]
	v_mfma_f32_16x16x32_bf16 v[50:53], v[170:173], v[178:181], v[50:53]
	v_mfma_f32_16x16x32_bf16 v[42:45], v[162:165], v[204:207], v[42:45]
	v_mfma_f32_16x16x32_bf16 v[34:37], v[170:173], v[204:207], v[34:37]
	v_mfma_f32_16x16x32_bf16 v[26:29], v[162:165], v[212:215], v[26:29]
	v_mfma_f32_16x16x32_bf16 v[18:21], v[170:173], v[212:215], v[18:21]
	v_mfma_f32_16x16x32_bf16 v[10:13], v[162:165], v[224:227], v[10:13]
	v_mfma_f32_16x16x32_bf16 v[2:5], v[170:173], v[224:227], v[2:5]
	v_mfma_f32_16x16x32_bf16 v[58:61], v[166:169], v[182:185], v[58:61]
	v_mfma_f32_16x16x32_bf16 v[50:53], v[174:177], v[182:185], v[50:53]
	v_mfma_f32_16x16x32_bf16 v[42:45], v[166:169], v[208:211], v[42:45]
	v_mfma_f32_16x16x32_bf16 v[34:37], v[174:177], v[208:211], v[34:37]
	v_mfma_f32_16x16x32_bf16 v[26:29], v[166:169], v[220:223], v[26:29]
	v_mfma_f32_16x16x32_bf16 v[18:21], v[174:177], v[220:223], v[18:21]
	v_mfma_f32_16x16x32_bf16 v[10:13], v[166:169], v[228:231], v[10:13]
	v_mfma_f32_16x16x32_bf16 v[2:5], v[174:177], v[228:231], v[2:5]
	s_barrier
	s_add_i32 s67, 0, 0x18000
	v_add_u32_e32 v0, s67, v144
	s_add_i32 s68, 0, 0x1c000
	ds_read_b128 v[146:149], v0
	ds_read_b128 v[150:153], v0 offset:1024
	ds_read_b128 v[154:157], v0 offset:2048
	ds_read_b128 v[158:161], v0 offset:3072
	v_add_u32_e32 v0, s68, v144
	ds_read_b128 v[162:165], v0
	ds_read_b128 v[166:169], v0 offset:1024
	ds_read_b128 v[170:173], v0 offset:2048
	ds_read_b128 v[174:177], v0 offset:3072
	s_add_u32 s54, s54, 0x40000
	s_addc_u32 s55, s55, 0
	s_mov_b32 m0, s7
	ds_read_b128 v[178:181], v145 offset:32768
	ds_read_b128 v[182:185], v145 offset:33792
	ds_read_b128 v[204:207], v145 offset:34816
	ds_read_b128 v[208:211], v145 offset:35840
	ds_read_b128 v[212:215], v145 offset:36864
	ds_read_b128 v[220:223], v145 offset:37888
	ds_read_b128 v[224:227], v145 offset:38912
	ds_read_b128 v[228:231], v145 offset:39936
	global_load_lds_dwordx4 v136, s[54:55]
	s_mov_b32 m0, s56
	s_nop 0
	global_load_lds_dwordx4 v132, s[54:55]
	s_waitcnt vmcnt(8)
	s_waitcnt lgkmcnt(0)
	s_barrier
	v_mfma_f32_16x16x32_bf16 v[118:121], v[146:149], v[178:181], v[118:121]
	v_mfma_f32_16x16x32_bf16 v[114:117], v[154:157], v[178:181], v[114:117]
	v_mfma_f32_16x16x32_bf16 v[110:113], v[146:149], v[204:207], v[110:113]
	v_mfma_f32_16x16x32_bf16 v[102:105], v[154:157], v[204:207], v[102:105]
	v_mfma_f32_16x16x32_bf16 v[94:97], v[146:149], v[212:215], v[94:97]
	v_mfma_f32_16x16x32_bf16 v[86:89], v[154:157], v[212:215], v[86:89]
	v_mfma_f32_16x16x32_bf16 v[78:81], v[146:149], v[224:227], v[78:81]
	v_mfma_f32_16x16x32_bf16 v[70:73], v[154:157], v[224:227], v[70:73]
	v_mfma_f32_16x16x32_bf16 v[118:121], v[150:153], v[182:185], v[118:121]
	v_mfma_f32_16x16x32_bf16 v[114:117], v[158:161], v[182:185], v[114:117]
	v_mfma_f32_16x16x32_bf16 v[110:113], v[150:153], v[208:211], v[110:113]
	v_mfma_f32_16x16x32_bf16 v[102:105], v[158:161], v[208:211], v[102:105]
	v_mfma_f32_16x16x32_bf16 v[94:97], v[150:153], v[220:223], v[94:97]
	v_mfma_f32_16x16x32_bf16 v[86:89], v[158:161], v[220:223], v[86:89]
	v_mfma_f32_16x16x32_bf16 v[78:81], v[150:153], v[228:231], v[78:81]
	v_mfma_f32_16x16x32_bf16 v[70:73], v[158:161], v[228:231], v[70:73]
	v_mfma_f32_16x16x32_bf16 v[126:129], v[162:165], v[178:181], v[126:129]
	v_mfma_f32_16x16x32_bf16 v[122:125], v[170:173], v[178:181], v[122:125]
	v_mfma_f32_16x16x32_bf16 v[106:109], v[162:165], v[204:207], v[106:109]
	v_mfma_f32_16x16x32_bf16 v[98:101], v[170:173], v[204:207], v[98:101]
	v_mfma_f32_16x16x32_bf16 v[90:93], v[162:165], v[212:215], v[90:93]
	v_mfma_f32_16x16x32_bf16 v[82:85], v[170:173], v[212:215], v[82:85]
	v_mfma_f32_16x16x32_bf16 v[74:77], v[162:165], v[224:227], v[74:77]
	v_mfma_f32_16x16x32_bf16 v[66:69], v[170:173], v[224:227], v[66:69]
	v_mfma_f32_16x16x32_bf16 v[126:129], v[166:169], v[182:185], v[126:129]
	v_mfma_f32_16x16x32_bf16 v[122:125], v[174:177], v[182:185], v[122:125]
	v_mfma_f32_16x16x32_bf16 v[106:109], v[166:169], v[208:211], v[106:109]
	v_mfma_f32_16x16x32_bf16 v[98:101], v[174:177], v[208:211], v[98:101]
	v_mfma_f32_16x16x32_bf16 v[90:93], v[166:169], v[220:223], v[90:93]
	v_mfma_f32_16x16x32_bf16 v[82:85], v[174:177], v[220:223], v[82:85]
	v_mfma_f32_16x16x32_bf16 v[74:77], v[166:169], v[228:231], v[74:77]
	v_mfma_f32_16x16x32_bf16 v[66:69], v[174:177], v[228:231], v[66:69]
	s_barrier
	s_add_i32 s69, s67, s4
	s_add_u32 s52, s52, 0x80
	s_addc_u32 s53, s53, 0
	s_mov_b32 m0, s69
	ds_read_b128 v[178:181], v145 offset:49152
	ds_read_b128 v[182:185], v145 offset:50176
	ds_read_b128 v[204:207], v145 offset:51200
	ds_read_b128 v[208:211], v145 offset:52224
	ds_read_b128 v[212:215], v145 offset:53248
	ds_read_b128 v[220:223], v145 offset:54272
	ds_read_b128 v[224:227], v145 offset:55296
	ds_read_b128 v[228:231], v145 offset:56320
	global_load_lds_dwordx4 v134, s[52:53]
	s_add_i32 m0, s69, 0x2000
	s_add_i32 s69, s68, s4
	global_load_lds_dwordx4 v130, s[52:53]
	s_add_u32 s52, s52, 0x40000
	s_addc_u32 s53, s53, 0
	s_mov_b32 m0, s69
	s_sub_u32 s54, s54, 0x3ff80
	global_load_lds_dwordx4 v134, s[52:53]
	s_subb_u32 s55, s55, 0
	s_add_i32 m0, s69, 0x2000
	s_nop 0
	global_load_lds_dwordx4 v130, s[52:53]
	s_mov_b32 m0, s59
	s_nop 0
	global_load_lds_dwordx4 v136, s[54:55]
	s_mov_b32 m0, s60
	s_nop 0
	global_load_lds_dwordx4 v132, s[54:55]
	s_waitcnt vmcnt(8)
	s_waitcnt lgkmcnt(0)
	s_barrier
	v_mfma_f32_16x16x32_bf16 v[62:65], v[146:149], v[178:181], v[62:65]
	v_mfma_f32_16x16x32_bf16 v[54:57], v[154:157], v[178:181], v[54:57]
	v_mfma_f32_16x16x32_bf16 v[46:49], v[146:149], v[204:207], v[46:49]
	v_mfma_f32_16x16x32_bf16 v[38:41], v[154:157], v[204:207], v[38:41]
	v_mfma_f32_16x16x32_bf16 v[30:33], v[146:149], v[212:215], v[30:33]
	v_mfma_f32_16x16x32_bf16 v[22:25], v[154:157], v[212:215], v[22:25]
	v_mfma_f32_16x16x32_bf16 v[14:17], v[146:149], v[224:227], v[14:17]
	v_mfma_f32_16x16x32_bf16 v[6:9], v[154:157], v[224:227], v[6:9]
	v_mfma_f32_16x16x32_bf16 v[62:65], v[150:153], v[182:185], v[62:65]
	v_mfma_f32_16x16x32_bf16 v[54:57], v[158:161], v[182:185], v[54:57]
	v_mfma_f32_16x16x32_bf16 v[46:49], v[150:153], v[208:211], v[46:49]
	v_mfma_f32_16x16x32_bf16 v[38:41], v[158:161], v[208:211], v[38:41]
	v_mfma_f32_16x16x32_bf16 v[30:33], v[150:153], v[220:223], v[30:33]
	v_mfma_f32_16x16x32_bf16 v[22:25], v[158:161], v[220:223], v[22:25]
	v_mfma_f32_16x16x32_bf16 v[14:17], v[150:153], v[228:231], v[14:17]
	v_mfma_f32_16x16x32_bf16 v[6:9], v[158:161], v[228:231], v[6:9]
	v_mfma_f32_16x16x32_bf16 v[58:61], v[162:165], v[178:181], v[58:61]
	v_mfma_f32_16x16x32_bf16 v[50:53], v[170:173], v[178:181], v[50:53]
	v_mfma_f32_16x16x32_bf16 v[42:45], v[162:165], v[204:207], v[42:45]
	v_mfma_f32_16x16x32_bf16 v[34:37], v[170:173], v[204:207], v[34:37]
	v_mfma_f32_16x16x32_bf16 v[26:29], v[162:165], v[212:215], v[26:29]
	v_mfma_f32_16x16x32_bf16 v[18:21], v[170:173], v[212:215], v[18:21]
	v_mfma_f32_16x16x32_bf16 v[10:13], v[162:165], v[224:227], v[10:13]
	v_mfma_f32_16x16x32_bf16 v[2:5], v[170:173], v[224:227], v[2:5]
	v_mfma_f32_16x16x32_bf16 v[58:61], v[166:169], v[182:185], v[58:61]
	v_mfma_f32_16x16x32_bf16 v[50:53], v[174:177], v[182:185], v[50:53]
	v_mfma_f32_16x16x32_bf16 v[42:45], v[166:169], v[208:211], v[42:45]
	v_mfma_f32_16x16x32_bf16 v[34:37], v[174:177], v[208:211], v[34:37]
	v_mfma_f32_16x16x32_bf16 v[26:29], v[166:169], v[220:223], v[26:29]
	v_mfma_f32_16x16x32_bf16 v[18:21], v[174:177], v[220:223], v[18:21]
	v_mfma_f32_16x16x32_bf16 v[10:13], v[166:169], v[228:231], v[10:13]
	v_mfma_f32_16x16x32_bf16 v[2:5], v[174:177], v[228:231], v[2:5]
	s_barrier
	s_add_i32 s66, s66, 2
	s_add_u32 s50, s50, 0x100
	s_addc_u32 s51, s51, 0
	s_add_u32 s64, s64, 0x100
	s_addc_u32 s65, s65, 0
	s_cmp_gt_u32 s66, 13
	s_cbranch_scc0 .LBB0_997
	s_and_b64 vcc, exec, s[40:41]
	s_cbranch_vccz .LBB0_1000
	s_barrier

.Lrb6_skip:
	s_add_u32 s0, s44, 0x100
	s_addc_u32 s1, s45, 0
	s_add_i32 s63, 0, 0x10000
	s_cmp_eq_u32 s62, 40
	s_cselect_b32 s51, s41, s1
	s_cselect_b32 s50, s40, s0
	v_add_u32_e32 v0, s63, v221
	s_cselect_b32 s49, s43, s47
	s_cselect_b32 s48, s42, s7
	s_add_i32 s64, 0, 0x14000
	ds_read_b128 v[106:109], v0
	ds_read_b128 v[110:113], v0 offset:1024
	ds_read_b128 v[126:129], v0 offset:2048
	ds_read_b128 v[134:137], v0 offset:3072
	v_add_u32_e32 v0, s64, v221
	ds_read_b128 v[146:149], v0
	ds_read_b128 v[150:153], v0 offset:1024
	ds_read_b128 v[154:157], v0 offset:2048
	ds_read_b128 v[158:161], v0 offset:3072
	v_lshl_add_u64 v[216:217], s[44:45], 0, v[212:213]
	s_add_i32 m0, s53, 0xc000
	ds_read_b128 v[162:165], v222
	ds_read_b128 v[166:169], v222 offset:1024
	ds_read_b128 v[170:173], v222 offset:2048
	ds_read_b128 v[174:177], v222 offset:3072
	ds_read_b128 v[178:181], v222 offset:4096
	ds_read_b128 v[182:185], v222 offset:5120
	ds_read_b128 v[224:227], v222 offset:6144
	ds_read_b128 v[228:231], v222 offset:7168
	global_load_lds_dwordx4 v[216:217], off
	v_lshl_add_u64 v[216:217], s[44:45], 0, v[214:215]
	s_add_i32 m0, s53, 0xe000
	s_nop 0
	global_load_lds_dwordx4 v[216:217], off
	s_waitcnt vmcnt(8)
	s_waitcnt lgkmcnt(0)
	s_barrier
	v_mfma_f32_16x16x32_bf16 v[142:145], v[106:109], v[162:165], 0
	v_mfma_f32_16x16x32_bf16 v[138:141], v[126:129], v[162:165], 0
	v_mfma_f32_16x16x32_bf16 v[118:121], v[106:109], v[170:173], 0
	v_mfma_f32_16x16x32_bf16 v[114:117], v[126:129], v[170:173], 0
	v_mfma_f32_16x16x32_bf16 v[94:97], v[106:109], v[178:181], 0
	v_mfma_f32_16x16x32_bf16 v[90:93], v[126:129], v[178:181], 0
	v_mfma_f32_16x16x32_bf16 v[78:81], v[106:109], v[224:227], 0
	v_mfma_f32_16x16x32_bf16 v[74:77], v[126:129], v[224:227], 0
	v_mfma_f32_16x16x32_bf16 v[142:145], v[110:113], v[166:169], v[142:145]
	v_mfma_f32_16x16x32_bf16 v[138:141], v[134:137], v[166:169], v[138:141]
	v_mfma_f32_16x16x32_bf16 v[118:121], v[110:113], v[174:177], v[118:121]
	v_mfma_f32_16x16x32_bf16 v[114:117], v[134:137], v[174:177], v[114:117]
	v_mfma_f32_16x16x32_bf16 v[94:97], v[110:113], v[182:185], v[94:97]
	v_mfma_f32_16x16x32_bf16 v[90:93], v[134:137], v[182:185], v[90:93]
	v_mfma_f32_16x16x32_bf16 v[78:81], v[110:113], v[228:231], v[78:81]
	v_mfma_f32_16x16x32_bf16 v[74:77], v[134:137], v[228:231], v[74:77]
	v_mfma_f32_16x16x32_bf16 v[130:133], v[146:149], v[162:165], 0
	v_mfma_f32_16x16x32_bf16 v[122:125], v[154:157], v[162:165], 0
	v_mfma_f32_16x16x32_bf16 v[102:105], v[146:149], v[170:173], 0
	v_mfma_f32_16x16x32_bf16 v[98:101], v[154:157], v[170:173], 0
	v_mfma_f32_16x16x32_bf16 v[86:89], v[146:149], v[178:181], 0
	v_mfma_f32_16x16x32_bf16 v[82:85], v[154:157], v[178:181], 0
	v_mfma_f32_16x16x32_bf16 v[70:73], v[146:149], v[224:227], 0
	v_mfma_f32_16x16x32_bf16 v[66:69], v[154:157], v[224:227], 0
	v_mfma_f32_16x16x32_bf16 v[130:133], v[150:153], v[166:169], v[130:133]
	v_mfma_f32_16x16x32_bf16 v[122:125], v[158:161], v[166:169], v[122:125]
	v_mfma_f32_16x16x32_bf16 v[102:105], v[150:153], v[174:177], v[102:105]
	v_mfma_f32_16x16x32_bf16 v[98:101], v[158:161], v[174:177], v[98:101]
	v_mfma_f32_16x16x32_bf16 v[86:89], v[150:153], v[182:185], v[86:89]
	v_mfma_f32_16x16x32_bf16 v[82:85], v[158:161], v[182:185], v[82:85]
	v_mfma_f32_16x16x32_bf16 v[70:73], v[150:153], v[228:231], v[70:73]
	v_mfma_f32_16x16x32_bf16 v[66:69], v[158:161], v[228:231], v[66:69]
	s_barrier
	s_add_i32 s44, s63, s52
	v_lshl_add_u64 v[216:217], s[48:49], 0, v[208:209]
	s_mov_b32 m0, s44
	ds_read_b128 v[162:165], v222 offset:16384
	ds_read_b128 v[166:169], v222 offset:17408
	ds_read_b128 v[170:173], v222 offset:18432
	ds_read_b128 v[174:177], v222 offset:19456
	ds_read_b128 v[178:181], v222 offset:20480
	ds_read_b128 v[182:185], v222 offset:21504
	ds_read_b128 v[224:227], v222 offset:22528
	ds_read_b128 v[228:231], v222 offset:23552
	global_load_lds_dwordx4 v[216:217], off
	s_add_i32 m0, s44, 0x2000
	s_add_u32 s44, s48, 0xb0000
	v_lshl_add_u64 v[240:241], s[48:49], 0, v[204:205]
	s_addc_u32 s45, s49, 0
	s_add_i32 s63, s64, s52
	global_load_lds_dwordx4 v[240:241], off
	v_lshl_add_u64 v[242:243], s[44:45], 0, v[208:209]
	s_mov_b32 m0, s63
	v_lshl_add_u64 v[244:245], s[50:51], 0, v[206:207]
	global_load_lds_dwordx4 v[242:243], off
	v_lshl_add_u64 v[242:243], s[44:45], 0, v[204:205]
	s_add_i32 m0, s63, 0x2000
	s_nop 0
	global_load_lds_dwordx4 v[242:243], off
	v_lshl_add_u64 v[242:243], s[50:51], 0, v[210:211]
	s_mov_b32 m0, s53
	s_nop 0
	global_load_lds_dwordx4 v[242:243], off
	s_mov_b32 m0, s54
	s_nop 0
	global_load_lds_dwordx4 v[244:245], off
	s_waitcnt vmcnt(8)
	s_waitcnt lgkmcnt(0)
	s_barrier
	v_mfma_f32_16x16x32_bf16 v[62:65], v[106:109], v[162:165], 0
	v_mfma_f32_16x16x32_bf16 v[58:61], v[126:129], v[162:165], 0
	v_mfma_f32_16x16x32_bf16 v[46:49], v[106:109], v[170:173], 0
	v_mfma_f32_16x16x32_bf16 v[42:45], v[126:129], v[170:173], 0
	v_mfma_f32_16x16x32_bf16 v[30:33], v[106:109], v[178:181], 0
	v_mfma_f32_16x16x32_bf16 v[26:29], v[126:129], v[178:181], 0
	v_mfma_f32_16x16x32_bf16 v[14:17], v[106:109], v[224:227], 0
	v_mfma_f32_16x16x32_bf16 v[10:13], v[126:129], v[224:227], 0
	v_mfma_f32_16x16x32_bf16 v[62:65], v[110:113], v[166:169], v[62:65]
	v_mfma_f32_16x16x32_bf16 v[58:61], v[134:137], v[166:169], v[58:61]
	v_mfma_f32_16x16x32_bf16 v[46:49], v[110:113], v[174:177], v[46:49]
	v_mfma_f32_16x16x32_bf16 v[42:45], v[134:137], v[174:177], v[42:45]
	v_mfma_f32_16x16x32_bf16 v[30:33], v[110:113], v[182:185], v[30:33]
	v_mfma_f32_16x16x32_bf16 v[26:29], v[134:137], v[182:185], v[26:29]
	v_mfma_f32_16x16x32_bf16 v[14:17], v[110:113], v[228:231], v[14:17]
	v_mfma_f32_16x16x32_bf16 v[10:13], v[134:137], v[228:231], v[10:13]
	v_mfma_f32_16x16x32_bf16 v[54:57], v[146:149], v[162:165], 0
	v_mfma_f32_16x16x32_bf16 v[50:53], v[154:157], v[162:165], 0
	v_mfma_f32_16x16x32_bf16 v[38:41], v[146:149], v[170:173], 0
	v_mfma_f32_16x16x32_bf16 v[34:37], v[154:157], v[170:173], 0
	v_mfma_f32_16x16x32_bf16 v[22:25], v[146:149], v[178:181], 0
	v_mfma_f32_16x16x32_bf16 v[18:21], v[154:157], v[178:181], 0
	v_mfma_f32_16x16x32_bf16 v[6:9], v[146:149], v[224:227], 0
	v_mfma_f32_16x16x32_bf16 v[2:5], v[154:157], v[224:227], 0
	v_mfma_f32_16x16x32_bf16 v[54:57], v[150:153], v[166:169], v[54:57]
	v_mfma_f32_16x16x32_bf16 v[50:53], v[158:161], v[166:169], v[50:53]
	v_mfma_f32_16x16x32_bf16 v[38:41], v[150:153], v[174:177], v[38:41]
	v_mfma_f32_16x16x32_bf16 v[34:37], v[158:161], v[174:177], v[34:37]
	v_mfma_f32_16x16x32_bf16 v[22:25], v[150:153], v[182:185], v[22:25]
	v_mfma_f32_16x16x32_bf16 v[18:21], v[158:161], v[182:185], v[18:21]
	v_mfma_f32_16x16x32_bf16 v[6:9], v[150:153], v[228:231], v[6:9]
	v_mfma_f32_16x16x32_bf16 v[2:5], v[158:161], v[228:231], v[2:5]
	s_barrier
	s_add_i32 s63, 0, 0x18000
	v_add_u32_e32 v0, s63, v221
	s_add_i32 s64, 0, 0x1c000
	ds_read_b128 v[106:109], v0
	ds_read_b128 v[110:113], v0 offset:1024
	ds_read_b128 v[126:129], v0 offset:2048
	ds_read_b128 v[134:137], v0 offset:3072
	v_add_u32_e32 v0, s64, v221
	ds_read_b128 v[146:149], v0
	ds_read_b128 v[150:153], v0 offset:1024
	ds_read_b128 v[154:157], v0 offset:2048
	ds_read_b128 v[158:161], v0 offset:3072
	s_add_u32 s44, s50, 0xb0000
	s_addc_u32 s45, s51, 0
	s_mov_b32 m0, s55
	v_lshl_add_u64 v[246:247], s[44:45], 0, v[210:211]
	ds_read_b128 v[162:165], v222 offset:32768
	ds_read_b128 v[166:169], v222 offset:33792
	ds_read_b128 v[170:173], v222 offset:34816
	ds_read_b128 v[174:177], v222 offset:35840
	ds_read_b128 v[178:181], v222 offset:36864
	ds_read_b128 v[182:185], v222 offset:37888
	ds_read_b128 v[224:227], v222 offset:38912
	ds_read_b128 v[228:231], v222 offset:39936
	global_load_lds_dwordx4 v[246:247], off
	v_lshl_add_u64 v[246:247], s[44:45], 0, v[206:207]
	s_mov_b32 m0, s56
	s_nop 0
	global_load_lds_dwordx4 v[246:247], off
	s_waitcnt vmcnt(8)
	s_waitcnt lgkmcnt(0)
	s_barrier
	v_mfma_f32_16x16x32_bf16 v[142:145], v[106:109], v[162:165], v[142:145]
	v_mfma_f32_16x16x32_bf16 v[138:141], v[126:129], v[162:165], v[138:141]
	v_mfma_f32_16x16x32_bf16 v[118:121], v[106:109], v[170:173], v[118:121]
	v_mfma_f32_16x16x32_bf16 v[114:117], v[126:129], v[170:173], v[114:117]
	v_mfma_f32_16x16x32_bf16 v[94:97], v[106:109], v[178:181], v[94:97]
	v_mfma_f32_16x16x32_bf16 v[90:93], v[126:129], v[178:181], v[90:93]
	v_mfma_f32_16x16x32_bf16 v[78:81], v[106:109], v[224:227], v[78:81]
	v_mfma_f32_16x16x32_bf16 v[74:77], v[126:129], v[224:227], v[74:77]
	v_mfma_f32_16x16x32_bf16 v[142:145], v[110:113], v[166:169], v[142:145]
	v_mfma_f32_16x16x32_bf16 v[138:141], v[134:137], v[166:169], v[138:141]
	v_mfma_f32_16x16x32_bf16 v[118:121], v[110:113], v[174:177], v[118:121]
	v_mfma_f32_16x16x32_bf16 v[114:117], v[134:137], v[174:177], v[114:117]
	v_mfma_f32_16x16x32_bf16 v[94:97], v[110:113], v[182:185], v[94:97]
	v_mfma_f32_16x16x32_bf16 v[90:93], v[134:137], v[182:185], v[90:93]
	v_mfma_f32_16x16x32_bf16 v[78:81], v[110:113], v[228:231], v[78:81]
	v_mfma_f32_16x16x32_bf16 v[74:77], v[134:137], v[228:231], v[74:77]
	v_mfma_f32_16x16x32_bf16 v[130:133], v[146:149], v[162:165], v[130:133]
	v_mfma_f32_16x16x32_bf16 v[122:125], v[154:157], v[162:165], v[122:125]
	v_mfma_f32_16x16x32_bf16 v[102:105], v[146:149], v[170:173], v[102:105]
	v_mfma_f32_16x16x32_bf16 v[98:101], v[154:157], v[170:173], v[98:101]
	v_mfma_f32_16x16x32_bf16 v[86:89], v[146:149], v[178:181], v[86:89]
	v_mfma_f32_16x16x32_bf16 v[82:85], v[154:157], v[178:181], v[82:85]
	v_mfma_f32_16x16x32_bf16 v[70:73], v[146:149], v[224:227], v[70:73]
	v_mfma_f32_16x16x32_bf16 v[66:69], v[154:157], v[224:227], v[66:69]
	v_mfma_f32_16x16x32_bf16 v[130:133], v[150:153], v[166:169], v[130:133]
	v_mfma_f32_16x16x32_bf16 v[122:125], v[158:161], v[166:169], v[122:125]
	v_mfma_f32_16x16x32_bf16 v[102:105], v[150:153], v[174:177], v[102:105]
	v_mfma_f32_16x16x32_bf16 v[98:101], v[158:161], v[174:177], v[98:101]
	v_mfma_f32_16x16x32_bf16 v[86:89], v[150:153], v[182:185], v[86:89]
	v_mfma_f32_16x16x32_bf16 v[82:85], v[158:161], v[182:185], v[82:85]
	v_mfma_f32_16x16x32_bf16 v[70:73], v[150:153], v[228:231], v[70:73]
	v_mfma_f32_16x16x32_bf16 v[66:69], v[158:161], v[228:231], v[66:69]
	s_barrier
	s_add_i32 s44, s63, s52
	v_lshl_add_u64 v[216:217], v[216:217], 0, s[16:17]
	s_mov_b32 m0, s44
	ds_read_b128 v[162:165], v222 offset:49152
	ds_read_b128 v[166:169], v222 offset:50176
	ds_read_b128 v[170:173], v222 offset:51200
	ds_read_b128 v[174:177], v222 offset:52224
	ds_read_b128 v[178:181], v222 offset:53248
	ds_read_b128 v[182:185], v222 offset:54272
	ds_read_b128 v[224:227], v222 offset:55296
	ds_read_b128 v[228:231], v222 offset:56320
	global_load_lds_dwordx4 v[216:217], off
	s_add_i32 m0, s44, 0x2000
	s_add_u32 s44, s48, 0xb0080
	v_lshl_add_u64 v[216:217], v[240:241], 0, s[16:17]
	s_addc_u32 s45, s49, 0
	s_add_i32 s48, s64, s52
	global_load_lds_dwordx4 v[216:217], off
	v_lshl_add_u64 v[216:217], s[44:45], 0, v[208:209]
	s_mov_b32 m0, s48
	s_nop 0
	global_load_lds_dwordx4 v[216:217], off
	v_lshl_add_u64 v[216:217], s[44:45], 0, v[204:205]
	s_add_i32 m0, s48, 0x2000
	s_nop 0
	global_load_lds_dwordx4 v[216:217], off
	v_lshl_add_u64 v[216:217], v[242:243], 0, s[16:17]
	s_mov_b32 m0, s59
	s_nop 0
	global_load_lds_dwordx4 v[216:217], off
	v_lshl_add_u64 v[216:217], v[244:245], 0, s[16:17]
	s_mov_b32 m0, s60
	s_nop 0
	global_load_lds_dwordx4 v[216:217], off
	s_waitcnt vmcnt(8)
	s_waitcnt lgkmcnt(0)
	s_barrier
	v_mfma_f32_16x16x32_bf16 v[62:65], v[106:109], v[162:165], v[62:65]
	v_mfma_f32_16x16x32_bf16 v[58:61], v[126:129], v[162:165], v[58:61]
	v_mfma_f32_16x16x32_bf16 v[46:49], v[106:109], v[170:173], v[46:49]
	v_mfma_f32_16x16x32_bf16 v[42:45], v[126:129], v[170:173], v[42:45]
	v_mfma_f32_16x16x32_bf16 v[30:33], v[106:109], v[178:181], v[30:33]
	v_mfma_f32_16x16x32_bf16 v[26:29], v[126:129], v[178:181], v[26:29]
	v_mfma_f32_16x16x32_bf16 v[14:17], v[106:109], v[224:227], v[14:17]
	v_mfma_f32_16x16x32_bf16 v[10:13], v[126:129], v[224:227], v[10:13]
	v_mfma_f32_16x16x32_bf16 v[62:65], v[110:113], v[166:169], v[62:65]
	v_mfma_f32_16x16x32_bf16 v[58:61], v[134:137], v[166:169], v[58:61]
	v_mfma_f32_16x16x32_bf16 v[46:49], v[110:113], v[174:177], v[46:49]
	v_mfma_f32_16x16x32_bf16 v[42:45], v[134:137], v[174:177], v[42:45]
	v_mfma_f32_16x16x32_bf16 v[30:33], v[110:113], v[182:185], v[30:33]
	v_mfma_f32_16x16x32_bf16 v[26:29], v[134:137], v[182:185], v[26:29]
	v_mfma_f32_16x16x32_bf16 v[14:17], v[110:113], v[228:231], v[14:17]
	v_mfma_f32_16x16x32_bf16 v[10:13], v[134:137], v[228:231], v[10:13]
	v_mfma_f32_16x16x32_bf16 v[54:57], v[146:149], v[162:165], v[54:57]
	v_mfma_f32_16x16x32_bf16 v[50:53], v[154:157], v[162:165], v[50:53]
	v_mfma_f32_16x16x32_bf16 v[38:41], v[146:149], v[170:173], v[38:41]
	v_mfma_f32_16x16x32_bf16 v[34:37], v[154:157], v[170:173], v[34:37]
	v_mfma_f32_16x16x32_bf16 v[22:25], v[146:149], v[178:181], v[22:25]
	v_mfma_f32_16x16x32_bf16 v[18:21], v[154:157], v[178:181], v[18:21]
	v_mfma_f32_16x16x32_bf16 v[6:9], v[146:149], v[224:227], v[6:9]
	v_mfma_f32_16x16x32_bf16 v[2:5], v[154:157], v[224:227], v[2:5]
	v_mfma_f32_16x16x32_bf16 v[54:57], v[150:153], v[166:169], v[54:57]
	v_mfma_f32_16x16x32_bf16 v[50:53], v[158:161], v[166:169], v[50:53]
	v_mfma_f32_16x16x32_bf16 v[38:41], v[150:153], v[174:177], v[38:41]
	v_mfma_f32_16x16x32_bf16 v[34:37], v[158:161], v[174:177], v[34:37]
	v_mfma_f32_16x16x32_bf16 v[22:25], v[150:153], v[182:185], v[22:25]
	v_mfma_f32_16x16x32_bf16 v[18:21], v[158:161], v[182:185], v[18:21]
	v_mfma_f32_16x16x32_bf16 v[6:9], v[150:153], v[228:231], v[6:9]
	v_mfma_f32_16x16x32_bf16 v[2:5], v[158:161], v[228:231], v[2:5]
	s_barrier
	s_add_i32 s62, s62, 2
	s_add_u32 s7, s7, 0x100
	s_addc_u32 s47, s47, 0
	s_cmp_gt_u32 s62, 41
	s_mov_b64 s[44:45], s[0:1]
.LBB0_1088:
	s_add_u32 s0, s44, 0x100
	s_addc_u32 s1, s45, 0
	s_add_i32 s63, 0, 0x10000
	s_cmp_eq_u32 s62, 40
	s_cselect_b32 s51, s41, s1
	s_cselect_b32 s50, s40, s0
	v_add_u32_e32 v0, s63, v221
	s_cselect_b32 s49, s43, s47
	s_cselect_b32 s48, s42, s7
	s_add_i32 s64, 0, 0x14000
	ds_read_b128 v[106:109], v0
	ds_read_b128 v[110:113], v0 offset:1024
	ds_read_b128 v[126:129], v0 offset:2048
	ds_read_b128 v[134:137], v0 offset:3072
	v_add_u32_e32 v0, s64, v221
	ds_read_b128 v[146:149], v0
	ds_read_b128 v[150:153], v0 offset:1024
	ds_read_b128 v[154:157], v0 offset:2048
	ds_read_b128 v[158:161], v0 offset:3072
	v_lshl_add_u64 v[216:217], s[44:45], 0, v[212:213]
	s_add_i32 m0, s53, 0xc000
	ds_read_b128 v[162:165], v222
	ds_read_b128 v[166:169], v222 offset:1024
	ds_read_b128 v[170:173], v222 offset:2048
	ds_read_b128 v[174:177], v222 offset:3072
	ds_read_b128 v[178:181], v222 offset:4096
	ds_read_b128 v[182:185], v222 offset:5120
	ds_read_b128 v[224:227], v222 offset:6144
	ds_read_b128 v[228:231], v222 offset:7168
	global_load_lds_dwordx4 v[216:217], off
	v_lshl_add_u64 v[216:217], s[44:45], 0, v[214:215]
	s_add_i32 m0, s53, 0xe000
	s_nop 0
	global_load_lds_dwordx4 v[216:217], off
	s_waitcnt vmcnt(8)
	s_waitcnt lgkmcnt(0)
	s_barrier
	v_mfma_f32_16x16x32_bf16 v[142:145], v[106:109], v[162:165], v[142:145]
	v_mfma_f32_16x16x32_bf16 v[138:141], v[126:129], v[162:165], v[138:141]
	v_mfma_f32_16x16x32_bf16 v[118:121], v[106:109], v[170:173], v[118:121]
	v_mfma_f32_16x16x32_bf16 v[114:117], v[126:129], v[170:173], v[114:117]
	v_mfma_f32_16x16x32_bf16 v[94:97], v[106:109], v[178:181], v[94:97]
	v_mfma_f32_16x16x32_bf16 v[90:93], v[126:129], v[178:181], v[90:93]
	v_mfma_f32_16x16x32_bf16 v[78:81], v[106:109], v[224:227], v[78:81]
	v_mfma_f32_16x16x32_bf16 v[74:77], v[126:129], v[224:227], v[74:77]
	v_mfma_f32_16x16x32_bf16 v[142:145], v[110:113], v[166:169], v[142:145]
	v_mfma_f32_16x16x32_bf16 v[138:141], v[134:137], v[166:169], v[138:141]
	v_mfma_f32_16x16x32_bf16 v[118:121], v[110:113], v[174:177], v[118:121]
	v_mfma_f32_16x16x32_bf16 v[114:117], v[134:137], v[174:177], v[114:117]
	v_mfma_f32_16x16x32_bf16 v[94:97], v[110:113], v[182:185], v[94:97]
	v_mfma_f32_16x16x32_bf16 v[90:93], v[134:137], v[182:185], v[90:93]
	v_mfma_f32_16x16x32_bf16 v[78:81], v[110:113], v[228:231], v[78:81]
	v_mfma_f32_16x16x32_bf16 v[74:77], v[134:137], v[228:231], v[74:77]
	v_mfma_f32_16x16x32_bf16 v[130:133], v[146:149], v[162:165], v[130:133]
	v_mfma_f32_16x16x32_bf16 v[122:125], v[154:157], v[162:165], v[122:125]
	v_mfma_f32_16x16x32_bf16 v[102:105], v[146:149], v[170:173], v[102:105]
	v_mfma_f32_16x16x32_bf16 v[98:101], v[154:157], v[170:173], v[98:101]
	v_mfma_f32_16x16x32_bf16 v[86:89], v[146:149], v[178:181], v[86:89]
	v_mfma_f32_16x16x32_bf16 v[82:85], v[154:157], v[178:181], v[82:85]
	v_mfma_f32_16x16x32_bf16 v[70:73], v[146:149], v[224:227], v[70:73]
	v_mfma_f32_16x16x32_bf16 v[66:69], v[154:157], v[224:227], v[66:69]
	v_mfma_f32_16x16x32_bf16 v[130:133], v[150:153], v[166:169], v[130:133]
	v_mfma_f32_16x16x32_bf16 v[122:125], v[158:161], v[166:169], v[122:125]
	v_mfma_f32_16x16x32_bf16 v[102:105], v[150:153], v[174:177], v[102:105]
	v_mfma_f32_16x16x32_bf16 v[98:101], v[158:161], v[174:177], v[98:101]
	v_mfma_f32_16x16x32_bf16 v[86:89], v[150:153], v[182:185], v[86:89]
	v_mfma_f32_16x16x32_bf16 v[82:85], v[158:161], v[182:185], v[82:85]
	v_mfma_f32_16x16x32_bf16 v[70:73], v[150:153], v[228:231], v[70:73]
	v_mfma_f32_16x16x32_bf16 v[66:69], v[158:161], v[228:231], v[66:69]
	s_barrier
	s_add_i32 s44, s63, s52
	v_lshl_add_u64 v[216:217], s[48:49], 0, v[208:209]
	s_mov_b32 m0, s44
	ds_read_b128 v[162:165], v222 offset:16384
	ds_read_b128 v[166:169], v222 offset:17408
	ds_read_b128 v[170:173], v222 offset:18432
	ds_read_b128 v[174:177], v222 offset:19456
	ds_read_b128 v[178:181], v222 offset:20480
	ds_read_b128 v[182:185], v222 offset:21504
	ds_read_b128 v[224:227], v222 offset:22528
	ds_read_b128 v[228:231], v222 offset:23552
	global_load_lds_dwordx4 v[216:217], off
	s_add_i32 m0, s44, 0x2000
	s_add_u32 s44, s48, 0xb0000
	v_lshl_add_u64 v[240:241], s[48:49], 0, v[204:205]
	s_addc_u32 s45, s49, 0
	s_add_i32 s63, s64, s52
	global_load_lds_dwordx4 v[240:241], off
	v_lshl_add_u64 v[242:243], s[44:45], 0, v[208:209]
	s_mov_b32 m0, s63
	v_lshl_add_u64 v[244:245], s[50:51], 0, v[206:207]
	global_load_lds_dwordx4 v[242:243], off
	v_lshl_add_u64 v[242:243], s[44:45], 0, v[204:205]
	s_add_i32 m0, s63, 0x2000
	s_nop 0
	global_load_lds_dwordx4 v[242:243], off
	v_lshl_add_u64 v[242:243], s[50:51], 0, v[210:211]
	s_mov_b32 m0, s53
	s_nop 0
	global_load_lds_dwordx4 v[242:243], off
	s_mov_b32 m0, s54
	s_nop 0
	global_load_lds_dwordx4 v[244:245], off
	s_waitcnt vmcnt(8)
	s_waitcnt lgkmcnt(0)
	s_barrier
	v_mfma_f32_16x16x32_bf16 v[62:65], v[106:109], v[162:165], v[62:65]
	v_mfma_f32_16x16x32_bf16 v[58:61], v[126:129], v[162:165], v[58:61]
	v_mfma_f32_16x16x32_bf16 v[46:49], v[106:109], v[170:173], v[46:49]
	v_mfma_f32_16x16x32_bf16 v[42:45], v[126:129], v[170:173], v[42:45]
	v_mfma_f32_16x16x32_bf16 v[30:33], v[106:109], v[178:181], v[30:33]
	v_mfma_f32_16x16x32_bf16 v[26:29], v[126:129], v[178:181], v[26:29]
	v_mfma_f32_16x16x32_bf16 v[14:17], v[106:109], v[224:227], v[14:17]
	v_mfma_f32_16x16x32_bf16 v[10:13], v[126:129], v[224:227], v[10:13]
	v_mfma_f32_16x16x32_bf16 v[62:65], v[110:113], v[166:169], v[62:65]
	v_mfma_f32_16x16x32_bf16 v[58:61], v[134:137], v[166:169], v[58:61]
	v_mfma_f32_16x16x32_bf16 v[46:49], v[110:113], v[174:177], v[46:49]
	v_mfma_f32_16x16x32_bf16 v[42:45], v[134:137], v[174:177], v[42:45]
	v_mfma_f32_16x16x32_bf16 v[30:33], v[110:113], v[182:185], v[30:33]
	v_mfma_f32_16x16x32_bf16 v[26:29], v[134:137], v[182:185], v[26:29]
	v_mfma_f32_16x16x32_bf16 v[14:17], v[110:113], v[228:231], v[14:17]
	v_mfma_f32_16x16x32_bf16 v[10:13], v[134:137], v[228:231], v[10:13]
	v_mfma_f32_16x16x32_bf16 v[54:57], v[146:149], v[162:165], v[54:57]
	v_mfma_f32_16x16x32_bf16 v[50:53], v[154:157], v[162:165], v[50:53]
	v_mfma_f32_16x16x32_bf16 v[38:41], v[146:149], v[170:173], v[38:41]
	v_mfma_f32_16x16x32_bf16 v[34:37], v[154:157], v[170:173], v[34:37]
	v_mfma_f32_16x16x32_bf16 v[22:25], v[146:149], v[178:181], v[22:25]
	v_mfma_f32_16x16x32_bf16 v[18:21], v[154:157], v[178:181], v[18:21]
	v_mfma_f32_16x16x32_bf16 v[6:9], v[146:149], v[224:227], v[6:9]
	v_mfma_f32_16x16x32_bf16 v[2:5], v[154:157], v[224:227], v[2:5]
	v_mfma_f32_16x16x32_bf16 v[54:57], v[150:153], v[166:169], v[54:57]
	v_mfma_f32_16x16x32_bf16 v[50:53], v[158:161], v[166:169], v[50:53]
	v_mfma_f32_16x16x32_bf16 v[38:41], v[150:153], v[174:177], v[38:41]
	v_mfma_f32_16x16x32_bf16 v[34:37], v[158:161], v[174:177], v[34:37]
	v_mfma_f32_16x16x32_bf16 v[22:25], v[150:153], v[182:185], v[22:25]
	v_mfma_f32_16x16x32_bf16 v[18:21], v[158:161], v[182:185], v[18:21]
	v_mfma_f32_16x16x32_bf16 v[6:9], v[150:153], v[228:231], v[6:9]
	v_mfma_f32_16x16x32_bf16 v[2:5], v[158:161], v[228:231], v[2:5]
	s_barrier
	s_add_i32 s63, 0, 0x18000
	v_add_u32_e32 v0, s63, v221
	s_add_i32 s64, 0, 0x1c000
	ds_read_b128 v[106:109], v0
	ds_read_b128 v[110:113], v0 offset:1024
	ds_read_b128 v[126:129], v0 offset:2048
	ds_read_b128 v[134:137], v0 offset:3072
	v_add_u32_e32 v0, s64, v221
	ds_read_b128 v[146:149], v0
	ds_read_b128 v[150:153], v0 offset:1024
	ds_read_b128 v[154:157], v0 offset:2048
	ds_read_b128 v[158:161], v0 offset:3072
	s_add_u32 s44, s50, 0xb0000
	s_addc_u32 s45, s51, 0
	s_mov_b32 m0, s55
	v_lshl_add_u64 v[246:247], s[44:45], 0, v[210:211]
	ds_read_b128 v[162:165], v222 offset:32768
	ds_read_b128 v[166:169], v222 offset:33792
	ds_read_b128 v[170:173], v222 offset:34816
	ds_read_b128 v[174:177], v222 offset:35840
	ds_read_b128 v[178:181], v222 offset:36864
	ds_read_b128 v[182:185], v222 offset:37888
	ds_read_b128 v[224:227], v222 offset:38912
	ds_read_b128 v[228:231], v222 offset:39936
	global_load_lds_dwordx4 v[246:247], off
	v_lshl_add_u64 v[246:247], s[44:45], 0, v[206:207]
	s_mov_b32 m0, s56
	s_nop 0
	global_load_lds_dwordx4 v[246:247], off
	s_waitcnt vmcnt(8)
	s_waitcnt lgkmcnt(0)
	s_barrier
	v_mfma_f32_16x16x32_bf16 v[142:145], v[106:109], v[162:165], v[142:145]
	v_mfma_f32_16x16x32_bf16 v[138:141], v[126:129], v[162:165], v[138:141]
	v_mfma_f32_16x16x32_bf16 v[118:121], v[106:109], v[170:173], v[118:121]
	v_mfma_f32_16x16x32_bf16 v[114:117], v[126:129], v[170:173], v[114:117]
	v_mfma_f32_16x16x32_bf16 v[94:97], v[106:109], v[178:181], v[94:97]
	v_mfma_f32_16x16x32_bf16 v[90:93], v[126:129], v[178:181], v[90:93]
	v_mfma_f32_16x16x32_bf16 v[78:81], v[106:109], v[224:227], v[78:81]
	v_mfma_f32_16x16x32_bf16 v[74:77], v[126:129], v[224:227], v[74:77]
	v_mfma_f32_16x16x32_bf16 v[142:145], v[110:113], v[166:169], v[142:145]
	v_mfma_f32_16x16x32_bf16 v[138:141], v[134:137], v[166:169], v[138:141]
	v_mfma_f32_16x16x32_bf16 v[118:121], v[110:113], v[174:177], v[118:121]
	v_mfma_f32_16x16x32_bf16 v[114:117], v[134:137], v[174:177], v[114:117]
	v_mfma_f32_16x16x32_bf16 v[94:97], v[110:113], v[182:185], v[94:97]
	v_mfma_f32_16x16x32_bf16 v[90:93], v[134:137], v[182:185], v[90:93]
	v_mfma_f32_16x16x32_bf16 v[78:81], v[110:113], v[228:231], v[78:81]
	v_mfma_f32_16x16x32_bf16 v[74:77], v[134:137], v[228:231], v[74:77]
	v_mfma_f32_16x16x32_bf16 v[130:133], v[146:149], v[162:165], v[130:133]
	v_mfma_f32_16x16x32_bf16 v[122:125], v[154:157], v[162:165], v[122:125]
	v_mfma_f32_16x16x32_bf16 v[102:105], v[146:149], v[170:173], v[102:105]
	v_mfma_f32_16x16x32_bf16 v[98:101], v[154:157], v[170:173], v[98:101]
	v_mfma_f32_16x16x32_bf16 v[86:89], v[146:149], v[178:181], v[86:89]
	v_mfma_f32_16x16x32_bf16 v[82:85], v[154:157], v[178:181], v[82:85]
	v_mfma_f32_16x16x32_bf16 v[70:73], v[146:149], v[224:227], v[70:73]
	v_mfma_f32_16x16x32_bf16 v[66:69], v[154:157], v[224:227], v[66:69]
	v_mfma_f32_16x16x32_bf16 v[130:133], v[150:153], v[166:169], v[130:133]
	v_mfma_f32_16x16x32_bf16 v[122:125], v[158:161], v[166:169], v[122:125]
	v_mfma_f32_16x16x32_bf16 v[102:105], v[150:153], v[174:177], v[102:105]
	v_mfma_f32_16x16x32_bf16 v[98:101], v[158:161], v[174:177], v[98:101]
	v_mfma_f32_16x16x32_bf16 v[86:89], v[150:153], v[182:185], v[86:89]
	v_mfma_f32_16x16x32_bf16 v[82:85], v[158:161], v[182:185], v[82:85]
	v_mfma_f32_16x16x32_bf16 v[70:73], v[150:153], v[228:231], v[70:73]
	v_mfma_f32_16x16x32_bf16 v[66:69], v[158:161], v[228:231], v[66:69]
	s_barrier
	s_add_i32 s44, s63, s52
	v_lshl_add_u64 v[216:217], v[216:217], 0, s[16:17]
	s_mov_b32 m0, s44
	ds_read_b128 v[162:165], v222 offset:49152
	ds_read_b128 v[166:169], v222 offset:50176
	ds_read_b128 v[170:173], v222 offset:51200
	ds_read_b128 v[174:177], v222 offset:52224
	ds_read_b128 v[178:181], v222 offset:53248
	ds_read_b128 v[182:185], v222 offset:54272
	ds_read_b128 v[224:227], v222 offset:55296
	ds_read_b128 v[228:231], v222 offset:56320
	global_load_lds_dwordx4 v[216:217], off
	s_add_i32 m0, s44, 0x2000
	s_add_u32 s44, s48, 0xb0080
	v_lshl_add_u64 v[216:217], v[240:241], 0, s[16:17]
	s_addc_u32 s45, s49, 0
	s_add_i32 s48, s64, s52
	global_load_lds_dwordx4 v[216:217], off
	v_lshl_add_u64 v[216:217], s[44:45], 0, v[208:209]
	s_mov_b32 m0, s48
	s_nop 0
	global_load_lds_dwordx4 v[216:217], off
	v_lshl_add_u64 v[216:217], s[44:45], 0, v[204:205]
	s_add_i32 m0, s48, 0x2000
	s_nop 0
	global_load_lds_dwordx4 v[216:217], off
	v_lshl_add_u64 v[216:217], v[242:243], 0, s[16:17]
	s_mov_b32 m0, s59
	s_nop 0
	global_load_lds_dwordx4 v[216:217], off
	v_lshl_add_u64 v[216:217], v[244:245], 0, s[16:17]
	s_mov_b32 m0, s60
	s_nop 0
	global_load_lds_dwordx4 v[216:217], off
	s_waitcnt vmcnt(8)
	s_waitcnt lgkmcnt(0)
	s_barrier
	v_mfma_f32_16x16x32_bf16 v[62:65], v[106:109], v[162:165], v[62:65]
	v_mfma_f32_16x16x32_bf16 v[58:61], v[126:129], v[162:165], v[58:61]
	v_mfma_f32_16x16x32_bf16 v[46:49], v[106:109], v[170:173], v[46:49]
	v_mfma_f32_16x16x32_bf16 v[42:45], v[126:129], v[170:173], v[42:45]
	v_mfma_f32_16x16x32_bf16 v[30:33], v[106:109], v[178:181], v[30:33]
	v_mfma_f32_16x16x32_bf16 v[26:29], v[126:129], v[178:181], v[26:29]
	v_mfma_f32_16x16x32_bf16 v[14:17], v[106:109], v[224:227], v[14:17]
	v_mfma_f32_16x16x32_bf16 v[10:13], v[126:129], v[224:227], v[10:13]
	v_mfma_f32_16x16x32_bf16 v[62:65], v[110:113], v[166:169], v[62:65]
	v_mfma_f32_16x16x32_bf16 v[58:61], v[134:137], v[166:169], v[58:61]
	v_mfma_f32_16x16x32_bf16 v[46:49], v[110:113], v[174:177], v[46:49]
	v_mfma_f32_16x16x32_bf16 v[42:45], v[134:137], v[174:177], v[42:45]
	v_mfma_f32_16x16x32_bf16 v[30:33], v[110:113], v[182:185], v[30:33]
	v_mfma_f32_16x16x32_bf16 v[26:29], v[134:137], v[182:185], v[26:29]
	v_mfma_f32_16x16x32_bf16 v[14:17], v[110:113], v[228:231], v[14:17]
	v_mfma_f32_16x16x32_bf16 v[10:13], v[134:137], v[228:231], v[10:13]
	v_mfma_f32_16x16x32_bf16 v[54:57], v[146:149], v[162:165], v[54:57]
	v_mfma_f32_16x16x32_bf16 v[50:53], v[154:157], v[162:165], v[50:53]
	v_mfma_f32_16x16x32_bf16 v[38:41], v[146:149], v[170:173], v[38:41]
	v_mfma_f32_16x16x32_bf16 v[34:37], v[154:157], v[170:173], v[34:37]
	v_mfma_f32_16x16x32_bf16 v[22:25], v[146:149], v[178:181], v[22:25]
	v_mfma_f32_16x16x32_bf16 v[18:21], v[154:157], v[178:181], v[18:21]
	v_mfma_f32_16x16x32_bf16 v[6:9], v[146:149], v[224:227], v[6:9]
	v_mfma_f32_16x16x32_bf16 v[2:5], v[154:157], v[224:227], v[2:5]
	v_mfma_f32_16x16x32_bf16 v[54:57], v[150:153], v[166:169], v[54:57]
	v_mfma_f32_16x16x32_bf16 v[50:53], v[158:161], v[166:169], v[50:53]
	v_mfma_f32_16x16x32_bf16 v[38:41], v[150:153], v[174:177], v[38:41]
	v_mfma_f32_16x16x32_bf16 v[34:37], v[158:161], v[174:177], v[34:37]
	v_mfma_f32_16x16x32_bf16 v[22:25], v[150:153], v[182:185], v[22:25]
	v_mfma_f32_16x16x32_bf16 v[18:21], v[158:161], v[182:185], v[18:21]
	v_mfma_f32_16x16x32_bf16 v[6:9], v[150:153], v[228:231], v[6:9]
	v_mfma_f32_16x16x32_bf16 v[2:5], v[158:161], v[228:231], v[2:5]
	s_barrier
	s_add_i32 s62, s62, 2
	s_add_u32 s7, s7, 0x100
	s_addc_u32 s47, s47, 0
	s_cmp_gt_u32 s62, 41
	s_mov_b64 s[44:45], s[0:1]
	s_cbranch_scc0 .LBB0_1088
	s_and_b64 vcc, exec, s[22:23]
	s_cbranch_vccz .LBB0_1091
	s_barrier

.Lrb7_skip:
	s_add_u32 s42, s40, 0xfffc0080
	s_addc_u32 s43, s41, -1
	s_add_i32 s54, 0, 0x10000
	s_cmp_eq_u32 s53, 12
	s_cselect_b32 s49, s7, s43
	s_cselect_b32 s48, s23, s42
	v_add_u32_e32 v0, s54, v160
	s_cselect_b32 s43, s21, s52
	s_cselect_b32 s42, s50, s51
	s_add_i32 s65, 0, 0x14000
	ds_read_b128 v[142:145], v0
	ds_read_b128 v[146:149], v0 offset:1024
	ds_read_b128 v[150:153], v0 offset:2048
	ds_read_b128 v[154:157], v0 offset:3072
	v_add_u32_e32 v0, s65, v160
	ds_read_b128 v[162:165], v0
	ds_read_b128 v[166:169], v0 offset:1024
	ds_read_b128 v[170:173], v0 offset:2048
	ds_read_b128 v[174:177], v0 offset:3072
	v_lshl_add_u64 v[228:229], s[40:41], 0, v[138:139]
	s_add_i32 m0, s57, 0xc000
	ds_read_b128 v[178:181], v161
	ds_read_b128 v[182:185], v161 offset:1024
	ds_read_b128 v[204:207], v161 offset:2048
	ds_read_b128 v[208:211], v161 offset:3072
	ds_read_b128 v[212:215], v161 offset:4096
	ds_read_b128 v[216:219], v161 offset:5120
	ds_read_b128 v[220:223], v161 offset:6144
	ds_read_b128 v[224:227], v161 offset:7168
	global_load_lds_dwordx4 v[228:229], off
	v_lshl_add_u64 v[228:229], s[40:41], 0, v[140:141]
	s_add_i32 m0, s57, 0xe000
	s_nop 0
	global_load_lds_dwordx4 v[228:229], off
	s_waitcnt vmcnt(8)
	s_waitcnt lgkmcnt(0)
	s_barrier
	v_mfma_f32_16x16x32_bf16 v[126:129], v[142:145], v[178:181], 0
	v_mfma_f32_16x16x32_bf16 v[122:125], v[150:153], v[178:181], 0
	v_mfma_f32_16x16x32_bf16 v[110:113], v[142:145], v[204:207], 0
	v_mfma_f32_16x16x32_bf16 v[106:109], v[150:153], v[204:207], 0
	v_mfma_f32_16x16x32_bf16 v[94:97], v[142:145], v[212:215], 0
	v_mfma_f32_16x16x32_bf16 v[90:93], v[150:153], v[212:215], 0
	v_mfma_f32_16x16x32_bf16 v[78:81], v[142:145], v[220:223], 0
	v_mfma_f32_16x16x32_bf16 v[74:77], v[150:153], v[220:223], 0
	v_mfma_f32_16x16x32_bf16 v[126:129], v[146:149], v[182:185], v[126:129]
	v_mfma_f32_16x16x32_bf16 v[122:125], v[154:157], v[182:185], v[122:125]
	v_mfma_f32_16x16x32_bf16 v[110:113], v[146:149], v[208:211], v[110:113]
	v_mfma_f32_16x16x32_bf16 v[106:109], v[154:157], v[208:211], v[106:109]
	v_mfma_f32_16x16x32_bf16 v[94:97], v[146:149], v[216:219], v[94:97]
	v_mfma_f32_16x16x32_bf16 v[90:93], v[154:157], v[216:219], v[90:93]
	v_mfma_f32_16x16x32_bf16 v[78:81], v[146:149], v[224:227], v[78:81]
	v_mfma_f32_16x16x32_bf16 v[74:77], v[154:157], v[224:227], v[74:77]
	v_mfma_f32_16x16x32_bf16 v[118:121], v[162:165], v[178:181], 0
	v_mfma_f32_16x16x32_bf16 v[114:117], v[170:173], v[178:181], 0
	v_mfma_f32_16x16x32_bf16 v[102:105], v[162:165], v[204:207], 0
	v_mfma_f32_16x16x32_bf16 v[98:101], v[170:173], v[204:207], 0
	v_mfma_f32_16x16x32_bf16 v[86:89], v[162:165], v[212:215], 0
	v_mfma_f32_16x16x32_bf16 v[82:85], v[170:173], v[212:215], 0
	v_mfma_f32_16x16x32_bf16 v[70:73], v[162:165], v[220:223], 0
	v_mfma_f32_16x16x32_bf16 v[66:69], v[170:173], v[220:223], 0
	v_mfma_f32_16x16x32_bf16 v[118:121], v[166:169], v[182:185], v[118:121]
	v_mfma_f32_16x16x32_bf16 v[114:117], v[174:177], v[182:185], v[114:117]
	v_mfma_f32_16x16x32_bf16 v[102:105], v[166:169], v[208:211], v[102:105]
	v_mfma_f32_16x16x32_bf16 v[98:101], v[174:177], v[208:211], v[98:101]
	v_mfma_f32_16x16x32_bf16 v[86:89], v[166:169], v[216:219], v[86:89]
	v_mfma_f32_16x16x32_bf16 v[82:85], v[174:177], v[216:219], v[82:85]
	v_mfma_f32_16x16x32_bf16 v[70:73], v[166:169], v[224:227], v[70:73]
	v_mfma_f32_16x16x32_bf16 v[66:69], v[174:177], v[224:227], v[66:69]
	s_barrier
	s_add_i32 s54, s54, s56
	v_lshl_add_u64 v[228:229], s[42:43], 0, v[134:135]
	s_mov_b32 m0, s54
	ds_read_b128 v[178:181], v161 offset:16384
	ds_read_b128 v[182:185], v161 offset:17408
	ds_read_b128 v[204:207], v161 offset:18432
	ds_read_b128 v[208:211], v161 offset:19456
	ds_read_b128 v[212:215], v161 offset:20480
	ds_read_b128 v[216:219], v161 offset:21504
	ds_read_b128 v[220:223], v161 offset:22528
	ds_read_b128 v[224:227], v161 offset:23552
	global_load_lds_dwordx4 v[228:229], off
	s_add_i32 m0, s54, 0x2000
	s_add_u32 s54, s42, 0x40000
	v_lshl_add_u64 v[230:231], s[42:43], 0, v[130:131]
	s_addc_u32 s55, s43, 0
	s_add_i32 s65, s65, s56
	global_load_lds_dwordx4 v[230:231], off
	v_lshl_add_u64 v[240:241], s[54:55], 0, v[134:135]
	s_mov_b32 m0, s65
	v_lshl_add_u64 v[242:243], s[48:49], 0, v[132:133]
	global_load_lds_dwordx4 v[240:241], off
	v_lshl_add_u64 v[240:241], s[54:55], 0, v[130:131]
	s_add_i32 m0, s65, 0x2000
	s_nop 0
	global_load_lds_dwordx4 v[240:241], off
	v_lshl_add_u64 v[240:241], s[48:49], 0, v[136:137]
	s_mov_b32 m0, s57
	s_nop 0
	global_load_lds_dwordx4 v[240:241], off
	s_mov_b32 m0, s58
	s_nop 0
	global_load_lds_dwordx4 v[242:243], off
	s_waitcnt vmcnt(8)
	s_waitcnt lgkmcnt(0)
	s_barrier
	v_mfma_f32_16x16x32_bf16 v[62:65], v[142:145], v[178:181], 0
	v_mfma_f32_16x16x32_bf16 v[58:61], v[150:153], v[178:181], 0
	v_mfma_f32_16x16x32_bf16 v[46:49], v[142:145], v[204:207], 0
	v_mfma_f32_16x16x32_bf16 v[42:45], v[150:153], v[204:207], 0
	v_mfma_f32_16x16x32_bf16 v[30:33], v[142:145], v[212:215], 0
	v_mfma_f32_16x16x32_bf16 v[26:29], v[150:153], v[212:215], 0
	v_mfma_f32_16x16x32_bf16 v[14:17], v[142:145], v[220:223], 0
	v_mfma_f32_16x16x32_bf16 v[10:13], v[150:153], v[220:223], 0
	v_mfma_f32_16x16x32_bf16 v[62:65], v[146:149], v[182:185], v[62:65]
	v_mfma_f32_16x16x32_bf16 v[58:61], v[154:157], v[182:185], v[58:61]
	v_mfma_f32_16x16x32_bf16 v[46:49], v[146:149], v[208:211], v[46:49]
	v_mfma_f32_16x16x32_bf16 v[42:45], v[154:157], v[208:211], v[42:45]
	v_mfma_f32_16x16x32_bf16 v[30:33], v[146:149], v[216:219], v[30:33]
	v_mfma_f32_16x16x32_bf16 v[26:29], v[154:157], v[216:219], v[26:29]
	v_mfma_f32_16x16x32_bf16 v[14:17], v[146:149], v[224:227], v[14:17]
	v_mfma_f32_16x16x32_bf16 v[10:13], v[154:157], v[224:227], v[10:13]
	v_mfma_f32_16x16x32_bf16 v[54:57], v[162:165], v[178:181], 0
	v_mfma_f32_16x16x32_bf16 v[50:53], v[170:173], v[178:181], 0
	v_mfma_f32_16x16x32_bf16 v[38:41], v[162:165], v[204:207], 0
	v_mfma_f32_16x16x32_bf16 v[34:37], v[170:173], v[204:207], 0
	v_mfma_f32_16x16x32_bf16 v[22:25], v[162:165], v[212:215], 0
	v_mfma_f32_16x16x32_bf16 v[18:21], v[170:173], v[212:215], 0
	v_mfma_f32_16x16x32_bf16 v[6:9], v[162:165], v[220:223], 0
	v_mfma_f32_16x16x32_bf16 v[2:5], v[170:173], v[220:223], 0
	v_mfma_f32_16x16x32_bf16 v[54:57], v[166:169], v[182:185], v[54:57]
	v_mfma_f32_16x16x32_bf16 v[50:53], v[174:177], v[182:185], v[50:53]
	v_mfma_f32_16x16x32_bf16 v[38:41], v[166:169], v[208:211], v[38:41]
	v_mfma_f32_16x16x32_bf16 v[34:37], v[174:177], v[208:211], v[34:37]
	v_mfma_f32_16x16x32_bf16 v[22:25], v[166:169], v[216:219], v[22:25]
	v_mfma_f32_16x16x32_bf16 v[18:21], v[174:177], v[216:219], v[18:21]
	v_mfma_f32_16x16x32_bf16 v[6:9], v[166:169], v[224:227], v[6:9]
	v_mfma_f32_16x16x32_bf16 v[2:5], v[174:177], v[224:227], v[2:5]
	s_barrier
	s_add_i32 s54, 0, 0x18000
	v_add_u32_e32 v0, s54, v160
	s_add_i32 s55, 0, 0x1c000
	ds_read_b128 v[142:145], v0
	ds_read_b128 v[146:149], v0 offset:1024
	ds_read_b128 v[150:153], v0 offset:2048
	ds_read_b128 v[154:157], v0 offset:3072
	v_add_u32_e32 v0, s55, v160
	ds_read_b128 v[162:165], v0
	ds_read_b128 v[166:169], v0 offset:1024
	ds_read_b128 v[170:173], v0 offset:2048
	ds_read_b128 v[174:177], v0 offset:3072
	s_add_u32 s48, s48, 0x40000
	s_addc_u32 s49, s49, 0
	s_mov_b32 m0, s59
	v_lshl_add_u64 v[244:245], s[48:49], 0, v[136:137]
	ds_read_b128 v[178:181], v161 offset:32768
	ds_read_b128 v[182:185], v161 offset:33792
	ds_read_b128 v[204:207], v161 offset:34816
	ds_read_b128 v[208:211], v161 offset:35840
	ds_read_b128 v[212:215], v161 offset:36864
	ds_read_b128 v[216:219], v161 offset:37888
	ds_read_b128 v[220:223], v161 offset:38912
	ds_read_b128 v[224:227], v161 offset:39936
	global_load_lds_dwordx4 v[244:245], off
	v_lshl_add_u64 v[244:245], s[48:49], 0, v[132:133]
	s_mov_b32 m0, s60
	s_nop 0
	global_load_lds_dwordx4 v[244:245], off
	s_waitcnt vmcnt(8)
	s_waitcnt lgkmcnt(0)
	s_barrier
	v_mfma_f32_16x16x32_bf16 v[126:129], v[142:145], v[178:181], v[126:129]
	v_mfma_f32_16x16x32_bf16 v[122:125], v[150:153], v[178:181], v[122:125]
	v_mfma_f32_16x16x32_bf16 v[110:113], v[142:145], v[204:207], v[110:113]
	v_mfma_f32_16x16x32_bf16 v[106:109], v[150:153], v[204:207], v[106:109]
	v_mfma_f32_16x16x32_bf16 v[94:97], v[142:145], v[212:215], v[94:97]
	v_mfma_f32_16x16x32_bf16 v[90:93], v[150:153], v[212:215], v[90:93]
	v_mfma_f32_16x16x32_bf16 v[78:81], v[142:145], v[220:223], v[78:81]
	v_mfma_f32_16x16x32_bf16 v[74:77], v[150:153], v[220:223], v[74:77]
	v_mfma_f32_16x16x32_bf16 v[126:129], v[146:149], v[182:185], v[126:129]
	v_mfma_f32_16x16x32_bf16 v[122:125], v[154:157], v[182:185], v[122:125]
	v_mfma_f32_16x16x32_bf16 v[110:113], v[146:149], v[208:211], v[110:113]
	v_mfma_f32_16x16x32_bf16 v[106:109], v[154:157], v[208:211], v[106:109]
	v_mfma_f32_16x16x32_bf16 v[94:97], v[146:149], v[216:219], v[94:97]
	v_mfma_f32_16x16x32_bf16 v[90:93], v[154:157], v[216:219], v[90:93]
	v_mfma_f32_16x16x32_bf16 v[78:81], v[146:149], v[224:227], v[78:81]
	v_mfma_f32_16x16x32_bf16 v[74:77], v[154:157], v[224:227], v[74:77]
	v_mfma_f32_16x16x32_bf16 v[118:121], v[162:165], v[178:181], v[118:121]
	v_mfma_f32_16x16x32_bf16 v[114:117], v[170:173], v[178:181], v[114:117]
	v_mfma_f32_16x16x32_bf16 v[102:105], v[162:165], v[204:207], v[102:105]
	v_mfma_f32_16x16x32_bf16 v[98:101], v[170:173], v[204:207], v[98:101]
	v_mfma_f32_16x16x32_bf16 v[86:89], v[162:165], v[212:215], v[86:89]
	v_mfma_f32_16x16x32_bf16 v[82:85], v[170:173], v[212:215], v[82:85]
	v_mfma_f32_16x16x32_bf16 v[70:73], v[162:165], v[220:223], v[70:73]
	v_mfma_f32_16x16x32_bf16 v[66:69], v[170:173], v[220:223], v[66:69]
	v_mfma_f32_16x16x32_bf16 v[118:121], v[166:169], v[182:185], v[118:121]
	v_mfma_f32_16x16x32_bf16 v[114:117], v[174:177], v[182:185], v[114:117]
	v_mfma_f32_16x16x32_bf16 v[102:105], v[166:169], v[208:211], v[102:105]
	v_mfma_f32_16x16x32_bf16 v[98:101], v[174:177], v[208:211], v[98:101]
	v_mfma_f32_16x16x32_bf16 v[86:89], v[166:169], v[216:219], v[86:89]
	v_mfma_f32_16x16x32_bf16 v[82:85], v[174:177], v[216:219], v[82:85]
	v_mfma_f32_16x16x32_bf16 v[70:73], v[166:169], v[224:227], v[70:73]
	v_mfma_f32_16x16x32_bf16 v[66:69], v[174:177], v[224:227], v[66:69]
	s_barrier
	s_add_i32 s48, s54, s56
	v_lshl_add_u64 v[228:229], v[228:229], 0, s[16:17]
	s_mov_b32 m0, s48
	ds_read_b128 v[178:181], v161 offset:49152
	ds_read_b128 v[182:185], v161 offset:50176
	ds_read_b128 v[204:207], v161 offset:51200
	ds_read_b128 v[208:211], v161 offset:52224
	ds_read_b128 v[212:215], v161 offset:53248
	ds_read_b128 v[216:219], v161 offset:54272
	ds_read_b128 v[220:223], v161 offset:55296
	ds_read_b128 v[224:227], v161 offset:56320
	global_load_lds_dwordx4 v[228:229], off
	s_add_i32 m0, s48, 0x2000
	s_add_u32 s42, s42, 0x40080
	v_lshl_add_u64 v[228:229], v[230:231], 0, s[16:17]
	s_addc_u32 s43, s43, 0
	s_add_i32 s48, s55, s56
	global_load_lds_dwordx4 v[228:229], off
	v_lshl_add_u64 v[228:229], s[42:43], 0, v[134:135]
	s_mov_b32 m0, s48
	s_nop 0
	global_load_lds_dwordx4 v[228:229], off
	v_lshl_add_u64 v[228:229], s[42:43], 0, v[130:131]
	s_add_i32 m0, s48, 0x2000
	s_nop 0
	global_load_lds_dwordx4 v[228:229], off
	v_lshl_add_u64 v[228:229], v[240:241], 0, s[16:17]
	s_mov_b32 m0, s63
	s_nop 0
	global_load_lds_dwordx4 v[228:229], off
	v_lshl_add_u64 v[228:229], v[242:243], 0, s[16:17]
	s_mov_b32 m0, s64
	s_nop 0
	global_load_lds_dwordx4 v[228:229], off
	s_waitcnt vmcnt(8)
	s_waitcnt lgkmcnt(0)
	s_barrier
	v_mfma_f32_16x16x32_bf16 v[62:65], v[142:145], v[178:181], v[62:65]
	v_mfma_f32_16x16x32_bf16 v[58:61], v[150:153], v[178:181], v[58:61]
	v_mfma_f32_16x16x32_bf16 v[46:49], v[142:145], v[204:207], v[46:49]
	v_mfma_f32_16x16x32_bf16 v[42:45], v[150:153], v[204:207], v[42:45]
	v_mfma_f32_16x16x32_bf16 v[30:33], v[142:145], v[212:215], v[30:33]
	v_mfma_f32_16x16x32_bf16 v[26:29], v[150:153], v[212:215], v[26:29]
	v_mfma_f32_16x16x32_bf16 v[14:17], v[142:145], v[220:223], v[14:17]
	v_mfma_f32_16x16x32_bf16 v[10:13], v[150:153], v[220:223], v[10:13]
	v_mfma_f32_16x16x32_bf16 v[62:65], v[146:149], v[182:185], v[62:65]
	v_mfma_f32_16x16x32_bf16 v[58:61], v[154:157], v[182:185], v[58:61]
	v_mfma_f32_16x16x32_bf16 v[46:49], v[146:149], v[208:211], v[46:49]
	v_mfma_f32_16x16x32_bf16 v[42:45], v[154:157], v[208:211], v[42:45]
	v_mfma_f32_16x16x32_bf16 v[30:33], v[146:149], v[216:219], v[30:33]
	v_mfma_f32_16x16x32_bf16 v[26:29], v[154:157], v[216:219], v[26:29]
	v_mfma_f32_16x16x32_bf16 v[14:17], v[146:149], v[224:227], v[14:17]
	v_mfma_f32_16x16x32_bf16 v[10:13], v[154:157], v[224:227], v[10:13]
	v_mfma_f32_16x16x32_bf16 v[54:57], v[162:165], v[178:181], v[54:57]
	v_mfma_f32_16x16x32_bf16 v[50:53], v[170:173], v[178:181], v[50:53]
	v_mfma_f32_16x16x32_bf16 v[38:41], v[162:165], v[204:207], v[38:41]
	v_mfma_f32_16x16x32_bf16 v[34:37], v[170:173], v[204:207], v[34:37]
	v_mfma_f32_16x16x32_bf16 v[22:25], v[162:165], v[212:215], v[22:25]
	v_mfma_f32_16x16x32_bf16 v[18:21], v[170:173], v[212:215], v[18:21]
	v_mfma_f32_16x16x32_bf16 v[6:9], v[162:165], v[220:223], v[6:9]
	v_mfma_f32_16x16x32_bf16 v[2:5], v[170:173], v[220:223], v[2:5]
	v_mfma_f32_16x16x32_bf16 v[54:57], v[166:169], v[182:185], v[54:57]
	v_mfma_f32_16x16x32_bf16 v[50:53], v[174:177], v[182:185], v[50:53]
	v_mfma_f32_16x16x32_bf16 v[38:41], v[166:169], v[208:211], v[38:41]
	v_mfma_f32_16x16x32_bf16 v[34:37], v[174:177], v[208:211], v[34:37]
	v_mfma_f32_16x16x32_bf16 v[22:25], v[166:169], v[216:219], v[22:25]
	v_mfma_f32_16x16x32_bf16 v[18:21], v[174:177], v[216:219], v[18:21]
	v_mfma_f32_16x16x32_bf16 v[6:9], v[166:169], v[224:227], v[6:9]
	v_mfma_f32_16x16x32_bf16 v[2:5], v[174:177], v[224:227], v[2:5]
	s_barrier
	s_add_i32 s53, s53, 2
	s_add_u32 s40, s40, 0x100
	s_addc_u32 s41, s41, 0
	s_add_u32 s51, s51, 0x100
	s_addc_u32 s52, s52, 0
	s_cmp_gt_u32 s53, 13
.LBB0_1186:
	s_add_u32 s42, s40, 0xfffc0080
	s_addc_u32 s43, s41, -1
	s_add_i32 s54, 0, 0x10000
	s_cmp_eq_u32 s53, 12
	s_cselect_b32 s49, s7, s43
	s_cselect_b32 s48, s23, s42
	v_add_u32_e32 v0, s54, v160
	s_cselect_b32 s43, s21, s52
	s_cselect_b32 s42, s50, s51
	s_add_i32 s65, 0, 0x14000
	ds_read_b128 v[142:145], v0
	ds_read_b128 v[146:149], v0 offset:1024
	ds_read_b128 v[150:153], v0 offset:2048
	ds_read_b128 v[154:157], v0 offset:3072
	v_add_u32_e32 v0, s65, v160
	ds_read_b128 v[162:165], v0
	ds_read_b128 v[166:169], v0 offset:1024
	ds_read_b128 v[170:173], v0 offset:2048
	ds_read_b128 v[174:177], v0 offset:3072
	v_lshl_add_u64 v[228:229], s[40:41], 0, v[138:139]
	s_add_i32 m0, s57, 0xc000
	ds_read_b128 v[178:181], v161
	ds_read_b128 v[182:185], v161 offset:1024
	ds_read_b128 v[204:207], v161 offset:2048
	ds_read_b128 v[208:211], v161 offset:3072
	ds_read_b128 v[212:215], v161 offset:4096
	ds_read_b128 v[216:219], v161 offset:5120
	ds_read_b128 v[220:223], v161 offset:6144
	ds_read_b128 v[224:227], v161 offset:7168
	global_load_lds_dwordx4 v[228:229], off
	v_lshl_add_u64 v[228:229], s[40:41], 0, v[140:141]
	s_add_i32 m0, s57, 0xe000
	s_nop 0
	global_load_lds_dwordx4 v[228:229], off
	s_waitcnt vmcnt(8)
	s_waitcnt lgkmcnt(0)
	s_barrier
	v_mfma_f32_16x16x32_bf16 v[126:129], v[142:145], v[178:181], v[126:129]
	v_mfma_f32_16x16x32_bf16 v[122:125], v[150:153], v[178:181], v[122:125]
	v_mfma_f32_16x16x32_bf16 v[110:113], v[142:145], v[204:207], v[110:113]
	v_mfma_f32_16x16x32_bf16 v[106:109], v[150:153], v[204:207], v[106:109]
	v_mfma_f32_16x16x32_bf16 v[94:97], v[142:145], v[212:215], v[94:97]
	v_mfma_f32_16x16x32_bf16 v[90:93], v[150:153], v[212:215], v[90:93]
	v_mfma_f32_16x16x32_bf16 v[78:81], v[142:145], v[220:223], v[78:81]
	v_mfma_f32_16x16x32_bf16 v[74:77], v[150:153], v[220:223], v[74:77]
	v_mfma_f32_16x16x32_bf16 v[126:129], v[146:149], v[182:185], v[126:129]
	v_mfma_f32_16x16x32_bf16 v[122:125], v[154:157], v[182:185], v[122:125]
	v_mfma_f32_16x16x32_bf16 v[110:113], v[146:149], v[208:211], v[110:113]
	v_mfma_f32_16x16x32_bf16 v[106:109], v[154:157], v[208:211], v[106:109]
	v_mfma_f32_16x16x32_bf16 v[94:97], v[146:149], v[216:219], v[94:97]
	v_mfma_f32_16x16x32_bf16 v[90:93], v[154:157], v[216:219], v[90:93]
	v_mfma_f32_16x16x32_bf16 v[78:81], v[146:149], v[224:227], v[78:81]
	v_mfma_f32_16x16x32_bf16 v[74:77], v[154:157], v[224:227], v[74:77]
	v_mfma_f32_16x16x32_bf16 v[118:121], v[162:165], v[178:181], v[118:121]
	v_mfma_f32_16x16x32_bf16 v[114:117], v[170:173], v[178:181], v[114:117]
	v_mfma_f32_16x16x32_bf16 v[102:105], v[162:165], v[204:207], v[102:105]
	v_mfma_f32_16x16x32_bf16 v[98:101], v[170:173], v[204:207], v[98:101]
	v_mfma_f32_16x16x32_bf16 v[86:89], v[162:165], v[212:215], v[86:89]
	v_mfma_f32_16x16x32_bf16 v[82:85], v[170:173], v[212:215], v[82:85]
	v_mfma_f32_16x16x32_bf16 v[70:73], v[162:165], v[220:223], v[70:73]
	v_mfma_f32_16x16x32_bf16 v[66:69], v[170:173], v[220:223], v[66:69]
	v_mfma_f32_16x16x32_bf16 v[118:121], v[166:169], v[182:185], v[118:121]
	v_mfma_f32_16x16x32_bf16 v[114:117], v[174:177], v[182:185], v[114:117]
	v_mfma_f32_16x16x32_bf16 v[102:105], v[166:169], v[208:211], v[102:105]
	v_mfma_f32_16x16x32_bf16 v[98:101], v[174:177], v[208:211], v[98:101]
	v_mfma_f32_16x16x32_bf16 v[86:89], v[166:169], v[216:219], v[86:89]
	v_mfma_f32_16x16x32_bf16 v[82:85], v[174:177], v[216:219], v[82:85]
	v_mfma_f32_16x16x32_bf16 v[70:73], v[166:169], v[224:227], v[70:73]
	v_mfma_f32_16x16x32_bf16 v[66:69], v[174:177], v[224:227], v[66:69]
	s_barrier
	s_add_i32 s54, s54, s56
	v_lshl_add_u64 v[228:229], s[42:43], 0, v[134:135]
	s_mov_b32 m0, s54
	ds_read_b128 v[178:181], v161 offset:16384
	ds_read_b128 v[182:185], v161 offset:17408
	ds_read_b128 v[204:207], v161 offset:18432
	ds_read_b128 v[208:211], v161 offset:19456
	ds_read_b128 v[212:215], v161 offset:20480
	ds_read_b128 v[216:219], v161 offset:21504
	ds_read_b128 v[220:223], v161 offset:22528
	ds_read_b128 v[224:227], v161 offset:23552
	global_load_lds_dwordx4 v[228:229], off
	s_add_i32 m0, s54, 0x2000
	s_add_u32 s54, s42, 0x40000
	v_lshl_add_u64 v[230:231], s[42:43], 0, v[130:131]
	s_addc_u32 s55, s43, 0
	s_add_i32 s65, s65, s56
	global_load_lds_dwordx4 v[230:231], off
	v_lshl_add_u64 v[240:241], s[54:55], 0, v[134:135]
	s_mov_b32 m0, s65
	v_lshl_add_u64 v[242:243], s[48:49], 0, v[132:133]
	global_load_lds_dwordx4 v[240:241], off
	v_lshl_add_u64 v[240:241], s[54:55], 0, v[130:131]
	s_add_i32 m0, s65, 0x2000
	s_nop 0
	global_load_lds_dwordx4 v[240:241], off
	v_lshl_add_u64 v[240:241], s[48:49], 0, v[136:137]
	s_mov_b32 m0, s57
	s_nop 0
	global_load_lds_dwordx4 v[240:241], off
	s_mov_b32 m0, s58
	s_nop 0
	global_load_lds_dwordx4 v[242:243], off
	s_waitcnt vmcnt(8)
	s_waitcnt lgkmcnt(0)
	s_barrier
	v_mfma_f32_16x16x32_bf16 v[62:65], v[142:145], v[178:181], v[62:65]
	v_mfma_f32_16x16x32_bf16 v[58:61], v[150:153], v[178:181], v[58:61]
	v_mfma_f32_16x16x32_bf16 v[46:49], v[142:145], v[204:207], v[46:49]
	v_mfma_f32_16x16x32_bf16 v[42:45], v[150:153], v[204:207], v[42:45]
	v_mfma_f32_16x16x32_bf16 v[30:33], v[142:145], v[212:215], v[30:33]
	v_mfma_f32_16x16x32_bf16 v[26:29], v[150:153], v[212:215], v[26:29]
	v_mfma_f32_16x16x32_bf16 v[14:17], v[142:145], v[220:223], v[14:17]
	v_mfma_f32_16x16x32_bf16 v[10:13], v[150:153], v[220:223], v[10:13]
	v_mfma_f32_16x16x32_bf16 v[62:65], v[146:149], v[182:185], v[62:65]
	v_mfma_f32_16x16x32_bf16 v[58:61], v[154:157], v[182:185], v[58:61]
	v_mfma_f32_16x16x32_bf16 v[46:49], v[146:149], v[208:211], v[46:49]
	v_mfma_f32_16x16x32_bf16 v[42:45], v[154:157], v[208:211], v[42:45]
	v_mfma_f32_16x16x32_bf16 v[30:33], v[146:149], v[216:219], v[30:33]
	v_mfma_f32_16x16x32_bf16 v[26:29], v[154:157], v[216:219], v[26:29]
	v_mfma_f32_16x16x32_bf16 v[14:17], v[146:149], v[224:227], v[14:17]
	v_mfma_f32_16x16x32_bf16 v[10:13], v[154:157], v[224:227], v[10:13]
	v_mfma_f32_16x16x32_bf16 v[54:57], v[162:165], v[178:181], v[54:57]
	v_mfma_f32_16x16x32_bf16 v[50:53], v[170:173], v[178:181], v[50:53]
	v_mfma_f32_16x16x32_bf16 v[38:41], v[162:165], v[204:207], v[38:41]
	v_mfma_f32_16x16x32_bf16 v[34:37], v[170:173], v[204:207], v[34:37]
	v_mfma_f32_16x16x32_bf16 v[22:25], v[162:165], v[212:215], v[22:25]
	v_mfma_f32_16x16x32_bf16 v[18:21], v[170:173], v[212:215], v[18:21]
	v_mfma_f32_16x16x32_bf16 v[6:9], v[162:165], v[220:223], v[6:9]
	v_mfma_f32_16x16x32_bf16 v[2:5], v[170:173], v[220:223], v[2:5]
	v_mfma_f32_16x16x32_bf16 v[54:57], v[166:169], v[182:185], v[54:57]
	v_mfma_f32_16x16x32_bf16 v[50:53], v[174:177], v[182:185], v[50:53]
	v_mfma_f32_16x16x32_bf16 v[38:41], v[166:169], v[208:211], v[38:41]
	v_mfma_f32_16x16x32_bf16 v[34:37], v[174:177], v[208:211], v[34:37]
	v_mfma_f32_16x16x32_bf16 v[22:25], v[166:169], v[216:219], v[22:25]
	v_mfma_f32_16x16x32_bf16 v[18:21], v[174:177], v[216:219], v[18:21]
	v_mfma_f32_16x16x32_bf16 v[6:9], v[166:169], v[224:227], v[6:9]
	v_mfma_f32_16x16x32_bf16 v[2:5], v[174:177], v[224:227], v[2:5]
	s_barrier
	s_add_i32 s54, 0, 0x18000
	v_add_u32_e32 v0, s54, v160
	s_add_i32 s55, 0, 0x1c000
	ds_read_b128 v[142:145], v0
	ds_read_b128 v[146:149], v0 offset:1024
	ds_read_b128 v[150:153], v0 offset:2048
	ds_read_b128 v[154:157], v0 offset:3072
	v_add_u32_e32 v0, s55, v160
	ds_read_b128 v[162:165], v0
	ds_read_b128 v[166:169], v0 offset:1024
	ds_read_b128 v[170:173], v0 offset:2048
	ds_read_b128 v[174:177], v0 offset:3072
	s_add_u32 s48, s48, 0x40000
	s_addc_u32 s49, s49, 0
	s_mov_b32 m0, s59
	v_lshl_add_u64 v[244:245], s[48:49], 0, v[136:137]
	ds_read_b128 v[178:181], v161 offset:32768
	ds_read_b128 v[182:185], v161 offset:33792
	ds_read_b128 v[204:207], v161 offset:34816
	ds_read_b128 v[208:211], v161 offset:35840
	ds_read_b128 v[212:215], v161 offset:36864
	ds_read_b128 v[216:219], v161 offset:37888
	ds_read_b128 v[220:223], v161 offset:38912
	ds_read_b128 v[224:227], v161 offset:39936
	global_load_lds_dwordx4 v[244:245], off
	v_lshl_add_u64 v[244:245], s[48:49], 0, v[132:133]
	s_mov_b32 m0, s60
	s_nop 0
	global_load_lds_dwordx4 v[244:245], off
	s_waitcnt vmcnt(8)
	s_waitcnt lgkmcnt(0)
	s_barrier
	v_mfma_f32_16x16x32_bf16 v[126:129], v[142:145], v[178:181], v[126:129]
	v_mfma_f32_16x16x32_bf16 v[122:125], v[150:153], v[178:181], v[122:125]
	v_mfma_f32_16x16x32_bf16 v[110:113], v[142:145], v[204:207], v[110:113]
	v_mfma_f32_16x16x32_bf16 v[106:109], v[150:153], v[204:207], v[106:109]
	v_mfma_f32_16x16x32_bf16 v[94:97], v[142:145], v[212:215], v[94:97]
	v_mfma_f32_16x16x32_bf16 v[90:93], v[150:153], v[212:215], v[90:93]
	v_mfma_f32_16x16x32_bf16 v[78:81], v[142:145], v[220:223], v[78:81]
	v_mfma_f32_16x16x32_bf16 v[74:77], v[150:153], v[220:223], v[74:77]
	v_mfma_f32_16x16x32_bf16 v[126:129], v[146:149], v[182:185], v[126:129]
	v_mfma_f32_16x16x32_bf16 v[122:125], v[154:157], v[182:185], v[122:125]
	v_mfma_f32_16x16x32_bf16 v[110:113], v[146:149], v[208:211], v[110:113]
	v_mfma_f32_16x16x32_bf16 v[106:109], v[154:157], v[208:211], v[106:109]
	v_mfma_f32_16x16x32_bf16 v[94:97], v[146:149], v[216:219], v[94:97]
	v_mfma_f32_16x16x32_bf16 v[90:93], v[154:157], v[216:219], v[90:93]
	v_mfma_f32_16x16x32_bf16 v[78:81], v[146:149], v[224:227], v[78:81]
	v_mfma_f32_16x16x32_bf16 v[74:77], v[154:157], v[224:227], v[74:77]
	v_mfma_f32_16x16x32_bf16 v[118:121], v[162:165], v[178:181], v[118:121]
	v_mfma_f32_16x16x32_bf16 v[114:117], v[170:173], v[178:181], v[114:117]
	v_mfma_f32_16x16x32_bf16 v[102:105], v[162:165], v[204:207], v[102:105]
	v_mfma_f32_16x16x32_bf16 v[98:101], v[170:173], v[204:207], v[98:101]
	v_mfma_f32_16x16x32_bf16 v[86:89], v[162:165], v[212:215], v[86:89]
	v_mfma_f32_16x16x32_bf16 v[82:85], v[170:173], v[212:215], v[82:85]
	v_mfma_f32_16x16x32_bf16 v[70:73], v[162:165], v[220:223], v[70:73]
	v_mfma_f32_16x16x32_bf16 v[66:69], v[170:173], v[220:223], v[66:69]
	v_mfma_f32_16x16x32_bf16 v[118:121], v[166:169], v[182:185], v[118:121]
	v_mfma_f32_16x16x32_bf16 v[114:117], v[174:177], v[182:185], v[114:117]
	v_mfma_f32_16x16x32_bf16 v[102:105], v[166:169], v[208:211], v[102:105]
	v_mfma_f32_16x16x32_bf16 v[98:101], v[174:177], v[208:211], v[98:101]
	v_mfma_f32_16x16x32_bf16 v[86:89], v[166:169], v[216:219], v[86:89]
	v_mfma_f32_16x16x32_bf16 v[82:85], v[174:177], v[216:219], v[82:85]
	v_mfma_f32_16x16x32_bf16 v[70:73], v[166:169], v[224:227], v[70:73]
	v_mfma_f32_16x16x32_bf16 v[66:69], v[174:177], v[224:227], v[66:69]
	s_barrier
	s_add_i32 s48, s54, s56
	v_lshl_add_u64 v[228:229], v[228:229], 0, s[16:17]
	s_mov_b32 m0, s48
	ds_read_b128 v[178:181], v161 offset:49152
	ds_read_b128 v[182:185], v161 offset:50176
	ds_read_b128 v[204:207], v161 offset:51200
	ds_read_b128 v[208:211], v161 offset:52224
	ds_read_b128 v[212:215], v161 offset:53248
	ds_read_b128 v[216:219], v161 offset:54272
	ds_read_b128 v[220:223], v161 offset:55296
	ds_read_b128 v[224:227], v161 offset:56320
	global_load_lds_dwordx4 v[228:229], off
	s_add_i32 m0, s48, 0x2000
	s_add_u32 s42, s42, 0x40080
	v_lshl_add_u64 v[228:229], v[230:231], 0, s[16:17]
	s_addc_u32 s43, s43, 0
	s_add_i32 s48, s55, s56
	global_load_lds_dwordx4 v[228:229], off
	v_lshl_add_u64 v[228:229], s[42:43], 0, v[134:135]
	s_mov_b32 m0, s48
	s_nop 0
	global_load_lds_dwordx4 v[228:229], off
	v_lshl_add_u64 v[228:229], s[42:43], 0, v[130:131]
	s_add_i32 m0, s48, 0x2000
	s_nop 0
	global_load_lds_dwordx4 v[228:229], off
	v_lshl_add_u64 v[228:229], v[240:241], 0, s[16:17]
	s_mov_b32 m0, s63
	s_nop 0
	global_load_lds_dwordx4 v[228:229], off
	v_lshl_add_u64 v[228:229], v[242:243], 0, s[16:17]
	s_mov_b32 m0, s64
	s_nop 0
	global_load_lds_dwordx4 v[228:229], off
	s_waitcnt vmcnt(8)
	s_waitcnt lgkmcnt(0)
	s_barrier
	v_mfma_f32_16x16x32_bf16 v[62:65], v[142:145], v[178:181], v[62:65]
	v_mfma_f32_16x16x32_bf16 v[58:61], v[150:153], v[178:181], v[58:61]
	v_mfma_f32_16x16x32_bf16 v[46:49], v[142:145], v[204:207], v[46:49]
	v_mfma_f32_16x16x32_bf16 v[42:45], v[150:153], v[204:207], v[42:45]
	v_mfma_f32_16x16x32_bf16 v[30:33], v[142:145], v[212:215], v[30:33]
	v_mfma_f32_16x16x32_bf16 v[26:29], v[150:153], v[212:215], v[26:29]
	v_mfma_f32_16x16x32_bf16 v[14:17], v[142:145], v[220:223], v[14:17]
	v_mfma_f32_16x16x32_bf16 v[10:13], v[150:153], v[220:223], v[10:13]
	v_mfma_f32_16x16x32_bf16 v[62:65], v[146:149], v[182:185], v[62:65]
	v_mfma_f32_16x16x32_bf16 v[58:61], v[154:157], v[182:185], v[58:61]
	v_mfma_f32_16x16x32_bf16 v[46:49], v[146:149], v[208:211], v[46:49]
	v_mfma_f32_16x16x32_bf16 v[42:45], v[154:157], v[208:211], v[42:45]
	v_mfma_f32_16x16x32_bf16 v[30:33], v[146:149], v[216:219], v[30:33]
	v_mfma_f32_16x16x32_bf16 v[26:29], v[154:157], v[216:219], v[26:29]
	v_mfma_f32_16x16x32_bf16 v[14:17], v[146:149], v[224:227], v[14:17]
	v_mfma_f32_16x16x32_bf16 v[10:13], v[154:157], v[224:227], v[10:13]
	v_mfma_f32_16x16x32_bf16 v[54:57], v[162:165], v[178:181], v[54:57]
	v_mfma_f32_16x16x32_bf16 v[50:53], v[170:173], v[178:181], v[50:53]
	v_mfma_f32_16x16x32_bf16 v[38:41], v[162:165], v[204:207], v[38:41]
	v_mfma_f32_16x16x32_bf16 v[34:37], v[170:173], v[204:207], v[34:37]
	v_mfma_f32_16x16x32_bf16 v[22:25], v[162:165], v[212:215], v[22:25]
	v_mfma_f32_16x16x32_bf16 v[18:21], v[170:173], v[212:215], v[18:21]
	v_mfma_f32_16x16x32_bf16 v[6:9], v[162:165], v[220:223], v[6:9]
	v_mfma_f32_16x16x32_bf16 v[2:5], v[170:173], v[220:223], v[2:5]
	v_mfma_f32_16x16x32_bf16 v[54:57], v[166:169], v[182:185], v[54:57]
	v_mfma_f32_16x16x32_bf16 v[50:53], v[174:177], v[182:185], v[50:53]
	v_mfma_f32_16x16x32_bf16 v[38:41], v[166:169], v[208:211], v[38:41]
	v_mfma_f32_16x16x32_bf16 v[34:37], v[174:177], v[208:211], v[34:37]
	v_mfma_f32_16x16x32_bf16 v[22:25], v[166:169], v[216:219], v[22:25]
	v_mfma_f32_16x16x32_bf16 v[18:21], v[174:177], v[216:219], v[18:21]
	v_mfma_f32_16x16x32_bf16 v[6:9], v[166:169], v[224:227], v[6:9]
	v_mfma_f32_16x16x32_bf16 v[2:5], v[174:177], v[224:227], v[2:5]
	s_barrier
	s_add_i32 s53, s53, 2
	s_add_u32 s40, s40, 0x100
	s_addc_u32 s41, s41, 0
	s_add_u32 s51, s51, 0x100
	s_addc_u32 s52, s52, 0
	s_cmp_gt_u32 s53, 13
	s_cbranch_scc0 .LBB0_1186
	s_and_b64 vcc, exec, s[18:19]
	s_cbranch_vccz .LBB0_1189
	s_barrier
